# FFT passes: copy coalescing of 170 v_mov after complex multiplies (dest written directly)
# speedup vs baseline: 1.0050x; 1.0009x over previous
;     static __device__ __forceinline__ float sl(float g, float up) { return g * __builtin_amdgcn_rcpf(1.0f + __builtin_amdgcn_exp2f(-1.4426950408889634f * g)) * up; }
; #define tid ltid()
; template <int LR, bool INV>
; __device__ __forceinline__ void fft_pass(float2* X, const int N, const int sl, const int tid) {
;     ...
;   for (int g = tid; g < (N >> LR); g += NTHR) {
;     const int r = g & (s - 1);
;     const int i0 = ((g >> sl) << (sl + LR)) + r;
;     float2 x[R];
; #pragma unroll
;     for (int m = 0; m < R; ++m) x[m] = X[PIDX(i0 + (m << sl))];
.LBB0_651:
	v_and_or_b32 v31, v30, s67, v28
	v_ashrrev_i32_e32 v32, 4, v31
	v_lshlrev_b32_e32 v32, 3, v32
	v_lshlrev_b32_e32 v33, 3, v31
	v_add3_u32 v50, s52, v32, v33


;     static __device__ __forceinline__ float sl(float g, float up) { return g * __builtin_amdgcn_rcpf(1.0f + __builtin_amdgcn_exp2f(-1.4426950408889634f * g)) * up; }
; #define tid ltid()
; template <int LR, bool INV>
; __device__ __forceinline__ void fft_pass(float2* X, const int N, const int sl, const int tid) {
;     ...
;   for (int g = tid; g < (N >> LR); g += NTHR) {
;     const int r = g & (s - 1);
;     const int i0 = ((g >> sl) << (sl + LR)) + r;
;     float2 x[R];
; #pragma unroll
;     for (int m = 0; m < R; ++m) x[m] = X[PIDX(i0 + (m << sl))];
	v_or_b32_e32 v31, 0xe00, v31

;     static __device__ __forceinline__ float sl(float g, float up) { return g * __builtin_amdgcn_rcpf(1.0f + __builtin_amdgcn_exp2f(-1.4426950408889634f * g)) * up; }
; #define tid ltid()
; template <int LR, bool INV>
; __device__ __forceinline__ void fft_pass(float2* X, const int N, const int sl, const int tid) {
;     ...
;   for (int g = tid; g < (N >> LR); g += NTHR) {
;     const int r = g & (s - 1);
;     const int i0 = ((g >> sl) << (sl + LR)) + r;
;     float2 x[R];
; #pragma unroll
;     for (int m = 0; m < R; ++m) x[m] = X[PIDX(i0 + (m << sl))];
	v_ashrrev_i32_e32 v31, 4, v31

;     static __device__ __forceinline__ float sl(float g, float up) { return g * __builtin_amdgcn_rcpf(1.0f + __builtin_amdgcn_exp2f(-1.4426950408889634f * g)) * up; }
; #define tid ltid()
; template <int LR, bool INV>
; __device__ __forceinline__ void fft_pass(float2* X, const int N, const int sl, const int tid) {
;     ...
;   for (int g = tid; g < (N >> LR); g += NTHR) {
;     const int r = g & (s - 1);
;     const int i0 = ((g >> sl) << (sl + LR)) + r;
;     float2 x[R];
; #pragma unroll
;     for (int m = 0; m < R; ++m) x[m] = X[PIDX(i0 + (m << sl))];
	v_lshlrev_b32_e32 v31, 3, v31

;     static __device__ __forceinline__ float sl(float g, float up) { return g * __builtin_amdgcn_rcpf(1.0f + __builtin_amdgcn_exp2f(-1.4426950408889634f * g)) * up; }
; __device__ __forceinline__ float2 cmul(float2 a, float2 b) { return make_float2(a.x * b.x - a.y * b.y, a.x * b.y + a.y * b.x); }
; #define tid ltid()
; template <int LR, bool INV>
; __device__ __forceinline__ void fft_stages(float2 (&x)[1 << LR], const int r, const int s) {
;   constexpr int R = 1 << LR;
; #pragma unroll
;   for (int st = 0; st < LR; ++st) {
;     const int hl = INV ? (1 << st) : (R >> (st + 1));
;     const float fb = (float)r * (0.5f / (float)(hl * s));
;     const float2 wb = make_float2(__builtin_amdgcn_cosf(fb), INV ? __builtin_amdgcn_sinf(fb) : -__builtin_amdgcn_sinf(fb));
; #pragma unroll
;     for (int m = 0; m < R; ++m) {
;       if (m & hl) continue;
;       const int k = m & (hl - 1); const int j = k * (8 / hl);
;       const float2 wc = make_float2(c16(j), INV ? s16(j) : -s16(j));
;       const float2 tw = cmul(wb, wc);
;       if (!INV) { const float2 p = x[m], q = x[m + hl]; x[m] = make_float2(p.x + q.x, p.y + q.y); x[m + hl] = cmul(make_float2(p.x - q.x, p.y - q.y), tw); }
;       else { const float2 p = x[m], q = cmul(x[m + hl], tw); x[m] = make_float2(p.x + q.x, p.y + q.y); x[m + hl] = make_float2(p.x - q.x, p.y - q.y); }
;     }
;   }
; }
; template <int LR, bool INV>
; __device__ __forceinline__ void fft_pass(float2* X, const int N, const int sl, const int tid) {
;   constexpr int R = 1 << LR;
;   const int s = 1 << sl;
;   for (int g = tid; g < (N >> LR); g += NTHR) {
;     const int r = g & (s - 1);
;     const int i0 = ((g >> sl) << (sl + LR)) + r;
;     float2 x[R];
; #pragma unroll
;     for (int m = 0; m < R; ++m) x[m] = X[PIDX(i0 + (m << sl))];
;     fft_stages<LR, INV>(x, r, s);
; #pragma unroll
;     for (int m = 0; m < R; ++m) X[PIDX(i0 + (m << sl))] = x[m];
;   }
	v_add3_u32 v31, s52, v31, v33
	ds_read_b64 v[32:33], v50
	ds_read_b64 v[34:35], v50 offset:4352
	ds_read_b64 v[36:37], v50 offset:8704
	ds_read_b64 v[38:39], v50 offset:13056
	ds_read_b64 v[40:41], v50 offset:17408
	ds_read_b64 v[42:43], v50 offset:21760
	ds_read_b64 v[44:45], v50 offset:26112
	ds_read_b64 v[46:47], v50 offset:30464
	v_add_u32_e32 v29, 0x200, v29
	s_waitcnt lgkmcnt(3)
	v_add_f32_e32 v48, v32, v40
	v_add_f32_e32 v49, v33, v41
	v_sub_f32_e32 v32, v32, v40
	v_sub_f32_e32 v33, v33, v41
	s_waitcnt lgkmcnt(2)
	v_add_f32_e32 v40, v34, v42
	v_add_f32_e32 v41, v35, v43
	v_sub_f32_e32 v34, v34, v42
	v_sub_f32_e32 v35, v35, v43
	s_waitcnt lgkmcnt(1)
	v_add_f32_e32 v42, v36, v44
	v_add_f32_e32 v43, v37, v45
	v_sub_f32_e32 v36, v36, v44
	v_sub_f32_e32 v37, v37, v45
	s_waitcnt lgkmcnt(0)
	v_add_f32_e32 v44, v38, v46
	v_add_f32_e32 v45, v39, v47
	v_sub_f32_e32 v38, v38, v46
	v_sub_f32_e32 v39, v39, v47
	v_add_f32_e32 v46, v48, v42
	v_add_f32_e32 v47, v49, v43
	v_sub_f32_e32 v42, v48, v42
	v_sub_f32_e32 v43, v49, v43
	v_add_f32_e32 v48, v40, v44
	v_add_f32_e32 v49, v41, v45
	v_sub_f32_e32 v40, v40, v44
	v_sub_f32_e32 v41, v41, v45
	v_add_f32_e32 v44, v46, v48
	v_add_f32_e32 v45, v47, v49
	v_sub_f32_e32 v46, v46, v48
	v_sub_f32_e32 v47, v47, v49
	ds_write_b64 v50, v[44:45]
	v_mul_f32_e32 v44, v14, v47
	v_mul_f32_e32 v45, v15, v47
	v_cmp_lt_i32_e32 vcc, -1, v29
	v_fma_f32 v48, v12, v46, -v44
	v_fma_f32 v49, v13, v46, v45
	v_add_u32_e32 v30, 0x1000, v30

;     static __device__ __forceinline__ float sl(float g, float up) { return g * __builtin_amdgcn_rcpf(1.0f + __builtin_amdgcn_exp2f(-1.4426950408889634f * g)) * up; }
; __device__ __forceinline__ float2 cmul(float2 a, float2 b) { return make_float2(a.x * b.x - a.y * b.y, a.x * b.y + a.y * b.x); }
; #define tid ltid()
; template <int LR, bool INV>
; __device__ __forceinline__ void fft_stages(float2 (&x)[1 << LR], const int r, const int s) {
;   constexpr int R = 1 << LR;
; #pragma unroll
;   for (int st = 0; st < LR; ++st) {
;     const int hl = INV ? (1 << st) : (R >> (st + 1));
;     const float fb = (float)r * (0.5f / (float)(hl * s));
;     const float2 wb = make_float2(__builtin_amdgcn_cosf(fb), INV ? __builtin_amdgcn_sinf(fb) : -__builtin_amdgcn_sinf(fb));
; #pragma unroll
;     for (int m = 0; m < R; ++m) {
;       if (m & hl) continue;
;       const int k = m & (hl - 1); const int j = k * (8 / hl);
;       const float2 wc = make_float2(c16(j), INV ? s16(j) : -s16(j));
;       const float2 tw = cmul(wb, wc);
;       if (!INV) { const float2 p = x[m], q = x[m + hl]; x[m] = make_float2(p.x + q.x, p.y + q.y); x[m + hl] = cmul(make_float2(p.x - q.x, p.y - q.y), tw); }
;       else { const float2 p = x[m], q = cmul(x[m + hl], tw); x[m] = make_float2(p.x + q.x, p.y + q.y); x[m + hl] = make_float2(p.x - q.x, p.y - q.y); }
;     }
;   }
; }
; template <int LR, bool INV>
; __device__ __forceinline__ void fft_pass(float2* X, const int N, const int sl, const int tid) {
;   constexpr int R = 1 << LR;
;   const int s = 1 << sl;
;   for (int g = tid; g < (N >> LR); g += NTHR) {
;     const int r = g & (s - 1);
;     const int i0 = ((g >> sl) << (sl + LR)) + r;
;     float2 x[R];
; #pragma unroll
;     for (int m = 0; m < R; ++m) x[m] = X[PIDX(i0 + (m << sl))];
;     fft_stages<LR, INV>(x, r, s);
; #pragma unroll
;     for (int m = 0; m < R; ++m) X[PIDX(i0 + (m << sl))] = x[m];
;   }
	v_mul_f32_e32 v44, v16, v43
	v_mul_f32_e32 v45, v17, v43
	ds_write_b64 v50, v[48:49] offset:4352
	v_fma_f32 v46, v8, v42, -v44
	v_fma_f32 v47, v9, v42, v45
	s_or_b64 s[14:15], vcc, s[14:15]

;     static __device__ __forceinline__ float sl(float g, float up) { return g * __builtin_amdgcn_rcpf(1.0f + __builtin_amdgcn_exp2f(-1.4426950408889634f * g)) * up; }
; __device__ __forceinline__ float2 cmul(float2 a, float2 b) { return make_float2(a.x * b.x - a.y * b.y, a.x * b.y + a.y * b.x); }
; #define tid ltid()
; template <int LR, bool INV>
; __device__ __forceinline__ void fft_stages(float2 (&x)[1 << LR], const int r, const int s) {
;   constexpr int R = 1 << LR;
; #pragma unroll
;   for (int st = 0; st < LR; ++st) {
;     const int hl = INV ? (1 << st) : (R >> (st + 1));
;     const float fb = (float)r * (0.5f / (float)(hl * s));
;     const float2 wb = make_float2(__builtin_amdgcn_cosf(fb), INV ? __builtin_amdgcn_sinf(fb) : -__builtin_amdgcn_sinf(fb));
; #pragma unroll
;     for (int m = 0; m < R; ++m) {
;       if (m & hl) continue;
;       const int k = m & (hl - 1); const int j = k * (8 / hl);
;       const float2 wc = make_float2(c16(j), INV ? s16(j) : -s16(j));
;       const float2 tw = cmul(wb, wc);
;       if (!INV) { const float2 p = x[m], q = x[m + hl]; x[m] = make_float2(p.x + q.x, p.y + q.y); x[m + hl] = cmul(make_float2(p.x - q.x, p.y - q.y), tw); }
;       else { const float2 p = x[m], q = cmul(x[m + hl], tw); x[m] = make_float2(p.x + q.x, p.y + q.y); x[m + hl] = make_float2(p.x - q.x, p.y - q.y); }
;     }
;   }
; }
; template <int LR, bool INV>
; __device__ __forceinline__ void fft_pass(float2* X, const int N, const int sl, const int tid) {
;   constexpr int R = 1 << LR;
;   const int s = 1 << sl;
;   for (int g = tid; g < (N >> LR); g += NTHR) {
;     const int r = g & (s - 1);
;     const int i0 = ((g >> sl) << (sl + LR)) + r;
;     float2 x[R];
; #pragma unroll
;     for (int m = 0; m < R; ++m) x[m] = X[PIDX(i0 + (m << sl))];
;     fft_stages<LR, INV>(x, r, s);
; #pragma unroll
;     for (int m = 0; m < R; ++m) X[PIDX(i0 + (m << sl))] = x[m];
;   }
	v_mul_f32_e32 v42, v18, v41
	v_mul_f32_e32 v43, v19, v41
	v_fma_f32 v44, v10, v40, -v42
	v_fma_f32 v45, v11, v40, v43

;     static __device__ __forceinline__ float sl(float g, float up) { return g * __builtin_amdgcn_rcpf(1.0f + __builtin_amdgcn_exp2f(-1.4426950408889634f * g)) * up; }
; __device__ __forceinline__ float2 cmul(float2 a, float2 b) { return make_float2(a.x * b.x - a.y * b.y, a.x * b.y + a.y * b.x); }
; #define tid ltid()
; template <int LR, bool INV>
; __device__ __forceinline__ void fft_stages(float2 (&x)[1 << LR], const int r, const int s) {
;   constexpr int R = 1 << LR;
; #pragma unroll
;   for (int st = 0; st < LR; ++st) {
;     const int hl = INV ? (1 << st) : (R >> (st + 1));
;     const float fb = (float)r * (0.5f / (float)(hl * s));
;     const float2 wb = make_float2(__builtin_amdgcn_cosf(fb), INV ? __builtin_amdgcn_sinf(fb) : -__builtin_amdgcn_sinf(fb));
; #pragma unroll
;     for (int m = 0; m < R; ++m) {
;       if (m & hl) continue;
;       const int k = m & (hl - 1); const int j = k * (8 / hl);
;       const float2 wc = make_float2(c16(j), INV ? s16(j) : -s16(j));
;       const float2 tw = cmul(wb, wc);
;       if (!INV) { const float2 p = x[m], q = x[m + hl]; x[m] = make_float2(p.x + q.x, p.y + q.y); x[m + hl] = cmul(make_float2(p.x - q.x, p.y - q.y), tw); }
;       else { const float2 p = x[m], q = cmul(x[m + hl], tw); x[m] = make_float2(p.x + q.x, p.y + q.y); x[m + hl] = make_float2(p.x - q.x, p.y - q.y); }
;     }
;   }
; }
; template <int LR, bool INV>
; __device__ __forceinline__ void fft_pass(float2* X, const int N, const int sl, const int tid) {
;   constexpr int R = 1 << LR;
;   const int s = 1 << sl;
;   for (int g = tid; g < (N >> LR); g += NTHR) {
;     const int r = g & (s - 1);
;     const int i0 = ((g >> sl) << (sl + LR)) + r;
;     float2 x[R];
; #pragma unroll
;     for (int m = 0; m < R; ++m) x[m] = X[PIDX(i0 + (m << sl))];
;     fft_stages<LR, INV>(x, r, s);
; #pragma unroll
;     for (int m = 0; m < R; ++m) X[PIDX(i0 + (m << sl))] = x[m];
;   }
	v_add_f32_e32 v40, v46, v44
	v_add_f32_e32 v41, v47, v45
	v_sub_f32_e32 v42, v46, v44
	v_sub_f32_e32 v43, v47, v45
	ds_write_b64 v50, v[40:41] offset:8704
	v_mul_f32_e32 v40, v14, v43
	v_mul_f32_e32 v41, v15, v43
	v_fma_f32 v44, v12, v42, -v40
	v_fma_f32 v45, v13, v42, v41

;     static __device__ __forceinline__ float sl(float g, float up) { return g * __builtin_amdgcn_rcpf(1.0f + __builtin_amdgcn_exp2f(-1.4426950408889634f * g)) * up; }
; __device__ __forceinline__ float2 cmul(float2 a, float2 b) { return make_float2(a.x * b.x - a.y * b.y, a.x * b.y + a.y * b.x); }
; #define tid ltid()
; template <int LR, bool INV>
; __device__ __forceinline__ void fft_stages(float2 (&x)[1 << LR], const int r, const int s) {
;   constexpr int R = 1 << LR;
; #pragma unroll
;   for (int st = 0; st < LR; ++st) {
;     const int hl = INV ? (1 << st) : (R >> (st + 1));
;     const float fb = (float)r * (0.5f / (float)(hl * s));
;     const float2 wb = make_float2(__builtin_amdgcn_cosf(fb), INV ? __builtin_amdgcn_sinf(fb) : -__builtin_amdgcn_sinf(fb));
; #pragma unroll
;     for (int m = 0; m < R; ++m) {
;       if (m & hl) continue;
;       const int k = m & (hl - 1); const int j = k * (8 / hl);
;       const float2 wc = make_float2(c16(j), INV ? s16(j) : -s16(j));
;       const float2 tw = cmul(wb, wc);
;       if (!INV) { const float2 p = x[m], q = x[m + hl]; x[m] = make_float2(p.x + q.x, p.y + q.y); x[m + hl] = cmul(make_float2(p.x - q.x, p.y - q.y), tw); }
;       else { const float2 p = x[m], q = cmul(x[m + hl], tw); x[m] = make_float2(p.x + q.x, p.y + q.y); x[m + hl] = make_float2(p.x - q.x, p.y - q.y); }
;     }
;   }
; }
; template <int LR, bool INV>
; __device__ __forceinline__ void fft_pass(float2* X, const int N, const int sl, const int tid) {
;   constexpr int R = 1 << LR;
;   const int s = 1 << sl;
;   for (int g = tid; g < (N >> LR); g += NTHR) {
;     const int r = g & (s - 1);
;     const int i0 = ((g >> sl) << (sl + LR)) + r;
;     float2 x[R];
; #pragma unroll
;     for (int m = 0; m < R; ++m) x[m] = X[PIDX(i0 + (m << sl))];
;     fft_stages<LR, INV>(x, r, s);
; #pragma unroll
;     for (int m = 0; m < R; ++m) X[PIDX(i0 + (m << sl))] = x[m];
;   }
	v_mul_f32_e32 v40, v20, v33
	v_mul_f32_e32 v41, v21, v33
	ds_write_b64 v50, v[44:45] offset:13056
	v_fma_f32 v42, v0, v32, -v40
	v_fma_f32 v43, v1, v32, v41

;     static __device__ __forceinline__ float sl(float g, float up) { return g * __builtin_amdgcn_rcpf(1.0f + __builtin_amdgcn_exp2f(-1.4426950408889634f * g)) * up; }
; __device__ __forceinline__ float2 cmul(float2 a, float2 b) { return make_float2(a.x * b.x - a.y * b.y, a.x * b.y + a.y * b.x); }
; #define tid ltid()
; template <int LR, bool INV>
; __device__ __forceinline__ void fft_stages(float2 (&x)[1 << LR], const int r, const int s) {
;   constexpr int R = 1 << LR;
; #pragma unroll
;   for (int st = 0; st < LR; ++st) {
;     const int hl = INV ? (1 << st) : (R >> (st + 1));
;     const float fb = (float)r * (0.5f / (float)(hl * s));
;     const float2 wb = make_float2(__builtin_amdgcn_cosf(fb), INV ? __builtin_amdgcn_sinf(fb) : -__builtin_amdgcn_sinf(fb));
; #pragma unroll
;     for (int m = 0; m < R; ++m) {
;       if (m & hl) continue;
;       const int k = m & (hl - 1); const int j = k * (8 / hl);
;       const float2 wc = make_float2(c16(j), INV ? s16(j) : -s16(j));
;       const float2 tw = cmul(wb, wc);
;       if (!INV) { const float2 p = x[m], q = x[m + hl]; x[m] = make_float2(p.x + q.x, p.y + q.y); x[m + hl] = cmul(make_float2(p.x - q.x, p.y - q.y), tw); }
;       else { const float2 p = x[m], q = cmul(x[m + hl], tw); x[m] = make_float2(p.x + q.x, p.y + q.y); x[m + hl] = make_float2(p.x - q.x, p.y - q.y); }
;     }
;   }
; }
; template <int LR, bool INV>
; __device__ __forceinline__ void fft_pass(float2* X, const int N, const int sl, const int tid) {
;   constexpr int R = 1 << LR;
;   const int s = 1 << sl;
;   for (int g = tid; g < (N >> LR); g += NTHR) {
;     const int r = g & (s - 1);
;     const int i0 = ((g >> sl) << (sl + LR)) + r;
;     float2 x[R];
; #pragma unroll
;     for (int m = 0; m < R; ++m) x[m] = X[PIDX(i0 + (m << sl))];
;     fft_stages<LR, INV>(x, r, s);
; #pragma unroll
;     for (int m = 0; m < R; ++m) X[PIDX(i0 + (m << sl))] = x[m];
;   }
	v_mul_f32_e32 v32, v22, v35
	v_mul_f32_e32 v33, v23, v35
	v_fma_f32 v40, v2, v34, -v32
	v_fma_f32 v41, v3, v34, v33

;     static __device__ __forceinline__ float sl(float g, float up) { return g * __builtin_amdgcn_rcpf(1.0f + __builtin_amdgcn_exp2f(-1.4426950408889634f * g)) * up; }
; __device__ __forceinline__ float2 cmul(float2 a, float2 b) { return make_float2(a.x * b.x - a.y * b.y, a.x * b.y + a.y * b.x); }
; #define tid ltid()
; template <int LR, bool INV>
; __device__ __forceinline__ void fft_stages(float2 (&x)[1 << LR], const int r, const int s) {
;   constexpr int R = 1 << LR;
; #pragma unroll
;   for (int st = 0; st < LR; ++st) {
;     const int hl = INV ? (1 << st) : (R >> (st + 1));
;     const float fb = (float)r * (0.5f / (float)(hl * s));
;     const float2 wb = make_float2(__builtin_amdgcn_cosf(fb), INV ? __builtin_amdgcn_sinf(fb) : -__builtin_amdgcn_sinf(fb));
; #pragma unroll
;     for (int m = 0; m < R; ++m) {
;       if (m & hl) continue;
;       const int k = m & (hl - 1); const int j = k * (8 / hl);
;       const float2 wc = make_float2(c16(j), INV ? s16(j) : -s16(j));
;       const float2 tw = cmul(wb, wc);
;       if (!INV) { const float2 p = x[m], q = x[m + hl]; x[m] = make_float2(p.x + q.x, p.y + q.y); x[m + hl] = cmul(make_float2(p.x - q.x, p.y - q.y), tw); }
;       else { const float2 p = x[m], q = cmul(x[m + hl], tw); x[m] = make_float2(p.x + q.x, p.y + q.y); x[m + hl] = make_float2(p.x - q.x, p.y - q.y); }
;     }
;   }
; }
; template <int LR, bool INV>
; __device__ __forceinline__ void fft_pass(float2* X, const int N, const int sl, const int tid) {
;   constexpr int R = 1 << LR;
;   const int s = 1 << sl;
;   for (int g = tid; g < (N >> LR); g += NTHR) {
;     const int r = g & (s - 1);
;     const int i0 = ((g >> sl) << (sl + LR)) + r;
;     float2 x[R];
; #pragma unroll
;     for (int m = 0; m < R; ++m) x[m] = X[PIDX(i0 + (m << sl))];
;     fft_stages<LR, INV>(x, r, s);
; #pragma unroll
;     for (int m = 0; m < R; ++m) X[PIDX(i0 + (m << sl))] = x[m];
;   }
	v_mul_f32_e32 v32, v24, v37
	v_mul_f32_e32 v33, v25, v37
	v_fma_f32 v34, v4, v36, -v32
	v_fma_f32 v35, v5, v36, v33

;     static __device__ __forceinline__ float sl(float g, float up) { return g * __builtin_amdgcn_rcpf(1.0f + __builtin_amdgcn_exp2f(-1.4426950408889634f * g)) * up; }
; __device__ __forceinline__ float2 cmul(float2 a, float2 b) { return make_float2(a.x * b.x - a.y * b.y, a.x * b.y + a.y * b.x); }
; #define tid ltid()
; template <int LR, bool INV>
; __device__ __forceinline__ void fft_stages(float2 (&x)[1 << LR], const int r, const int s) {
;   constexpr int R = 1 << LR;
; #pragma unroll
;   for (int st = 0; st < LR; ++st) {
;     const int hl = INV ? (1 << st) : (R >> (st + 1));
;     const float fb = (float)r * (0.5f / (float)(hl * s));
;     const float2 wb = make_float2(__builtin_amdgcn_cosf(fb), INV ? __builtin_amdgcn_sinf(fb) : -__builtin_amdgcn_sinf(fb));
; #pragma unroll
;     for (int m = 0; m < R; ++m) {
;       if (m & hl) continue;
;       const int k = m & (hl - 1); const int j = k * (8 / hl);
;       const float2 wc = make_float2(c16(j), INV ? s16(j) : -s16(j));
;       const float2 tw = cmul(wb, wc);
;       if (!INV) { const float2 p = x[m], q = x[m + hl]; x[m] = make_float2(p.x + q.x, p.y + q.y); x[m + hl] = cmul(make_float2(p.x - q.x, p.y - q.y), tw); }
;       else { const float2 p = x[m], q = cmul(x[m + hl], tw); x[m] = make_float2(p.x + q.x, p.y + q.y); x[m + hl] = make_float2(p.x - q.x, p.y - q.y); }
;     }
;   }
; }
; template <int LR, bool INV>
; __device__ __forceinline__ void fft_pass(float2* X, const int N, const int sl, const int tid) {
;   constexpr int R = 1 << LR;
;   const int s = 1 << sl;
;   for (int g = tid; g < (N >> LR); g += NTHR) {
;     const int r = g & (s - 1);
;     const int i0 = ((g >> sl) << (sl + LR)) + r;
;     float2 x[R];
; #pragma unroll
;     for (int m = 0; m < R; ++m) x[m] = X[PIDX(i0 + (m << sl))];
;     fft_stages<LR, INV>(x, r, s);
; #pragma unroll
;     for (int m = 0; m < R; ++m) X[PIDX(i0 + (m << sl))] = x[m];
;   }
	v_mul_f32_e32 v32, v26, v39
	v_mul_f32_e32 v33, v27, v39
	v_fma_f32 v36, v6, v38, -v32
	v_fma_f32 v37, v7, v38, v33

;     static __device__ __forceinline__ float sl(float g, float up) { return g * __builtin_amdgcn_rcpf(1.0f + __builtin_amdgcn_exp2f(-1.4426950408889634f * g)) * up; }
; __device__ __forceinline__ float2 cmul(float2 a, float2 b) { return make_float2(a.x * b.x - a.y * b.y, a.x * b.y + a.y * b.x); }
; #define tid ltid()
; template <int LR, bool INV>
; __device__ __forceinline__ void fft_stages(float2 (&x)[1 << LR], const int r, const int s) {
;   constexpr int R = 1 << LR;
; #pragma unroll
;   for (int st = 0; st < LR; ++st) {
;     const int hl = INV ? (1 << st) : (R >> (st + 1));
;     const float fb = (float)r * (0.5f / (float)(hl * s));
;     const float2 wb = make_float2(__builtin_amdgcn_cosf(fb), INV ? __builtin_amdgcn_sinf(fb) : -__builtin_amdgcn_sinf(fb));
; #pragma unroll
;     for (int m = 0; m < R; ++m) {
;       if (m & hl) continue;
;       const int k = m & (hl - 1); const int j = k * (8 / hl);
;       const float2 wc = make_float2(c16(j), INV ? s16(j) : -s16(j));
;       const float2 tw = cmul(wb, wc);
;       if (!INV) { const float2 p = x[m], q = x[m + hl]; x[m] = make_float2(p.x + q.x, p.y + q.y); x[m + hl] = cmul(make_float2(p.x - q.x, p.y - q.y), tw); }
;       else { const float2 p = x[m], q = cmul(x[m + hl], tw); x[m] = make_float2(p.x + q.x, p.y + q.y); x[m + hl] = make_float2(p.x - q.x, p.y - q.y); }
;     }
;   }
; }
; template <int LR, bool INV>
; __device__ __forceinline__ void fft_pass(float2* X, const int N, const int sl, const int tid) {
;   constexpr int R = 1 << LR;
;   const int s = 1 << sl;
;   for (int g = tid; g < (N >> LR); g += NTHR) {
;     const int r = g & (s - 1);
;     const int i0 = ((g >> sl) << (sl + LR)) + r;
;     float2 x[R];
; #pragma unroll
;     for (int m = 0; m < R; ++m) x[m] = X[PIDX(i0 + (m << sl))];
;     fft_stages<LR, INV>(x, r, s);
; #pragma unroll
;     for (int m = 0; m < R; ++m) X[PIDX(i0 + (m << sl))] = x[m];
;   }
	v_add_f32_e32 v32, v42, v34
	v_add_f32_e32 v33, v43, v35
	v_add_f32_e32 v38, v40, v36
	v_add_f32_e32 v39, v41, v37
	v_sub_f32_e32 v36, v40, v36
	v_sub_f32_e32 v37, v41, v37
	v_add_f32_e32 v40, v32, v38
	v_add_f32_e32 v41, v33, v39
	v_sub_f32_e32 v32, v32, v38
	v_sub_f32_e32 v33, v33, v39
	v_sub_f32_e32 v34, v42, v34
	v_sub_f32_e32 v35, v43, v35
	v_mul_f32_e32 v38, v14, v33
	v_mul_f32_e32 v39, v15, v33
	ds_write_b64 v50, v[40:41] offset:17408
	v_fma_f32 v40, v12, v32, -v38
	v_fma_f32 v41, v13, v32, v39

;     static __device__ __forceinline__ float sl(float g, float up) { return g * __builtin_amdgcn_rcpf(1.0f + __builtin_amdgcn_exp2f(-1.4426950408889634f * g)) * up; }
; __device__ __forceinline__ float2 cmul(float2 a, float2 b) { return make_float2(a.x * b.x - a.y * b.y, a.x * b.y + a.y * b.x); }
; #define tid ltid()
; template <int LR, bool INV>
; __device__ __forceinline__ void fft_stages(float2 (&x)[1 << LR], const int r, const int s) {
;   constexpr int R = 1 << LR;
; #pragma unroll
;   for (int st = 0; st < LR; ++st) {
;     const int hl = INV ? (1 << st) : (R >> (st + 1));
;     const float fb = (float)r * (0.5f / (float)(hl * s));
;     const float2 wb = make_float2(__builtin_amdgcn_cosf(fb), INV ? __builtin_amdgcn_sinf(fb) : -__builtin_amdgcn_sinf(fb));
; #pragma unroll
;     for (int m = 0; m < R; ++m) {
;       if (m & hl) continue;
;       const int k = m & (hl - 1); const int j = k * (8 / hl);
;       const float2 wc = make_float2(c16(j), INV ? s16(j) : -s16(j));
;       const float2 tw = cmul(wb, wc);
;       if (!INV) { const float2 p = x[m], q = x[m + hl]; x[m] = make_float2(p.x + q.x, p.y + q.y); x[m + hl] = cmul(make_float2(p.x - q.x, p.y - q.y), tw); }
;       else { const float2 p = x[m], q = cmul(x[m + hl], tw); x[m] = make_float2(p.x + q.x, p.y + q.y); x[m + hl] = make_float2(p.x - q.x, p.y - q.y); }
;     }
;   }
; }
; template <int LR, bool INV>
; __device__ __forceinline__ void fft_pass(float2* X, const int N, const int sl, const int tid) {
;   constexpr int R = 1 << LR;
;   const int s = 1 << sl;
;   for (int g = tid; g < (N >> LR); g += NTHR) {
;     const int r = g & (s - 1);
;     const int i0 = ((g >> sl) << (sl + LR)) + r;
;     float2 x[R];
; #pragma unroll
;     for (int m = 0; m < R; ++m) x[m] = X[PIDX(i0 + (m << sl))];
;     fft_stages<LR, INV>(x, r, s);
; #pragma unroll
;     for (int m = 0; m < R; ++m) X[PIDX(i0 + (m << sl))] = x[m];
;   }
	v_mul_f32_e32 v32, v16, v35
	v_mul_f32_e32 v33, v17, v35
	ds_write_b64 v50, v[40:41] offset:21760
	v_fma_f32 v38, v8, v34, -v32
	v_fma_f32 v39, v9, v34, v33

;     static __device__ __forceinline__ float sl(float g, float up) { return g * __builtin_amdgcn_rcpf(1.0f + __builtin_amdgcn_exp2f(-1.4426950408889634f * g)) * up; }
; __device__ __forceinline__ float2 cmul(float2 a, float2 b) { return make_float2(a.x * b.x - a.y * b.y, a.x * b.y + a.y * b.x); }
; #define tid ltid()
; template <int LR, bool INV>
; __device__ __forceinline__ void fft_stages(float2 (&x)[1 << LR], const int r, const int s) {
;   constexpr int R = 1 << LR;
; #pragma unroll
;   for (int st = 0; st < LR; ++st) {
;     const int hl = INV ? (1 << st) : (R >> (st + 1));
;     const float fb = (float)r * (0.5f / (float)(hl * s));
;     const float2 wb = make_float2(__builtin_amdgcn_cosf(fb), INV ? __builtin_amdgcn_sinf(fb) : -__builtin_amdgcn_sinf(fb));
; #pragma unroll
;     for (int m = 0; m < R; ++m) {
;       if (m & hl) continue;
;       const int k = m & (hl - 1); const int j = k * (8 / hl);
;       const float2 wc = make_float2(c16(j), INV ? s16(j) : -s16(j));
;       const float2 tw = cmul(wb, wc);
;       if (!INV) { const float2 p = x[m], q = x[m + hl]; x[m] = make_float2(p.x + q.x, p.y + q.y); x[m + hl] = cmul(make_float2(p.x - q.x, p.y - q.y), tw); }
;       else { const float2 p = x[m], q = cmul(x[m + hl], tw); x[m] = make_float2(p.x + q.x, p.y + q.y); x[m + hl] = make_float2(p.x - q.x, p.y - q.y); }
;     }
;   }
; }
; template <int LR, bool INV>
; __device__ __forceinline__ void fft_pass(float2* X, const int N, const int sl, const int tid) {
;   constexpr int R = 1 << LR;
;   const int s = 1 << sl;
;   for (int g = tid; g < (N >> LR); g += NTHR) {
;     const int r = g & (s - 1);
;     const int i0 = ((g >> sl) << (sl + LR)) + r;
;     float2 x[R];
; #pragma unroll
;     for (int m = 0; m < R; ++m) x[m] = X[PIDX(i0 + (m << sl))];
;     fft_stages<LR, INV>(x, r, s);
; #pragma unroll
;     for (int m = 0; m < R; ++m) X[PIDX(i0 + (m << sl))] = x[m];
;   }
	v_mul_f32_e32 v32, v18, v37
	v_mul_f32_e32 v33, v19, v37
	v_fma_f32 v34, v10, v36, -v32
	v_fma_f32 v35, v11, v36, v33

;     static __device__ __forceinline__ float sl(float g, float up) { return g * __builtin_amdgcn_rcpf(1.0f + __builtin_amdgcn_exp2f(-1.4426950408889634f * g)) * up; }
; __device__ __forceinline__ float2 cmul(float2 a, float2 b) { return make_float2(a.x * b.x - a.y * b.y, a.x * b.y + a.y * b.x); }
; #define tid ltid()
; template <int LR, bool INV>
; __device__ __forceinline__ void fft_stages(float2 (&x)[1 << LR], const int r, const int s) {
;   constexpr int R = 1 << LR;
; #pragma unroll
;   for (int st = 0; st < LR; ++st) {
;     const int hl = INV ? (1 << st) : (R >> (st + 1));
;     const float fb = (float)r * (0.5f / (float)(hl * s));
;     const float2 wb = make_float2(__builtin_amdgcn_cosf(fb), INV ? __builtin_amdgcn_sinf(fb) : -__builtin_amdgcn_sinf(fb));
; #pragma unroll
;     for (int m = 0; m < R; ++m) {
;       if (m & hl) continue;
;       const int k = m & (hl - 1); const int j = k * (8 / hl);
;       const float2 wc = make_float2(c16(j), INV ? s16(j) : -s16(j));
;       const float2 tw = cmul(wb, wc);
;       if (!INV) { const float2 p = x[m], q = x[m + hl]; x[m] = make_float2(p.x + q.x, p.y + q.y); x[m + hl] = cmul(make_float2(p.x - q.x, p.y - q.y), tw); }
;       else { const float2 p = x[m], q = cmul(x[m + hl], tw); x[m] = make_float2(p.x + q.x, p.y + q.y); x[m + hl] = make_float2(p.x - q.x, p.y - q.y); }
;     }
;   }
; }
; template <int LR, bool INV>
; __device__ __forceinline__ void fft_pass(float2* X, const int N, const int sl, const int tid) {
;   constexpr int R = 1 << LR;
;   const int s = 1 << sl;
;   for (int g = tid; g < (N >> LR); g += NTHR) {
;     const int r = g & (s - 1);
;     const int i0 = ((g >> sl) << (sl + LR)) + r;
;     float2 x[R];
; #pragma unroll
;     for (int m = 0; m < R; ++m) x[m] = X[PIDX(i0 + (m << sl))];
;     fft_stages<LR, INV>(x, r, s);
; #pragma unroll
;     for (int m = 0; m < R; ++m) X[PIDX(i0 + (m << sl))] = x[m];
;   }
	v_add_f32_e32 v32, v38, v34
	v_add_f32_e32 v33, v39, v35
	v_sub_f32_e32 v34, v38, v34
	v_sub_f32_e32 v35, v39, v35
	ds_write_b64 v50, v[32:33] offset:26112
	v_mul_f32_e32 v32, v14, v35
	v_mul_f32_e32 v33, v15, v35
	v_fma_f32 v36, v12, v34, -v32
	v_fma_f32 v32, v12, v34, v32
	v_fma_f32 v33, v13, v34, v33
	v_mov_b32_e32 v37, v33
	ds_write_b64 v50, v[36:37] offset:30464
	s_andn2_b64 exec, exec, s[14:15]
	s_cbranch_execnz .LBB0_651

;     static __device__ __forceinline__ float sl(float g, float up) { return g * __builtin_amdgcn_rcpf(1.0f + __builtin_amdgcn_exp2f(-1.4426950408889634f * g)) * up; }
; #define tid ltid()
; template <int LR, bool INV>
; __device__ __forceinline__ void fft_pass(float2* X, const int N, const int sl, const int tid) {
;     ...
;   for (int g = tid; g < (N >> LR); g += NTHR) {
;     const int r = g & (s - 1);
;     const int i0 = ((g >> sl) << (sl + LR)) + r;
;     float2 x[R];
; #pragma unroll
;     for (int m = 0; m < R; ++m) x[m] = X[PIDX(i0 + (m << sl))];
.LBB0_656:
	v_and_or_b32 v64, v63, s2, v61
	v_ashrrev_i32_e32 v65, 4, v64
	v_lshlrev_b32_e32 v66, 3, v64
	v_lshlrev_b32_e32 v65, 3, v65
	v_add3_u32 v98, s52, v66, v65


;     static __device__ __forceinline__ float sl(float g, float up) { return g * __builtin_amdgcn_rcpf(1.0f + __builtin_amdgcn_exp2f(-1.4426950408889634f * g)) * up; }
; __device__ __forceinline__ float2 cmul(float2 a, float2 b) { return make_float2(a.x * b.x - a.y * b.y, a.x * b.y + a.y * b.x); }
; #define tid ltid()
; template <int LR, bool INV>
; __device__ __forceinline__ void fft_stages(float2 (&x)[1 << LR], const int r, const int s) {
;   constexpr int R = 1 << LR;
; #pragma unroll
;   for (int st = 0; st < LR; ++st) {
;     const int hl = INV ? (1 << st) : (R >> (st + 1));
;     const float fb = (float)r * (0.5f / (float)(hl * s));
;     const float2 wb = make_float2(__builtin_amdgcn_cosf(fb), INV ? __builtin_amdgcn_sinf(fb) : -__builtin_amdgcn_sinf(fb));
; #pragma unroll
;     for (int m = 0; m < R; ++m) {
;       if (m & hl) continue;
;       const int k = m & (hl - 1); const int j = k * (8 / hl);
;       const float2 wc = make_float2(c16(j), INV ? s16(j) : -s16(j));
;       const float2 tw = cmul(wb, wc);
;       if (!INV) { const float2 p = x[m], q = x[m + hl]; x[m] = make_float2(p.x + q.x, p.y + q.y); x[m + hl] = cmul(make_float2(p.x - q.x, p.y - q.y), tw); }
;       else { const float2 p = x[m], q = cmul(x[m + hl], tw); x[m] = make_float2(p.x + q.x, p.y + q.y); x[m + hl] = make_float2(p.x - q.x, p.y - q.y); }
;     }
;   }
; }
; template <int LR, bool INV>
; __device__ __forceinline__ void fft_pass(float2* X, const int N, const int sl, const int tid) {
;   constexpr int R = 1 << LR;
;   const int s = 1 << sl;
;   for (int g = tid; g < (N >> LR); g += NTHR) {
;     const int r = g & (s - 1);
;     const int i0 = ((g >> sl) << (sl + LR)) + r;
;     float2 x[R];
; #pragma unroll
;     for (int m = 0; m < R; ++m) x[m] = X[PIDX(i0 + (m << sl))];
;     fft_stages<LR, INV>(x, r, s);
; #pragma unroll
;     for (int m = 0; m < R; ++m) X[PIDX(i0 + (m << sl))] = x[m];
;   }
	ds_read_b64 v[64:65], v98
	ds_read_b64 v[66:67], v98 offset:4352
	ds_read_b64 v[68:69], v98 offset:8704
	ds_read_b64 v[70:71], v98 offset:13056
	ds_read_b64 v[72:73], v98 offset:17408
	ds_read_b64 v[74:75], v98 offset:21760
	ds_read_b64 v[76:77], v98 offset:26112
	ds_read_b64 v[78:79], v98 offset:30464
	ds_read_b64 v[80:81], v98 offset:34816
	ds_read_b64 v[82:83], v98 offset:39168
	ds_read_b64 v[84:85], v98 offset:43520
	ds_read_b64 v[86:87], v98 offset:47872
	ds_read_b64 v[88:89], v98 offset:52224
	ds_read_b64 v[90:91], v98 offset:56576
	ds_read_b64 v[92:93], v98 offset:60928
	ds_read_b64 v[94:95], v98 offset:65280
	s_waitcnt lgkmcnt(7)
	v_add_f32_e32 v96, v64, v80
	v_add_f32_e32 v97, v65, v81
	v_sub_f32_e32 v64, v64, v80
	v_sub_f32_e32 v65, v65, v81
	s_waitcnt lgkmcnt(6)
	v_add_f32_e32 v80, v66, v82
	v_add_f32_e32 v81, v67, v83
	v_sub_f32_e32 v66, v66, v82
	v_sub_f32_e32 v67, v67, v83
	s_waitcnt lgkmcnt(5)
	v_add_f32_e32 v82, v68, v84
	v_add_f32_e32 v83, v69, v85
	v_sub_f32_e32 v68, v68, v84
	v_sub_f32_e32 v69, v69, v85
	s_waitcnt lgkmcnt(4)
	v_add_f32_e32 v84, v70, v86
	v_add_f32_e32 v85, v71, v87
	v_sub_f32_e32 v70, v70, v86
	v_sub_f32_e32 v71, v71, v87
	s_waitcnt lgkmcnt(3)
	v_add_f32_e32 v86, v72, v88
	v_add_f32_e32 v87, v73, v89
	v_sub_f32_e32 v72, v72, v88
	v_sub_f32_e32 v73, v73, v89
	s_waitcnt lgkmcnt(2)
	v_add_f32_e32 v88, v74, v90
	v_add_f32_e32 v89, v75, v91
	v_sub_f32_e32 v74, v74, v90
	v_sub_f32_e32 v75, v75, v91
	s_waitcnt lgkmcnt(1)
	v_add_f32_e32 v90, v76, v92
	v_add_f32_e32 v91, v77, v93
	v_sub_f32_e32 v76, v76, v92
	v_sub_f32_e32 v77, v77, v93
	s_waitcnt lgkmcnt(0)
	v_add_f32_e32 v92, v78, v94
	v_add_f32_e32 v93, v79, v95
	v_sub_f32_e32 v78, v78, v94
	v_sub_f32_e32 v79, v79, v95
	v_add_f32_e32 v94, v96, v86
	v_add_f32_e32 v95, v97, v87
	v_sub_f32_e32 v86, v96, v86
	v_sub_f32_e32 v87, v97, v87
	v_add_f32_e32 v96, v80, v88
	v_add_f32_e32 v97, v81, v89
	v_sub_f32_e32 v80, v80, v88
	v_sub_f32_e32 v81, v81, v89
	v_add_f32_e32 v88, v82, v90
	v_add_f32_e32 v89, v83, v91
	v_sub_f32_e32 v82, v82, v90
	v_sub_f32_e32 v83, v83, v91
	v_add_f32_e32 v90, v84, v92
	v_add_f32_e32 v91, v85, v93
	v_sub_f32_e32 v84, v84, v92
	v_sub_f32_e32 v85, v85, v93
	v_add_f32_e32 v92, v94, v88
	v_add_f32_e32 v93, v95, v89
	v_sub_f32_e32 v88, v94, v88
	v_sub_f32_e32 v89, v95, v89
	v_add_f32_e32 v94, v96, v90
	v_add_f32_e32 v95, v97, v91
	v_sub_f32_e32 v90, v96, v90
	v_sub_f32_e32 v91, v97, v91
	v_add_f32_e32 v96, v92, v94
	v_add_f32_e32 v97, v93, v95
	v_sub_f32_e32 v92, v92, v94
	v_sub_f32_e32 v93, v93, v95
	ds_write_b64 v98, v[96:97]
	v_mul_f32_e32 v94, v30, v93
	v_mul_f32_e32 v95, v31, v93
	v_add_u32_e32 v62, 0x200, v62
	v_fma_f32 v96, v28, v92, -v94
	v_fma_f32 v97, v29, v92, v95
	v_cmp_lt_i32_e32 vcc, -1, v62

;     static __device__ __forceinline__ float sl(float g, float up) { return g * __builtin_amdgcn_rcpf(1.0f + __builtin_amdgcn_exp2f(-1.4426950408889634f * g)) * up; }
; __device__ __forceinline__ float2 cmul(float2 a, float2 b) { return make_float2(a.x * b.x - a.y * b.y, a.x * b.y + a.y * b.x); }
; #define tid ltid()
; template <int LR, bool INV>
; __device__ __forceinline__ void fft_stages(float2 (&x)[1 << LR], const int r, const int s) {
;   constexpr int R = 1 << LR;
; #pragma unroll
;   for (int st = 0; st < LR; ++st) {
;     const int hl = INV ? (1 << st) : (R >> (st + 1));
;     const float fb = (float)r * (0.5f / (float)(hl * s));
;     const float2 wb = make_float2(__builtin_amdgcn_cosf(fb), INV ? __builtin_amdgcn_sinf(fb) : -__builtin_amdgcn_sinf(fb));
; #pragma unroll
;     for (int m = 0; m < R; ++m) {
;       if (m & hl) continue;
;       const int k = m & (hl - 1); const int j = k * (8 / hl);
;       const float2 wc = make_float2(c16(j), INV ? s16(j) : -s16(j));
;       const float2 tw = cmul(wb, wc);
;       if (!INV) { const float2 p = x[m], q = x[m + hl]; x[m] = make_float2(p.x + q.x, p.y + q.y); x[m + hl] = cmul(make_float2(p.x - q.x, p.y - q.y), tw); }
;       else { const float2 p = x[m], q = cmul(x[m + hl], tw); x[m] = make_float2(p.x + q.x, p.y + q.y); x[m + hl] = make_float2(p.x - q.x, p.y - q.y); }
;     }
;   }
; }
; template <int LR, bool INV>
; __device__ __forceinline__ void fft_pass(float2* X, const int N, const int sl, const int tid) {
;   constexpr int R = 1 << LR;
;   const int s = 1 << sl;
;   for (int g = tid; g < (N >> LR); g += NTHR) {
;     const int r = g & (s - 1);
;     const int i0 = ((g >> sl) << (sl + LR)) + r;
;     float2 x[R];
; #pragma unroll
;     for (int m = 0; m < R; ++m) x[m] = X[PIDX(i0 + (m << sl))];
;     fft_stages<LR, INV>(x, r, s);
; #pragma unroll
;     for (int m = 0; m < R; ++m) X[PIDX(i0 + (m << sl))] = x[m];
;   }
	v_mul_f32_e32 v92, v32, v89
	v_mul_f32_e32 v93, v33, v89
	ds_write_b64 v98, v[96:97] offset:4352
	v_fma_f32 v94, v24, v88, -v92
	v_fma_f32 v95, v25, v88, v93
	v_add_u32_e32 v63, 0x2000, v63

;     static __device__ __forceinline__ float sl(float g, float up) { return g * __builtin_amdgcn_rcpf(1.0f + __builtin_amdgcn_exp2f(-1.4426950408889634f * g)) * up; }
; __device__ __forceinline__ float2 cmul(float2 a, float2 b) { return make_float2(a.x * b.x - a.y * b.y, a.x * b.y + a.y * b.x); }
; #define tid ltid()
; template <int LR, bool INV>
; __device__ __forceinline__ void fft_stages(float2 (&x)[1 << LR], const int r, const int s) {
;   constexpr int R = 1 << LR;
; #pragma unroll
;   for (int st = 0; st < LR; ++st) {
;     const int hl = INV ? (1 << st) : (R >> (st + 1));
;     const float fb = (float)r * (0.5f / (float)(hl * s));
;     const float2 wb = make_float2(__builtin_amdgcn_cosf(fb), INV ? __builtin_amdgcn_sinf(fb) : -__builtin_amdgcn_sinf(fb));
; #pragma unroll
;     for (int m = 0; m < R; ++m) {
;       if (m & hl) continue;
;       const int k = m & (hl - 1); const int j = k * (8 / hl);
;       const float2 wc = make_float2(c16(j), INV ? s16(j) : -s16(j));
;       const float2 tw = cmul(wb, wc);
;       if (!INV) { const float2 p = x[m], q = x[m + hl]; x[m] = make_float2(p.x + q.x, p.y + q.y); x[m + hl] = cmul(make_float2(p.x - q.x, p.y - q.y), tw); }
;       else { const float2 p = x[m], q = cmul(x[m + hl], tw); x[m] = make_float2(p.x + q.x, p.y + q.y); x[m + hl] = make_float2(p.x - q.x, p.y - q.y); }
;     }
;   }
; }
; template <int LR, bool INV>
; __device__ __forceinline__ void fft_pass(float2* X, const int N, const int sl, const int tid) {
;   constexpr int R = 1 << LR;
;   const int s = 1 << sl;
;   for (int g = tid; g < (N >> LR); g += NTHR) {
;     const int r = g & (s - 1);
;     const int i0 = ((g >> sl) << (sl + LR)) + r;
;     float2 x[R];
; #pragma unroll
;     for (int m = 0; m < R; ++m) x[m] = X[PIDX(i0 + (m << sl))];
;     fft_stages<LR, INV>(x, r, s);
; #pragma unroll
;     for (int m = 0; m < R; ++m) X[PIDX(i0 + (m << sl))] = x[m];
;   }
	v_mul_f32_e32 v88, v34, v91
	v_mul_f32_e32 v89, v35, v91
	s_or_b64 s[14:15], vcc, s[14:15]
	v_fma_f32 v92, v26, v90, -v88
	v_fma_f32 v93, v27, v90, v89

;     static __device__ __forceinline__ float sl(float g, float up) { return g * __builtin_amdgcn_rcpf(1.0f + __builtin_amdgcn_exp2f(-1.4426950408889634f * g)) * up; }
; __device__ __forceinline__ float2 cmul(float2 a, float2 b) { return make_float2(a.x * b.x - a.y * b.y, a.x * b.y + a.y * b.x); }
; template <int LR, bool INV>
; __device__ __forceinline__ void fft_stages(float2 (&x)[1 << LR], const int r, const int s) {
;     ...
;     for (int m = 0; m < R; ++m) {
;       if (m & hl) continue;
;       const int k = m & (hl - 1); const int j = k * (8 / hl);
;       const float2 wc = make_float2(c16(j), INV ? s16(j) : -s16(j));
;       const float2 tw = cmul(wb, wc);
;       if (!INV) { const float2 p = x[m], q = x[m + hl]; x[m] = make_float2(p.x + q.x, p.y + q.y); x[m + hl] = cmul(make_float2(p.x - q.x, p.y - q.y), tw); }
;       else { const float2 p = x[m], q = cmul(x[m + hl], tw); x[m] = make_float2(p.x + q.x, p.y + q.y); x[m + hl] = make_float2(p.x - q.x, p.y - q.y); }
;     }
; template <int LR, bool INV>
; __device__ __forceinline__ void fft_pass(float2* X, const int N, const int sl, const int tid) {
;     ...
;     for (int m = 0; m < R; ++m) X[PIDX(i0 + (m << sl))] = x[m];
	v_add_f32_e32 v88, v94, v92
	v_add_f32_e32 v89, v95, v93
	v_sub_f32_e32 v90, v94, v92
	v_sub_f32_e32 v91, v95, v93
	ds_write_b64 v98, v[88:89] offset:8704
	v_mul_f32_e32 v88, v30, v91
	v_mul_f32_e32 v89, v31, v91
	v_fma_f32 v92, v28, v90, -v88
	v_fma_f32 v93, v29, v90, v89

;     static __device__ __forceinline__ float sl(float g, float up) { return g * __builtin_amdgcn_rcpf(1.0f + __builtin_amdgcn_exp2f(-1.4426950408889634f * g)) * up; }
; __device__ __forceinline__ float2 cmul(float2 a, float2 b) { return make_float2(a.x * b.x - a.y * b.y, a.x * b.y + a.y * b.x); }
; template <int LR, bool INV>
; __device__ __forceinline__ void fft_stages(float2 (&x)[1 << LR], const int r, const int s) {
;     ...
;     for (int m = 0; m < R; ++m) {
;       if (m & hl) continue;
;       const int k = m & (hl - 1); const int j = k * (8 / hl);
;       const float2 wc = make_float2(c16(j), INV ? s16(j) : -s16(j));
;       const float2 tw = cmul(wb, wc);
;       if (!INV) { const float2 p = x[m], q = x[m + hl]; x[m] = make_float2(p.x + q.x, p.y + q.y); x[m + hl] = cmul(make_float2(p.x - q.x, p.y - q.y), tw); }
;       else { const float2 p = x[m], q = cmul(x[m + hl], tw); x[m] = make_float2(p.x + q.x, p.y + q.y); x[m + hl] = make_float2(p.x - q.x, p.y - q.y); }
;     }
; template <int LR, bool INV>
; __device__ __forceinline__ void fft_pass(float2* X, const int N, const int sl, const int tid) {
;     ...
;     for (int m = 0; m < R; ++m) X[PIDX(i0 + (m << sl))] = x[m];
	v_mul_f32_e32 v88, v36, v87
	v_mul_f32_e32 v89, v37, v87
	ds_write_b64 v98, v[92:93] offset:13056
	v_fma_f32 v90, v16, v86, -v88
	v_fma_f32 v91, v17, v86, v89

; __device__ __forceinline__ float2 cmul(float2 a, float2 b) { return make_float2(a.x * b.x - a.y * b.y, a.x * b.y + a.y * b.x); }
; template <int LR, bool INV>
; __device__ __forceinline__ void fft_stages(float2 (&x)[1 << LR], const int r, const int s) {
;     ...
;     for (int m = 0; m < R; ++m) {
;       if (m & hl) continue;
;       const int k = m & (hl - 1); const int j = k * (8 / hl);
;       const float2 wc = make_float2(c16(j), INV ? s16(j) : -s16(j));
;       const float2 tw = cmul(wb, wc);
;       if (!INV) { const float2 p = x[m], q = x[m + hl]; x[m] = make_float2(p.x + q.x, p.y + q.y); x[m + hl] = cmul(make_float2(p.x - q.x, p.y - q.y), tw); }
;       else { const float2 p = x[m], q = cmul(x[m + hl], tw); x[m] = make_float2(p.x + q.x, p.y + q.y); x[m + hl] = make_float2(p.x - q.x, p.y - q.y); }
;     }
	v_mul_f32_e32 v86, v38, v81
	v_mul_f32_e32 v87, v39, v81
	v_fma_f32 v88, v18, v80, -v86
	v_fma_f32 v89, v19, v80, v87

; __device__ __forceinline__ float2 cmul(float2 a, float2 b) { return make_float2(a.x * b.x - a.y * b.y, a.x * b.y + a.y * b.x); }
; template <int LR, bool INV>
; __device__ __forceinline__ void fft_stages(float2 (&x)[1 << LR], const int r, const int s) {
;     ...
;     for (int m = 0; m < R; ++m) {
;       if (m & hl) continue;
;       const int k = m & (hl - 1); const int j = k * (8 / hl);
;       const float2 wc = make_float2(c16(j), INV ? s16(j) : -s16(j));
;       const float2 tw = cmul(wb, wc);
;       if (!INV) { const float2 p = x[m], q = x[m + hl]; x[m] = make_float2(p.x + q.x, p.y + q.y); x[m + hl] = cmul(make_float2(p.x - q.x, p.y - q.y), tw); }
;       else { const float2 p = x[m], q = cmul(x[m + hl], tw); x[m] = make_float2(p.x + q.x, p.y + q.y); x[m + hl] = make_float2(p.x - q.x, p.y - q.y); }
;     }
	v_mul_f32_e32 v80, v40, v83
	v_mul_f32_e32 v81, v41, v83
	v_fma_f32 v86, v20, v82, -v80
	v_fma_f32 v87, v21, v82, v81

; __device__ __forceinline__ float2 cmul(float2 a, float2 b) { return make_float2(a.x * b.x - a.y * b.y, a.x * b.y + a.y * b.x); }
; template <int LR, bool INV>
; __device__ __forceinline__ void fft_stages(float2 (&x)[1 << LR], const int r, const int s) {
;     ...
;     for (int m = 0; m < R; ++m) {
;       if (m & hl) continue;
;       const int k = m & (hl - 1); const int j = k * (8 / hl);
;       const float2 wc = make_float2(c16(j), INV ? s16(j) : -s16(j));
;       const float2 tw = cmul(wb, wc);
;       if (!INV) { const float2 p = x[m], q = x[m + hl]; x[m] = make_float2(p.x + q.x, p.y + q.y); x[m + hl] = cmul(make_float2(p.x - q.x, p.y - q.y), tw); }
;       else { const float2 p = x[m], q = cmul(x[m + hl], tw); x[m] = make_float2(p.x + q.x, p.y + q.y); x[m + hl] = make_float2(p.x - q.x, p.y - q.y); }
;     }
	v_mul_f32_e32 v80, v42, v85
	v_mul_f32_e32 v81, v43, v85
	v_fma_f32 v82, v22, v84, -v80
	v_fma_f32 v83, v23, v84, v81
	v_sub_f32_e32 v84, v90, v86
	v_sub_f32_e32 v85, v91, v87

;     static __device__ __forceinline__ float sl(float g, float up) { return g * __builtin_amdgcn_rcpf(1.0f + __builtin_amdgcn_exp2f(-1.4426950408889634f * g)) * up; }
; __device__ __forceinline__ float2 cmul(float2 a, float2 b) { return make_float2(a.x * b.x - a.y * b.y, a.x * b.y + a.y * b.x); }
; template <int LR, bool INV>
; __device__ __forceinline__ void fft_stages(float2 (&x)[1 << LR], const int r, const int s) {
;     ...
;     for (int m = 0; m < R; ++m) {
;       if (m & hl) continue;
;       const int k = m & (hl - 1); const int j = k * (8 / hl);
;       const float2 wc = make_float2(c16(j), INV ? s16(j) : -s16(j));
;       const float2 tw = cmul(wb, wc);
;       if (!INV) { const float2 p = x[m], q = x[m + hl]; x[m] = make_float2(p.x + q.x, p.y + q.y); x[m + hl] = cmul(make_float2(p.x - q.x, p.y - q.y), tw); }
;       else { const float2 p = x[m], q = cmul(x[m + hl], tw); x[m] = make_float2(p.x + q.x, p.y + q.y); x[m + hl] = make_float2(p.x - q.x, p.y - q.y); }
;     }
; template <int LR, bool INV>
; __device__ __forceinline__ void fft_pass(float2* X, const int N, const int sl, const int tid) {
;     ...
;     for (int m = 0; m < R; ++m) X[PIDX(i0 + (m << sl))] = x[m];
	v_add_f32_e32 v80, v90, v86
	v_add_f32_e32 v81, v91, v87
	v_add_f32_e32 v86, v88, v82
	v_add_f32_e32 v87, v89, v83
	v_sub_f32_e32 v82, v88, v82
	v_sub_f32_e32 v83, v89, v83
	v_add_f32_e32 v88, v80, v86
	v_add_f32_e32 v89, v81, v87
	v_sub_f32_e32 v80, v80, v86
	v_sub_f32_e32 v81, v81, v87
	ds_write_b64 v98, v[88:89] offset:17408
	v_mul_f32_e32 v86, v30, v81
	v_mul_f32_e32 v87, v31, v81
	v_fma_f32 v88, v28, v80, -v86
	v_fma_f32 v89, v29, v80, v87

;     static __device__ __forceinline__ float sl(float g, float up) { return g * __builtin_amdgcn_rcpf(1.0f + __builtin_amdgcn_exp2f(-1.4426950408889634f * g)) * up; }
; __device__ __forceinline__ float2 cmul(float2 a, float2 b) { return make_float2(a.x * b.x - a.y * b.y, a.x * b.y + a.y * b.x); }
; template <int LR, bool INV>
; __device__ __forceinline__ void fft_stages(float2 (&x)[1 << LR], const int r, const int s) {
;     ...
;     for (int m = 0; m < R; ++m) {
;       if (m & hl) continue;
;       const int k = m & (hl - 1); const int j = k * (8 / hl);
;       const float2 wc = make_float2(c16(j), INV ? s16(j) : -s16(j));
;       const float2 tw = cmul(wb, wc);
;       if (!INV) { const float2 p = x[m], q = x[m + hl]; x[m] = make_float2(p.x + q.x, p.y + q.y); x[m + hl] = cmul(make_float2(p.x - q.x, p.y - q.y), tw); }
;       else { const float2 p = x[m], q = cmul(x[m + hl], tw); x[m] = make_float2(p.x + q.x, p.y + q.y); x[m + hl] = make_float2(p.x - q.x, p.y - q.y); }
;     }
; template <int LR, bool INV>
; __device__ __forceinline__ void fft_pass(float2* X, const int N, const int sl, const int tid) {
;     ...
;     for (int m = 0; m < R; ++m) X[PIDX(i0 + (m << sl))] = x[m];
	v_mul_f32_e32 v80, v32, v85
	v_mul_f32_e32 v81, v33, v85
	ds_write_b64 v98, v[88:89] offset:21760
	v_fma_f32 v86, v24, v84, -v80
	v_fma_f32 v87, v25, v84, v81

; __device__ __forceinline__ float2 cmul(float2 a, float2 b) { return make_float2(a.x * b.x - a.y * b.y, a.x * b.y + a.y * b.x); }
; template <int LR, bool INV>
; __device__ __forceinline__ void fft_stages(float2 (&x)[1 << LR], const int r, const int s) {
;     ...
;     for (int m = 0; m < R; ++m) {
;       if (m & hl) continue;
;       const int k = m & (hl - 1); const int j = k * (8 / hl);
;       const float2 wc = make_float2(c16(j), INV ? s16(j) : -s16(j));
;       const float2 tw = cmul(wb, wc);
;       if (!INV) { const float2 p = x[m], q = x[m + hl]; x[m] = make_float2(p.x + q.x, p.y + q.y); x[m + hl] = cmul(make_float2(p.x - q.x, p.y - q.y), tw); }
;       else { const float2 p = x[m], q = cmul(x[m + hl], tw); x[m] = make_float2(p.x + q.x, p.y + q.y); x[m + hl] = make_float2(p.x - q.x, p.y - q.y); }
;     }
	v_mul_f32_e32 v80, v34, v83
	v_mul_f32_e32 v81, v35, v83
	v_fma_f32 v84, v26, v82, -v80
	v_fma_f32 v85, v27, v82, v81

;     static __device__ __forceinline__ float sl(float g, float up) { return g * __builtin_amdgcn_rcpf(1.0f + __builtin_amdgcn_exp2f(-1.4426950408889634f * g)) * up; }
; __device__ __forceinline__ float2 cmul(float2 a, float2 b) { return make_float2(a.x * b.x - a.y * b.y, a.x * b.y + a.y * b.x); }
; template <int LR, bool INV>
; __device__ __forceinline__ void fft_stages(float2 (&x)[1 << LR], const int r, const int s) {
;     ...
;     for (int m = 0; m < R; ++m) {
;       if (m & hl) continue;
;       const int k = m & (hl - 1); const int j = k * (8 / hl);
;       const float2 wc = make_float2(c16(j), INV ? s16(j) : -s16(j));
;       const float2 tw = cmul(wb, wc);
;       if (!INV) { const float2 p = x[m], q = x[m + hl]; x[m] = make_float2(p.x + q.x, p.y + q.y); x[m + hl] = cmul(make_float2(p.x - q.x, p.y - q.y), tw); }
;       else { const float2 p = x[m], q = cmul(x[m + hl], tw); x[m] = make_float2(p.x + q.x, p.y + q.y); x[m + hl] = make_float2(p.x - q.x, p.y - q.y); }
;     }
; template <int LR, bool INV>
; __device__ __forceinline__ void fft_pass(float2* X, const int N, const int sl, const int tid) {
;     ...
;     for (int m = 0; m < R; ++m) X[PIDX(i0 + (m << sl))] = x[m];
	v_add_f32_e32 v80, v86, v84
	v_add_f32_e32 v81, v87, v85
	v_sub_f32_e32 v82, v86, v84
	v_sub_f32_e32 v83, v87, v85
	ds_write_b64 v98, v[80:81] offset:26112
	v_mul_f32_e32 v80, v30, v83
	v_mul_f32_e32 v81, v31, v83
	v_fma_f32 v84, v28, v82, -v80
	v_fma_f32 v85, v29, v82, v81

;     static __device__ __forceinline__ float sl(float g, float up) { return g * __builtin_amdgcn_rcpf(1.0f + __builtin_amdgcn_exp2f(-1.4426950408889634f * g)) * up; }
; __device__ __forceinline__ float2 cmul(float2 a, float2 b) { return make_float2(a.x * b.x - a.y * b.y, a.x * b.y + a.y * b.x); }
; template <int LR, bool INV>
; __device__ __forceinline__ void fft_stages(float2 (&x)[1 << LR], const int r, const int s) {
;     ...
;     for (int m = 0; m < R; ++m) {
;       if (m & hl) continue;
;       const int k = m & (hl - 1); const int j = k * (8 / hl);
;       const float2 wc = make_float2(c16(j), INV ? s16(j) : -s16(j));
;       const float2 tw = cmul(wb, wc);
;       if (!INV) { const float2 p = x[m], q = x[m + hl]; x[m] = make_float2(p.x + q.x, p.y + q.y); x[m + hl] = cmul(make_float2(p.x - q.x, p.y - q.y), tw); }
;       else { const float2 p = x[m], q = cmul(x[m + hl], tw); x[m] = make_float2(p.x + q.x, p.y + q.y); x[m + hl] = make_float2(p.x - q.x, p.y - q.y); }
;     }
; template <int LR, bool INV>
; __device__ __forceinline__ void fft_pass(float2* X, const int N, const int sl, const int tid) {
;     ...
;     for (int m = 0; m < R; ++m) X[PIDX(i0 + (m << sl))] = x[m];
	v_mul_f32_e32 v80, v44, v65
	v_mul_f32_e32 v81, v45, v65
	ds_write_b64 v98, v[84:85] offset:30464
	v_fma_f32 v82, v0, v64, -v80
	v_fma_f32 v83, v1, v64, v81

; __device__ __forceinline__ float2 cmul(float2 a, float2 b) { return make_float2(a.x * b.x - a.y * b.y, a.x * b.y + a.y * b.x); }
; template <int LR, bool INV>
; __device__ __forceinline__ void fft_stages(float2 (&x)[1 << LR], const int r, const int s) {
;     ...
;     for (int m = 0; m < R; ++m) {
;       if (m & hl) continue;
;       const int k = m & (hl - 1); const int j = k * (8 / hl);
;       const float2 wc = make_float2(c16(j), INV ? s16(j) : -s16(j));
;       const float2 tw = cmul(wb, wc);
;       if (!INV) { const float2 p = x[m], q = x[m + hl]; x[m] = make_float2(p.x + q.x, p.y + q.y); x[m + hl] = cmul(make_float2(p.x - q.x, p.y - q.y), tw); }
;       else { const float2 p = x[m], q = cmul(x[m + hl], tw); x[m] = make_float2(p.x + q.x, p.y + q.y); x[m + hl] = make_float2(p.x - q.x, p.y - q.y); }
;     }
	v_mul_f32_e32 v64, v46, v67
	v_mul_f32_e32 v65, v47, v67
	v_fma_f32 v80, v2, v66, -v64
	v_fma_f32 v81, v3, v66, v65

; __device__ __forceinline__ float2 cmul(float2 a, float2 b) { return make_float2(a.x * b.x - a.y * b.y, a.x * b.y + a.y * b.x); }
; template <int LR, bool INV>
; __device__ __forceinline__ void fft_stages(float2 (&x)[1 << LR], const int r, const int s) {
;     ...
;     for (int m = 0; m < R; ++m) {
;       if (m & hl) continue;
;       const int k = m & (hl - 1); const int j = k * (8 / hl);
;       const float2 wc = make_float2(c16(j), INV ? s16(j) : -s16(j));
;       const float2 tw = cmul(wb, wc);
;       if (!INV) { const float2 p = x[m], q = x[m + hl]; x[m] = make_float2(p.x + q.x, p.y + q.y); x[m + hl] = cmul(make_float2(p.x - q.x, p.y - q.y), tw); }
;       else { const float2 p = x[m], q = cmul(x[m + hl], tw); x[m] = make_float2(p.x + q.x, p.y + q.y); x[m + hl] = make_float2(p.x - q.x, p.y - q.y); }
;     }
	v_mul_f32_e32 v64, v48, v69
	v_mul_f32_e32 v65, v49, v69
	v_fma_f32 v66, v4, v68, -v64
	v_fma_f32 v67, v5, v68, v65

; __device__ __forceinline__ float2 cmul(float2 a, float2 b) { return make_float2(a.x * b.x - a.y * b.y, a.x * b.y + a.y * b.x); }
; template <int LR, bool INV>
; __device__ __forceinline__ void fft_stages(float2 (&x)[1 << LR], const int r, const int s) {
;     ...
;     for (int m = 0; m < R; ++m) {
;       if (m & hl) continue;
;       const int k = m & (hl - 1); const int j = k * (8 / hl);
;       const float2 wc = make_float2(c16(j), INV ? s16(j) : -s16(j));
;       const float2 tw = cmul(wb, wc);
;       if (!INV) { const float2 p = x[m], q = x[m + hl]; x[m] = make_float2(p.x + q.x, p.y + q.y); x[m + hl] = cmul(make_float2(p.x - q.x, p.y - q.y), tw); }
;       else { const float2 p = x[m], q = cmul(x[m + hl], tw); x[m] = make_float2(p.x + q.x, p.y + q.y); x[m + hl] = make_float2(p.x - q.x, p.y - q.y); }
;     }
	v_mul_f32_e32 v64, v50, v71
	v_mul_f32_e32 v65, v51, v71
	v_fma_f32 v68, v6, v70, -v64
	v_fma_f32 v69, v7, v70, v65

; __device__ __forceinline__ float2 cmul(float2 a, float2 b) { return make_float2(a.x * b.x - a.y * b.y, a.x * b.y + a.y * b.x); }
; template <int LR, bool INV>
; __device__ __forceinline__ void fft_stages(float2 (&x)[1 << LR], const int r, const int s) {
;     ...
;     for (int m = 0; m < R; ++m) {
;       if (m & hl) continue;
;       const int k = m & (hl - 1); const int j = k * (8 / hl);
;       const float2 wc = make_float2(c16(j), INV ? s16(j) : -s16(j));
;       const float2 tw = cmul(wb, wc);
;       if (!INV) { const float2 p = x[m], q = x[m + hl]; x[m] = make_float2(p.x + q.x, p.y + q.y); x[m + hl] = cmul(make_float2(p.x - q.x, p.y - q.y), tw); }
;       else { const float2 p = x[m], q = cmul(x[m + hl], tw); x[m] = make_float2(p.x + q.x, p.y + q.y); x[m + hl] = make_float2(p.x - q.x, p.y - q.y); }
;     }
	v_mul_f32_e32 v64, v52, v73
	v_mul_f32_e32 v65, v53, v73
	v_fma_f32 v70, v8, v72, -v64
	v_fma_f32 v71, v9, v72, v65

; __device__ __forceinline__ float2 cmul(float2 a, float2 b) { return make_float2(a.x * b.x - a.y * b.y, a.x * b.y + a.y * b.x); }
; template <int LR, bool INV>
; __device__ __forceinline__ void fft_stages(float2 (&x)[1 << LR], const int r, const int s) {
;     ...
;     for (int m = 0; m < R; ++m) {
;       if (m & hl) continue;
;       const int k = m & (hl - 1); const int j = k * (8 / hl);
;       const float2 wc = make_float2(c16(j), INV ? s16(j) : -s16(j));
;       const float2 tw = cmul(wb, wc);
;       if (!INV) { const float2 p = x[m], q = x[m + hl]; x[m] = make_float2(p.x + q.x, p.y + q.y); x[m + hl] = cmul(make_float2(p.x - q.x, p.y - q.y), tw); }
;       else { const float2 p = x[m], q = cmul(x[m + hl], tw); x[m] = make_float2(p.x + q.x, p.y + q.y); x[m + hl] = make_float2(p.x - q.x, p.y - q.y); }
;     }
	v_mul_f32_e32 v64, v54, v75
	v_mul_f32_e32 v65, v55, v75
	v_fma_f32 v72, v10, v74, -v64
	v_fma_f32 v73, v11, v74, v65

; __device__ __forceinline__ float2 cmul(float2 a, float2 b) { return make_float2(a.x * b.x - a.y * b.y, a.x * b.y + a.y * b.x); }
; template <int LR, bool INV>
; __device__ __forceinline__ void fft_stages(float2 (&x)[1 << LR], const int r, const int s) {
;     ...
;     for (int m = 0; m < R; ++m) {
;       if (m & hl) continue;
;       const int k = m & (hl - 1); const int j = k * (8 / hl);
;       const float2 wc = make_float2(c16(j), INV ? s16(j) : -s16(j));
;       const float2 tw = cmul(wb, wc);
;       if (!INV) { const float2 p = x[m], q = x[m + hl]; x[m] = make_float2(p.x + q.x, p.y + q.y); x[m + hl] = cmul(make_float2(p.x - q.x, p.y - q.y), tw); }
;       else { const float2 p = x[m], q = cmul(x[m + hl], tw); x[m] = make_float2(p.x + q.x, p.y + q.y); x[m + hl] = make_float2(p.x - q.x, p.y - q.y); }
;     }
	v_mul_f32_e32 v64, v56, v77
	v_mul_f32_e32 v65, v57, v77
	v_fma_f32 v74, v12, v76, -v64
	v_fma_f32 v75, v13, v76, v65

; __device__ __forceinline__ float2 cmul(float2 a, float2 b) { return make_float2(a.x * b.x - a.y * b.y, a.x * b.y + a.y * b.x); }
; template <int LR, bool INV>
; __device__ __forceinline__ void fft_stages(float2 (&x)[1 << LR], const int r, const int s) {
;     ...
;     for (int m = 0; m < R; ++m) {
;       if (m & hl) continue;
;       const int k = m & (hl - 1); const int j = k * (8 / hl);
;       const float2 wc = make_float2(c16(j), INV ? s16(j) : -s16(j));
;       const float2 tw = cmul(wb, wc);
;       if (!INV) { const float2 p = x[m], q = x[m + hl]; x[m] = make_float2(p.x + q.x, p.y + q.y); x[m + hl] = cmul(make_float2(p.x - q.x, p.y - q.y), tw); }
;       else { const float2 p = x[m], q = cmul(x[m + hl], tw); x[m] = make_float2(p.x + q.x, p.y + q.y); x[m + hl] = make_float2(p.x - q.x, p.y - q.y); }
;     }
	v_mul_f32_e32 v64, v58, v79
	v_mul_f32_e32 v65, v59, v79
	v_fma_f32 v76, v14, v78, -v64
	v_fma_f32 v77, v15, v78, v65
	v_add_f32_e32 v78, v80, v72
	v_add_f32_e32 v79, v81, v73

;     static __device__ __forceinline__ float sl(float g, float up) { return g * __builtin_amdgcn_rcpf(1.0f + __builtin_amdgcn_exp2f(-1.4426950408889634f * g)) * up; }
; __device__ __forceinline__ float2 cmul(float2 a, float2 b) { return make_float2(a.x * b.x - a.y * b.y, a.x * b.y + a.y * b.x); }
; template <int LR, bool INV>
; __device__ __forceinline__ void fft_stages(float2 (&x)[1 << LR], const int r, const int s) {
;     ...
;     for (int m = 0; m < R; ++m) {
;       if (m & hl) continue;
;       const int k = m & (hl - 1); const int j = k * (8 / hl);
;       const float2 wc = make_float2(c16(j), INV ? s16(j) : -s16(j));
;       const float2 tw = cmul(wb, wc);
;       if (!INV) { const float2 p = x[m], q = x[m + hl]; x[m] = make_float2(p.x + q.x, p.y + q.y); x[m + hl] = cmul(make_float2(p.x - q.x, p.y - q.y), tw); }
;       else { const float2 p = x[m], q = cmul(x[m + hl], tw); x[m] = make_float2(p.x + q.x, p.y + q.y); x[m + hl] = make_float2(p.x - q.x, p.y - q.y); }
;     }
; template <int LR, bool INV>
; __device__ __forceinline__ void fft_pass(float2* X, const int N, const int sl, const int tid) {
;     ...
;     for (int m = 0; m < R; ++m) X[PIDX(i0 + (m << sl))] = x[m];
	v_add_f32_e32 v64, v82, v70
	v_add_f32_e32 v65, v83, v71
	v_sub_f32_e32 v72, v80, v72
	v_sub_f32_e32 v73, v81, v73
	v_add_f32_e32 v80, v66, v74
	v_add_f32_e32 v81, v67, v75
	v_sub_f32_e32 v66, v66, v74
	v_sub_f32_e32 v67, v67, v75
	v_add_f32_e32 v74, v68, v76
	v_add_f32_e32 v75, v69, v77
	v_sub_f32_e32 v68, v68, v76
	v_sub_f32_e32 v69, v69, v77
	v_add_f32_e32 v76, v64, v80
	v_add_f32_e32 v77, v65, v81
	v_sub_f32_e32 v64, v64, v80
	v_sub_f32_e32 v65, v65, v81
	v_add_f32_e32 v80, v78, v74
	v_add_f32_e32 v81, v79, v75
	v_sub_f32_e32 v74, v78, v74
	v_sub_f32_e32 v75, v79, v75
	v_add_f32_e32 v78, v76, v80
	v_add_f32_e32 v79, v77, v81
	v_sub_f32_e32 v76, v76, v80
	v_sub_f32_e32 v77, v77, v81
	ds_write_b64 v98, v[78:79] offset:34816
	v_mul_f32_e32 v78, v30, v77
	v_mul_f32_e32 v79, v31, v77
	v_sub_f32_e32 v70, v82, v70
	v_sub_f32_e32 v71, v83, v71
	v_fma_f32 v80, v28, v76, -v78
	v_fma_f32 v81, v29, v76, v79

;     static __device__ __forceinline__ float sl(float g, float up) { return g * __builtin_amdgcn_rcpf(1.0f + __builtin_amdgcn_exp2f(-1.4426950408889634f * g)) * up; }
; __device__ __forceinline__ float2 cmul(float2 a, float2 b) { return make_float2(a.x * b.x - a.y * b.y, a.x * b.y + a.y * b.x); }
; template <int LR, bool INV>
; __device__ __forceinline__ void fft_stages(float2 (&x)[1 << LR], const int r, const int s) {
;     ...
;     for (int m = 0; m < R; ++m) {
;       if (m & hl) continue;
;       const int k = m & (hl - 1); const int j = k * (8 / hl);
;       const float2 wc = make_float2(c16(j), INV ? s16(j) : -s16(j));
;       const float2 tw = cmul(wb, wc);
;       if (!INV) { const float2 p = x[m], q = x[m + hl]; x[m] = make_float2(p.x + q.x, p.y + q.y); x[m + hl] = cmul(make_float2(p.x - q.x, p.y - q.y), tw); }
;       else { const float2 p = x[m], q = cmul(x[m + hl], tw); x[m] = make_float2(p.x + q.x, p.y + q.y); x[m + hl] = make_float2(p.x - q.x, p.y - q.y); }
;     }
; template <int LR, bool INV>
; __device__ __forceinline__ void fft_pass(float2* X, const int N, const int sl, const int tid) {
;     ...
;     for (int m = 0; m < R; ++m) X[PIDX(i0 + (m << sl))] = x[m];
	v_mul_f32_e32 v76, v32, v65
	v_mul_f32_e32 v77, v33, v65
	ds_write_b64 v98, v[80:81] offset:39168
	v_fma_f32 v78, v24, v64, -v76
	v_fma_f32 v79, v25, v64, v77

; __device__ __forceinline__ float2 cmul(float2 a, float2 b) { return make_float2(a.x * b.x - a.y * b.y, a.x * b.y + a.y * b.x); }
; template <int LR, bool INV>
; __device__ __forceinline__ void fft_stages(float2 (&x)[1 << LR], const int r, const int s) {
;     ...
;     for (int m = 0; m < R; ++m) {
;       if (m & hl) continue;
;       const int k = m & (hl - 1); const int j = k * (8 / hl);
;       const float2 wc = make_float2(c16(j), INV ? s16(j) : -s16(j));
;       const float2 tw = cmul(wb, wc);
;       if (!INV) { const float2 p = x[m], q = x[m + hl]; x[m] = make_float2(p.x + q.x, p.y + q.y); x[m + hl] = cmul(make_float2(p.x - q.x, p.y - q.y), tw); }
;       else { const float2 p = x[m], q = cmul(x[m + hl], tw); x[m] = make_float2(p.x + q.x, p.y + q.y); x[m + hl] = make_float2(p.x - q.x, p.y - q.y); }
;     }
	v_mul_f32_e32 v64, v34, v75
	v_mul_f32_e32 v65, v35, v75
	v_fma_f32 v76, v26, v74, -v64
	v_fma_f32 v77, v27, v74, v65

;     static __device__ __forceinline__ float sl(float g, float up) { return g * __builtin_amdgcn_rcpf(1.0f + __builtin_amdgcn_exp2f(-1.4426950408889634f * g)) * up; }
; __device__ __forceinline__ float2 cmul(float2 a, float2 b) { return make_float2(a.x * b.x - a.y * b.y, a.x * b.y + a.y * b.x); }
; template <int LR, bool INV>
; __device__ __forceinline__ void fft_stages(float2 (&x)[1 << LR], const int r, const int s) {
;     ...
;     for (int m = 0; m < R; ++m) {
;       if (m & hl) continue;
;       const int k = m & (hl - 1); const int j = k * (8 / hl);
;       const float2 wc = make_float2(c16(j), INV ? s16(j) : -s16(j));
;       const float2 tw = cmul(wb, wc);
;       if (!INV) { const float2 p = x[m], q = x[m + hl]; x[m] = make_float2(p.x + q.x, p.y + q.y); x[m + hl] = cmul(make_float2(p.x - q.x, p.y - q.y), tw); }
;       else { const float2 p = x[m], q = cmul(x[m + hl], tw); x[m] = make_float2(p.x + q.x, p.y + q.y); x[m + hl] = make_float2(p.x - q.x, p.y - q.y); }
;     }
; template <int LR, bool INV>
; __device__ __forceinline__ void fft_pass(float2* X, const int N, const int sl, const int tid) {
;     ...
;     for (int m = 0; m < R; ++m) X[PIDX(i0 + (m << sl))] = x[m];
	v_add_f32_e32 v64, v78, v76
	v_add_f32_e32 v65, v79, v77
	v_sub_f32_e32 v74, v78, v76
	v_sub_f32_e32 v75, v79, v77
	ds_write_b64 v98, v[64:65] offset:43520
	v_mul_f32_e32 v64, v30, v75
	v_mul_f32_e32 v65, v31, v75
	v_fma_f32 v76, v28, v74, -v64
	v_fma_f32 v77, v29, v74, v65

;     static __device__ __forceinline__ float sl(float g, float up) { return g * __builtin_amdgcn_rcpf(1.0f + __builtin_amdgcn_exp2f(-1.4426950408889634f * g)) * up; }
; __device__ __forceinline__ float2 cmul(float2 a, float2 b) { return make_float2(a.x * b.x - a.y * b.y, a.x * b.y + a.y * b.x); }
; template <int LR, bool INV>
; __device__ __forceinline__ void fft_stages(float2 (&x)[1 << LR], const int r, const int s) {
;     ...
;     for (int m = 0; m < R; ++m) {
;       if (m & hl) continue;
;       const int k = m & (hl - 1); const int j = k * (8 / hl);
;       const float2 wc = make_float2(c16(j), INV ? s16(j) : -s16(j));
;       const float2 tw = cmul(wb, wc);
;       if (!INV) { const float2 p = x[m], q = x[m + hl]; x[m] = make_float2(p.x + q.x, p.y + q.y); x[m + hl] = cmul(make_float2(p.x - q.x, p.y - q.y), tw); }
;       else { const float2 p = x[m], q = cmul(x[m + hl], tw); x[m] = make_float2(p.x + q.x, p.y + q.y); x[m + hl] = make_float2(p.x - q.x, p.y - q.y); }
;     }
; template <int LR, bool INV>
; __device__ __forceinline__ void fft_pass(float2* X, const int N, const int sl, const int tid) {
;     ...
;     for (int m = 0; m < R; ++m) X[PIDX(i0 + (m << sl))] = x[m];
	v_mul_f32_e32 v64, v36, v71
	v_mul_f32_e32 v65, v37, v71
	ds_write_b64 v98, v[76:77] offset:47872
	v_fma_f32 v74, v16, v70, -v64
	v_fma_f32 v75, v17, v70, v65

; __device__ __forceinline__ float2 cmul(float2 a, float2 b) { return make_float2(a.x * b.x - a.y * b.y, a.x * b.y + a.y * b.x); }
; template <int LR, bool INV>
; __device__ __forceinline__ void fft_stages(float2 (&x)[1 << LR], const int r, const int s) {
;     ...
;     for (int m = 0; m < R; ++m) {
;       if (m & hl) continue;
;       const int k = m & (hl - 1); const int j = k * (8 / hl);
;       const float2 wc = make_float2(c16(j), INV ? s16(j) : -s16(j));
;       const float2 tw = cmul(wb, wc);
;       if (!INV) { const float2 p = x[m], q = x[m + hl]; x[m] = make_float2(p.x + q.x, p.y + q.y); x[m + hl] = cmul(make_float2(p.x - q.x, p.y - q.y), tw); }
;       else { const float2 p = x[m], q = cmul(x[m + hl], tw); x[m] = make_float2(p.x + q.x, p.y + q.y); x[m + hl] = make_float2(p.x - q.x, p.y - q.y); }
;     }
	v_mul_f32_e32 v64, v38, v73
	v_mul_f32_e32 v65, v39, v73
	v_fma_f32 v70, v18, v72, -v64
	v_fma_f32 v71, v19, v72, v65

; __device__ __forceinline__ float2 cmul(float2 a, float2 b) { return make_float2(a.x * b.x - a.y * b.y, a.x * b.y + a.y * b.x); }
; template <int LR, bool INV>
; __device__ __forceinline__ void fft_stages(float2 (&x)[1 << LR], const int r, const int s) {
;     ...
;     for (int m = 0; m < R; ++m) {
;       if (m & hl) continue;
;       const int k = m & (hl - 1); const int j = k * (8 / hl);
;       const float2 wc = make_float2(c16(j), INV ? s16(j) : -s16(j));
;       const float2 tw = cmul(wb, wc);
;       if (!INV) { const float2 p = x[m], q = x[m + hl]; x[m] = make_float2(p.x + q.x, p.y + q.y); x[m + hl] = cmul(make_float2(p.x - q.x, p.y - q.y), tw); }
;       else { const float2 p = x[m], q = cmul(x[m + hl], tw); x[m] = make_float2(p.x + q.x, p.y + q.y); x[m + hl] = make_float2(p.x - q.x, p.y - q.y); }
;     }
	v_mul_f32_e32 v64, v40, v67
	v_mul_f32_e32 v65, v41, v67
	v_fma_f32 v72, v20, v66, -v64
	v_fma_f32 v73, v21, v66, v65

; __device__ __forceinline__ float2 cmul(float2 a, float2 b) { return make_float2(a.x * b.x - a.y * b.y, a.x * b.y + a.y * b.x); }
; template <int LR, bool INV>
; __device__ __forceinline__ void fft_stages(float2 (&x)[1 << LR], const int r, const int s) {
;     ...
;     for (int m = 0; m < R; ++m) {
;       if (m & hl) continue;
;       const int k = m & (hl - 1); const int j = k * (8 / hl);
;       const float2 wc = make_float2(c16(j), INV ? s16(j) : -s16(j));
;       const float2 tw = cmul(wb, wc);
;       if (!INV) { const float2 p = x[m], q = x[m + hl]; x[m] = make_float2(p.x + q.x, p.y + q.y); x[m + hl] = cmul(make_float2(p.x - q.x, p.y - q.y), tw); }
;       else { const float2 p = x[m], q = cmul(x[m + hl], tw); x[m] = make_float2(p.x + q.x, p.y + q.y); x[m + hl] = make_float2(p.x - q.x, p.y - q.y); }
;     }
	v_mul_f32_e32 v64, v42, v69
	v_mul_f32_e32 v65, v43, v69
	v_fma_f32 v66, v22, v68, -v64
	v_fma_f32 v67, v23, v68, v65
	v_sub_f32_e32 v68, v74, v72
	v_sub_f32_e32 v69, v75, v73

;     static __device__ __forceinline__ float sl(float g, float up) { return g * __builtin_amdgcn_rcpf(1.0f + __builtin_amdgcn_exp2f(-1.4426950408889634f * g)) * up; }
; __device__ __forceinline__ float2 cmul(float2 a, float2 b) { return make_float2(a.x * b.x - a.y * b.y, a.x * b.y + a.y * b.x); }
; template <int LR, bool INV>
; __device__ __forceinline__ void fft_stages(float2 (&x)[1 << LR], const int r, const int s) {
;     ...
;     for (int m = 0; m < R; ++m) {
;       if (m & hl) continue;
;       const int k = m & (hl - 1); const int j = k * (8 / hl);
;       const float2 wc = make_float2(c16(j), INV ? s16(j) : -s16(j));
;       const float2 tw = cmul(wb, wc);
;       if (!INV) { const float2 p = x[m], q = x[m + hl]; x[m] = make_float2(p.x + q.x, p.y + q.y); x[m + hl] = cmul(make_float2(p.x - q.x, p.y - q.y), tw); }
;       else { const float2 p = x[m], q = cmul(x[m + hl], tw); x[m] = make_float2(p.x + q.x, p.y + q.y); x[m + hl] = make_float2(p.x - q.x, p.y - q.y); }
;     }
; template <int LR, bool INV>
; __device__ __forceinline__ void fft_pass(float2* X, const int N, const int sl, const int tid) {
;     ...
;     for (int m = 0; m < R; ++m) X[PIDX(i0 + (m << sl))] = x[m];
	v_add_f32_e32 v64, v74, v72
	v_add_f32_e32 v65, v75, v73
	v_add_f32_e32 v72, v70, v66
	v_add_f32_e32 v73, v71, v67
	v_sub_f32_e32 v66, v70, v66
	v_sub_f32_e32 v67, v71, v67
	v_add_f32_e32 v70, v64, v72
	v_add_f32_e32 v71, v65, v73
	v_sub_f32_e32 v64, v64, v72
	v_sub_f32_e32 v65, v65, v73
	ds_write_b64 v98, v[70:71] offset:52224
	v_mul_f32_e32 v70, v30, v65
	v_mul_f32_e32 v71, v31, v65
	v_fma_f32 v72, v28, v64, -v70
	v_fma_f32 v73, v29, v64, v71

;     static __device__ __forceinline__ float sl(float g, float up) { return g * __builtin_amdgcn_rcpf(1.0f + __builtin_amdgcn_exp2f(-1.4426950408889634f * g)) * up; }
; __device__ __forceinline__ float2 cmul(float2 a, float2 b) { return make_float2(a.x * b.x - a.y * b.y, a.x * b.y + a.y * b.x); }
; template <int LR, bool INV>
; __device__ __forceinline__ void fft_stages(float2 (&x)[1 << LR], const int r, const int s) {
;     ...
;     for (int m = 0; m < R; ++m) {
;       if (m & hl) continue;
;       const int k = m & (hl - 1); const int j = k * (8 / hl);
;       const float2 wc = make_float2(c16(j), INV ? s16(j) : -s16(j));
;       const float2 tw = cmul(wb, wc);
;       if (!INV) { const float2 p = x[m], q = x[m + hl]; x[m] = make_float2(p.x + q.x, p.y + q.y); x[m + hl] = cmul(make_float2(p.x - q.x, p.y - q.y), tw); }
;       else { const float2 p = x[m], q = cmul(x[m + hl], tw); x[m] = make_float2(p.x + q.x, p.y + q.y); x[m + hl] = make_float2(p.x - q.x, p.y - q.y); }
;     }
; template <int LR, bool INV>
; __device__ __forceinline__ void fft_pass(float2* X, const int N, const int sl, const int tid) {
;     ...
;     for (int m = 0; m < R; ++m) X[PIDX(i0 + (m << sl))] = x[m];
	v_mul_f32_e32 v64, v32, v69
	v_mul_f32_e32 v65, v33, v69
	ds_write_b64 v98, v[72:73] offset:56576
	v_fma_f32 v70, v24, v68, -v64
	v_fma_f32 v71, v25, v68, v65

; __device__ __forceinline__ float2 cmul(float2 a, float2 b) { return make_float2(a.x * b.x - a.y * b.y, a.x * b.y + a.y * b.x); }
; template <int LR, bool INV>
; __device__ __forceinline__ void fft_stages(float2 (&x)[1 << LR], const int r, const int s) {
;     ...
;     for (int m = 0; m < R; ++m) {
;       if (m & hl) continue;
;       const int k = m & (hl - 1); const int j = k * (8 / hl);
;       const float2 wc = make_float2(c16(j), INV ? s16(j) : -s16(j));
;       const float2 tw = cmul(wb, wc);
;       if (!INV) { const float2 p = x[m], q = x[m + hl]; x[m] = make_float2(p.x + q.x, p.y + q.y); x[m + hl] = cmul(make_float2(p.x - q.x, p.y - q.y), tw); }
;       else { const float2 p = x[m], q = cmul(x[m + hl], tw); x[m] = make_float2(p.x + q.x, p.y + q.y); x[m + hl] = make_float2(p.x - q.x, p.y - q.y); }
;     }
	v_mul_f32_e32 v64, v34, v67
	v_mul_f32_e32 v65, v35, v67
	v_fma_f32 v68, v26, v66, -v64
	v_fma_f32 v69, v27, v66, v65

;     static __device__ __forceinline__ float sl(float g, float up) { return g * __builtin_amdgcn_rcpf(1.0f + __builtin_amdgcn_exp2f(-1.4426950408889634f * g)) * up; }
; __device__ __forceinline__ float2 cmul(float2 a, float2 b) { return make_float2(a.x * b.x - a.y * b.y, a.x * b.y + a.y * b.x); }
; #define tid ltid()
; template <int LR, bool INV>
; __device__ __forceinline__ void fft_stages(float2 (&x)[1 << LR], const int r, const int s) {
;     ...
;     for (int m = 0; m < R; ++m) {
;       if (m & hl) continue;
;       const int k = m & (hl - 1); const int j = k * (8 / hl);
;       const float2 wc = make_float2(c16(j), INV ? s16(j) : -s16(j));
;       const float2 tw = cmul(wb, wc);
;       if (!INV) { const float2 p = x[m], q = x[m + hl]; x[m] = make_float2(p.x + q.x, p.y + q.y); x[m + hl] = cmul(make_float2(p.x - q.x, p.y - q.y), tw); }
;       else { const float2 p = x[m], q = cmul(x[m + hl], tw); x[m] = make_float2(p.x + q.x, p.y + q.y); x[m + hl] = make_float2(p.x - q.x, p.y - q.y); }
;     }
; template <int LR, bool INV>
; __device__ __forceinline__ void fft_pass(float2* X, const int N, const int sl, const int tid) {
;     ...
;   for (int g = tid; g < (N >> LR); g += NTHR) {
;     const int r = g & (s - 1);
;     const int i0 = ((g >> sl) << (sl + LR)) + r;
;     float2 x[R];
; #pragma unroll
;     for (int m = 0; m < R; ++m) x[m] = X[PIDX(i0 + (m << sl))];
;     fft_stages<LR, INV>(x, r, s);
; #pragma unroll
;     for (int m = 0; m < R; ++m) X[PIDX(i0 + (m << sl))] = x[m];
	v_add_f32_e32 v64, v70, v68
	v_add_f32_e32 v65, v71, v69
	v_sub_f32_e32 v66, v70, v68
	v_sub_f32_e32 v67, v71, v69
	ds_write_b64 v98, v[64:65] offset:60928
	v_mul_f32_e32 v64, v30, v67
	v_mul_f32_e32 v65, v31, v67
	v_fma_f32 v68, v28, v66, -v64
	v_fma_f32 v65, v29, v66, v65
	v_mov_b32_e32 v69, v65
	ds_write_b64 v98, v[68:69] offset:65280
	s_andn2_b64 exec, exec, s[14:15]
	s_cbranch_execnz .LBB0_656

;     static __device__ __forceinline__ float sl(float g, float up) { return g * __builtin_amdgcn_rcpf(1.0f + __builtin_amdgcn_exp2f(-1.4426950408889634f * g)) * up; }
; #define tid ltid()
; template <int LR, bool INV>
; __device__ __forceinline__ void fft_pass(float2* X, const int N, const int sl, const int tid) {
;     ...
;   for (int g = tid; g < (N >> LR); g += NTHR) {
;     const int r = g & (s - 1);
;     const int i0 = ((g >> sl) << (sl + LR)) + r;
.LBB0_660:
	v_and_or_b32 v32, v30, s53, v29
	v_ashrrev_i32_e32 v33, 4, v32
	v_lshlrev_b32_e32 v33, 3, v33
	v_lshlrev_b32_e32 v34, 3, v32
	v_add3_u32 v50, s52, v33, v34


;     static __device__ __forceinline__ float sl(float g, float up) { return g * __builtin_amdgcn_rcpf(1.0f + __builtin_amdgcn_exp2f(-1.4426950408889634f * g)) * up; }
; __device__ __forceinline__ float2 cmul(float2 a, float2 b) { return make_float2(a.x * b.x - a.y * b.y, a.x * b.y + a.y * b.x); }
; #define tid ltid()
; template <int LR, bool INV>
; __device__ __forceinline__ void fft_stages(float2 (&x)[1 << LR], const int r, const int s) {
;     ...
;     for (int m = 0; m < R; ++m) {
;       if (m & hl) continue;
;       const int k = m & (hl - 1); const int j = k * (8 / hl);
;       const float2 wc = make_float2(c16(j), INV ? s16(j) : -s16(j));
;       const float2 tw = cmul(wb, wc);
;       if (!INV) { const float2 p = x[m], q = x[m + hl]; x[m] = make_float2(p.x + q.x, p.y + q.y); x[m + hl] = cmul(make_float2(p.x - q.x, p.y - q.y), tw); }
;       else { const float2 p = x[m], q = cmul(x[m + hl], tw); x[m] = make_float2(p.x + q.x, p.y + q.y); x[m + hl] = make_float2(p.x - q.x, p.y - q.y); }
;     }
; template <int LR, bool INV>
; __device__ __forceinline__ void fft_pass(float2* X, const int N, const int sl, const int tid) {
;     ...
;   for (int g = tid; g < (N >> LR); g += NTHR) {
;     const int r = g & (s - 1);
;     const int i0 = ((g >> sl) << (sl + LR)) + r;
;     float2 x[R];
; #pragma unroll
;     for (int m = 0; m < R; ++m) x[m] = X[PIDX(i0 + (m << sl))];
;     fft_stages<LR, INV>(x, r, s);
; #pragma unroll
;     for (int m = 0; m < R; ++m) X[PIDX(i0 + (m << sl))] = x[m];
	ds_read_b64 v[32:33], v50
	ds_read_b64 v[34:35], v50 offset:544
	ds_read_b64 v[36:37], v50 offset:1088
	ds_read_b64 v[38:39], v50 offset:1632
	ds_read_b64 v[40:41], v50 offset:2176
	ds_read_b64 v[42:43], v50 offset:2720
	ds_read_b64 v[44:45], v50 offset:3264
	ds_read_b64 v[46:47], v50 offset:3808
	v_add_u32_e32 v31, 0x200, v31
	s_waitcnt lgkmcnt(3)
	v_add_f32_e32 v48, v32, v40
	v_add_f32_e32 v49, v33, v41
	v_sub_f32_e32 v32, v32, v40
	v_sub_f32_e32 v33, v33, v41
	s_waitcnt lgkmcnt(2)
	v_add_f32_e32 v40, v34, v42
	v_add_f32_e32 v41, v35, v43
	v_sub_f32_e32 v34, v34, v42
	v_sub_f32_e32 v35, v35, v43
	s_waitcnt lgkmcnt(1)
	v_add_f32_e32 v42, v36, v44
	v_add_f32_e32 v43, v37, v45
	v_sub_f32_e32 v36, v36, v44
	v_sub_f32_e32 v37, v37, v45
	s_waitcnt lgkmcnt(0)
	v_add_f32_e32 v44, v38, v46
	v_add_f32_e32 v45, v39, v47
	v_sub_f32_e32 v38, v38, v46
	v_sub_f32_e32 v39, v39, v47
	v_add_f32_e32 v46, v48, v42
	v_add_f32_e32 v47, v49, v43
	v_sub_f32_e32 v42, v48, v42
	v_sub_f32_e32 v43, v49, v43
	v_add_f32_e32 v48, v40, v44
	v_add_f32_e32 v49, v41, v45
	v_sub_f32_e32 v40, v40, v44
	v_sub_f32_e32 v41, v41, v45
	v_add_f32_e32 v44, v46, v48
	v_add_f32_e32 v45, v47, v49
	v_sub_f32_e32 v46, v46, v48
	v_sub_f32_e32 v47, v47, v49
	ds_write_b64 v50, v[44:45]
	v_mul_f32_e32 v44, v14, v47
	v_mul_f32_e32 v45, v15, v47
	v_cmp_le_i32_e64 s[40:41], s19, v31
	v_fma_f32 v48, v12, v46, -v44
	v_fma_f32 v49, v13, v46, v45
	v_add_u32_e32 v30, 0x1000, v30

;     static __device__ __forceinline__ float sl(float g, float up) { return g * __builtin_amdgcn_rcpf(1.0f + __builtin_amdgcn_exp2f(-1.4426950408889634f * g)) * up; }
; __device__ __forceinline__ float2 cmul(float2 a, float2 b) { return make_float2(a.x * b.x - a.y * b.y, a.x * b.y + a.y * b.x); }
; template <int LR, bool INV>
; __device__ __forceinline__ void fft_stages(float2 (&x)[1 << LR], const int r, const int s) {
;     ...
;     for (int m = 0; m < R; ++m) {
;       if (m & hl) continue;
;       const int k = m & (hl - 1); const int j = k * (8 / hl);
;       const float2 wc = make_float2(c16(j), INV ? s16(j) : -s16(j));
;       const float2 tw = cmul(wb, wc);
;       if (!INV) { const float2 p = x[m], q = x[m + hl]; x[m] = make_float2(p.x + q.x, p.y + q.y); x[m + hl] = cmul(make_float2(p.x - q.x, p.y - q.y), tw); }
;       else { const float2 p = x[m], q = cmul(x[m + hl], tw); x[m] = make_float2(p.x + q.x, p.y + q.y); x[m + hl] = make_float2(p.x - q.x, p.y - q.y); }
;     }
; template <int LR, bool INV>
; __device__ __forceinline__ void fft_pass(float2* X, const int N, const int sl, const int tid) {
;     ...
;     for (int m = 0; m < R; ++m) X[PIDX(i0 + (m << sl))] = x[m];
	v_mul_f32_e32 v44, v16, v43
	v_mul_f32_e32 v45, v17, v43
	ds_write_b64 v50, v[48:49] offset:544
	v_fma_f32 v46, v8, v42, -v44
	v_fma_f32 v47, v9, v42, v45
	s_or_b64 s[14:15], s[40:41], s[14:15]

; __device__ __forceinline__ float2 cmul(float2 a, float2 b) { return make_float2(a.x * b.x - a.y * b.y, a.x * b.y + a.y * b.x); }
; template <int LR, bool INV>
; __device__ __forceinline__ void fft_stages(float2 (&x)[1 << LR], const int r, const int s) {
;     ...
;     for (int m = 0; m < R; ++m) {
;       if (m & hl) continue;
;       const int k = m & (hl - 1); const int j = k * (8 / hl);
;       const float2 wc = make_float2(c16(j), INV ? s16(j) : -s16(j));
;       const float2 tw = cmul(wb, wc);
;       if (!INV) { const float2 p = x[m], q = x[m + hl]; x[m] = make_float2(p.x + q.x, p.y + q.y); x[m + hl] = cmul(make_float2(p.x - q.x, p.y - q.y), tw); }
;       else { const float2 p = x[m], q = cmul(x[m + hl], tw); x[m] = make_float2(p.x + q.x, p.y + q.y); x[m + hl] = make_float2(p.x - q.x, p.y - q.y); }
;     }
	v_mul_f32_e32 v42, v18, v41
	v_mul_f32_e32 v43, v19, v41
	v_fma_f32 v44, v10, v40, -v42
	v_fma_f32 v45, v11, v40, v43

;     static __device__ __forceinline__ float sl(float g, float up) { return g * __builtin_amdgcn_rcpf(1.0f + __builtin_amdgcn_exp2f(-1.4426950408889634f * g)) * up; }
; __device__ __forceinline__ float2 cmul(float2 a, float2 b) { return make_float2(a.x * b.x - a.y * b.y, a.x * b.y + a.y * b.x); }
; template <int LR, bool INV>
; __device__ __forceinline__ void fft_stages(float2 (&x)[1 << LR], const int r, const int s) {
;     ...
;     for (int m = 0; m < R; ++m) {
;       if (m & hl) continue;
;       const int k = m & (hl - 1); const int j = k * (8 / hl);
;       const float2 wc = make_float2(c16(j), INV ? s16(j) : -s16(j));
;       const float2 tw = cmul(wb, wc);
;       if (!INV) { const float2 p = x[m], q = x[m + hl]; x[m] = make_float2(p.x + q.x, p.y + q.y); x[m + hl] = cmul(make_float2(p.x - q.x, p.y - q.y), tw); }
;       else { const float2 p = x[m], q = cmul(x[m + hl], tw); x[m] = make_float2(p.x + q.x, p.y + q.y); x[m + hl] = make_float2(p.x - q.x, p.y - q.y); }
;     }
; template <int LR, bool INV>
; __device__ __forceinline__ void fft_pass(float2* X, const int N, const int sl, const int tid) {
;     ...
;     for (int m = 0; m < R; ++m) X[PIDX(i0 + (m << sl))] = x[m];
	v_add_f32_e32 v40, v46, v44
	v_add_f32_e32 v41, v47, v45
	v_sub_f32_e32 v42, v46, v44
	v_sub_f32_e32 v43, v47, v45
	ds_write_b64 v50, v[40:41] offset:1088
	v_mul_f32_e32 v40, v14, v43
	v_mul_f32_e32 v41, v15, v43
	v_fma_f32 v44, v12, v42, -v40
	v_fma_f32 v45, v13, v42, v41

;     static __device__ __forceinline__ float sl(float g, float up) { return g * __builtin_amdgcn_rcpf(1.0f + __builtin_amdgcn_exp2f(-1.4426950408889634f * g)) * up; }
; __device__ __forceinline__ float2 cmul(float2 a, float2 b) { return make_float2(a.x * b.x - a.y * b.y, a.x * b.y + a.y * b.x); }
; template <int LR, bool INV>
; __device__ __forceinline__ void fft_stages(float2 (&x)[1 << LR], const int r, const int s) {
;     ...
;     for (int m = 0; m < R; ++m) {
;       if (m & hl) continue;
;       const int k = m & (hl - 1); const int j = k * (8 / hl);
;       const float2 wc = make_float2(c16(j), INV ? s16(j) : -s16(j));
;       const float2 tw = cmul(wb, wc);
;       if (!INV) { const float2 p = x[m], q = x[m + hl]; x[m] = make_float2(p.x + q.x, p.y + q.y); x[m + hl] = cmul(make_float2(p.x - q.x, p.y - q.y), tw); }
;       else { const float2 p = x[m], q = cmul(x[m + hl], tw); x[m] = make_float2(p.x + q.x, p.y + q.y); x[m + hl] = make_float2(p.x - q.x, p.y - q.y); }
;     }
; template <int LR, bool INV>
; __device__ __forceinline__ void fft_pass(float2* X, const int N, const int sl, const int tid) {
;     ...
;     for (int m = 0; m < R; ++m) X[PIDX(i0 + (m << sl))] = x[m];
	v_mul_f32_e32 v40, v20, v33
	v_mul_f32_e32 v41, v21, v33
	ds_write_b64 v50, v[44:45] offset:1632
	v_fma_f32 v42, v0, v32, -v40
	v_fma_f32 v43, v1, v32, v41

; __device__ __forceinline__ float2 cmul(float2 a, float2 b) { return make_float2(a.x * b.x - a.y * b.y, a.x * b.y + a.y * b.x); }
; template <int LR, bool INV>
; __device__ __forceinline__ void fft_stages(float2 (&x)[1 << LR], const int r, const int s) {
;     ...
;     for (int m = 0; m < R; ++m) {
;       if (m & hl) continue;
;       const int k = m & (hl - 1); const int j = k * (8 / hl);
;       const float2 wc = make_float2(c16(j), INV ? s16(j) : -s16(j));
;       const float2 tw = cmul(wb, wc);
;       if (!INV) { const float2 p = x[m], q = x[m + hl]; x[m] = make_float2(p.x + q.x, p.y + q.y); x[m + hl] = cmul(make_float2(p.x - q.x, p.y - q.y), tw); }
;       else { const float2 p = x[m], q = cmul(x[m + hl], tw); x[m] = make_float2(p.x + q.x, p.y + q.y); x[m + hl] = make_float2(p.x - q.x, p.y - q.y); }
;     }
	v_mul_f32_e32 v32, v22, v35
	v_mul_f32_e32 v33, v23, v35
	v_fma_f32 v40, v2, v34, -v32
	v_fma_f32 v41, v3, v34, v33

; __device__ __forceinline__ float2 cmul(float2 a, float2 b) { return make_float2(a.x * b.x - a.y * b.y, a.x * b.y + a.y * b.x); }
; template <int LR, bool INV>
; __device__ __forceinline__ void fft_stages(float2 (&x)[1 << LR], const int r, const int s) {
;     ...
;     for (int m = 0; m < R; ++m) {
;       if (m & hl) continue;
;       const int k = m & (hl - 1); const int j = k * (8 / hl);
;       const float2 wc = make_float2(c16(j), INV ? s16(j) : -s16(j));
;       const float2 tw = cmul(wb, wc);
;       if (!INV) { const float2 p = x[m], q = x[m + hl]; x[m] = make_float2(p.x + q.x, p.y + q.y); x[m + hl] = cmul(make_float2(p.x - q.x, p.y - q.y), tw); }
;       else { const float2 p = x[m], q = cmul(x[m + hl], tw); x[m] = make_float2(p.x + q.x, p.y + q.y); x[m + hl] = make_float2(p.x - q.x, p.y - q.y); }
;     }
	v_mul_f32_e32 v32, v24, v37
	v_mul_f32_e32 v33, v25, v37
	v_fma_f32 v34, v4, v36, -v32
	v_fma_f32 v35, v5, v36, v33

; __device__ __forceinline__ float2 cmul(float2 a, float2 b) { return make_float2(a.x * b.x - a.y * b.y, a.x * b.y + a.y * b.x); }
; template <int LR, bool INV>
; __device__ __forceinline__ void fft_stages(float2 (&x)[1 << LR], const int r, const int s) {
;     ...
;     for (int m = 0; m < R; ++m) {
;       if (m & hl) continue;
;       const int k = m & (hl - 1); const int j = k * (8 / hl);
;       const float2 wc = make_float2(c16(j), INV ? s16(j) : -s16(j));
;       const float2 tw = cmul(wb, wc);
;       if (!INV) { const float2 p = x[m], q = x[m + hl]; x[m] = make_float2(p.x + q.x, p.y + q.y); x[m + hl] = cmul(make_float2(p.x - q.x, p.y - q.y), tw); }
;       else { const float2 p = x[m], q = cmul(x[m + hl], tw); x[m] = make_float2(p.x + q.x, p.y + q.y); x[m + hl] = make_float2(p.x - q.x, p.y - q.y); }
;     }
	v_mul_f32_e32 v32, v26, v39
	v_mul_f32_e32 v33, v27, v39
	v_fma_f32 v36, v6, v38, -v32
	v_fma_f32 v37, v7, v38, v33

;     static __device__ __forceinline__ float sl(float g, float up) { return g * __builtin_amdgcn_rcpf(1.0f + __builtin_amdgcn_exp2f(-1.4426950408889634f * g)) * up; }
; __device__ __forceinline__ float2 cmul(float2 a, float2 b) { return make_float2(a.x * b.x - a.y * b.y, a.x * b.y + a.y * b.x); }
; template <int LR, bool INV>
; __device__ __forceinline__ void fft_stages(float2 (&x)[1 << LR], const int r, const int s) {
;     ...
;     for (int m = 0; m < R; ++m) {
;       if (m & hl) continue;
;       const int k = m & (hl - 1); const int j = k * (8 / hl);
;       const float2 wc = make_float2(c16(j), INV ? s16(j) : -s16(j));
;       const float2 tw = cmul(wb, wc);
;       if (!INV) { const float2 p = x[m], q = x[m + hl]; x[m] = make_float2(p.x + q.x, p.y + q.y); x[m + hl] = cmul(make_float2(p.x - q.x, p.y - q.y), tw); }
;       else { const float2 p = x[m], q = cmul(x[m + hl], tw); x[m] = make_float2(p.x + q.x, p.y + q.y); x[m + hl] = make_float2(p.x - q.x, p.y - q.y); }
;     }
; template <int LR, bool INV>
; __device__ __forceinline__ void fft_pass(float2* X, const int N, const int sl, const int tid) {
;     ...
;     for (int m = 0; m < R; ++m) X[PIDX(i0 + (m << sl))] = x[m];
	v_add_f32_e32 v32, v42, v34
	v_add_f32_e32 v33, v43, v35
	v_add_f32_e32 v38, v40, v36
	v_add_f32_e32 v39, v41, v37
	v_sub_f32_e32 v36, v40, v36
	v_sub_f32_e32 v37, v41, v37
	v_add_f32_e32 v40, v32, v38
	v_add_f32_e32 v41, v33, v39
	v_sub_f32_e32 v32, v32, v38
	v_sub_f32_e32 v33, v33, v39
	v_sub_f32_e32 v34, v42, v34
	v_sub_f32_e32 v35, v43, v35
	v_mul_f32_e32 v38, v14, v33
	v_mul_f32_e32 v39, v15, v33
	ds_write_b64 v50, v[40:41] offset:2176
	v_fma_f32 v40, v12, v32, -v38
	v_fma_f32 v41, v13, v32, v39

;     static __device__ __forceinline__ float sl(float g, float up) { return g * __builtin_amdgcn_rcpf(1.0f + __builtin_amdgcn_exp2f(-1.4426950408889634f * g)) * up; }
; __device__ __forceinline__ float2 cmul(float2 a, float2 b) { return make_float2(a.x * b.x - a.y * b.y, a.x * b.y + a.y * b.x); }
; template <int LR, bool INV>
; __device__ __forceinline__ void fft_stages(float2 (&x)[1 << LR], const int r, const int s) {
;     ...
;     for (int m = 0; m < R; ++m) {
;       if (m & hl) continue;
;       const int k = m & (hl - 1); const int j = k * (8 / hl);
;       const float2 wc = make_float2(c16(j), INV ? s16(j) : -s16(j));
;       const float2 tw = cmul(wb, wc);
;       if (!INV) { const float2 p = x[m], q = x[m + hl]; x[m] = make_float2(p.x + q.x, p.y + q.y); x[m + hl] = cmul(make_float2(p.x - q.x, p.y - q.y), tw); }
;       else { const float2 p = x[m], q = cmul(x[m + hl], tw); x[m] = make_float2(p.x + q.x, p.y + q.y); x[m + hl] = make_float2(p.x - q.x, p.y - q.y); }
;     }
; template <int LR, bool INV>
; __device__ __forceinline__ void fft_pass(float2* X, const int N, const int sl, const int tid) {
;     ...
;     for (int m = 0; m < R; ++m) X[PIDX(i0 + (m << sl))] = x[m];
	v_mul_f32_e32 v32, v16, v35
	v_mul_f32_e32 v33, v17, v35
	ds_write_b64 v50, v[40:41] offset:2720
	v_fma_f32 v38, v8, v34, -v32
	v_fma_f32 v39, v9, v34, v33

; __device__ __forceinline__ float2 cmul(float2 a, float2 b) { return make_float2(a.x * b.x - a.y * b.y, a.x * b.y + a.y * b.x); }
; template <int LR, bool INV>
; __device__ __forceinline__ void fft_stages(float2 (&x)[1 << LR], const int r, const int s) {
;     ...
;     for (int m = 0; m < R; ++m) {
;       if (m & hl) continue;
;       const int k = m & (hl - 1); const int j = k * (8 / hl);
;       const float2 wc = make_float2(c16(j), INV ? s16(j) : -s16(j));
;       const float2 tw = cmul(wb, wc);
;       if (!INV) { const float2 p = x[m], q = x[m + hl]; x[m] = make_float2(p.x + q.x, p.y + q.y); x[m + hl] = cmul(make_float2(p.x - q.x, p.y - q.y), tw); }
;       else { const float2 p = x[m], q = cmul(x[m + hl], tw); x[m] = make_float2(p.x + q.x, p.y + q.y); x[m + hl] = make_float2(p.x - q.x, p.y - q.y); }
;     }
	v_mul_f32_e32 v32, v18, v37
	v_mul_f32_e32 v33, v19, v37
	v_fma_f32 v34, v10, v36, -v32
	v_fma_f32 v35, v11, v36, v33

;     static __device__ __forceinline__ float sl(float g, float up) { return g * __builtin_amdgcn_rcpf(1.0f + __builtin_amdgcn_exp2f(-1.4426950408889634f * g)) * up; }
; __device__ __forceinline__ float2 cmul(float2 a, float2 b) { return make_float2(a.x * b.x - a.y * b.y, a.x * b.y + a.y * b.x); }
; template <int LR, bool INV>
; __device__ __forceinline__ void fft_stages(float2 (&x)[1 << LR], const int r, const int s) {
;     ...
;     for (int m = 0; m < R; ++m) {
;       if (m & hl) continue;
;       const int k = m & (hl - 1); const int j = k * (8 / hl);
;       const float2 wc = make_float2(c16(j), INV ? s16(j) : -s16(j));
;       const float2 tw = cmul(wb, wc);
;       if (!INV) { const float2 p = x[m], q = x[m + hl]; x[m] = make_float2(p.x + q.x, p.y + q.y); x[m + hl] = cmul(make_float2(p.x - q.x, p.y - q.y), tw); }
;       else { const float2 p = x[m], q = cmul(x[m + hl], tw); x[m] = make_float2(p.x + q.x, p.y + q.y); x[m + hl] = make_float2(p.x - q.x, p.y - q.y); }
;     }
; template <int LR, bool INV>
; __device__ __forceinline__ void fft_pass(float2* X, const int N, const int sl, const int tid) {
;     ...
;     for (int m = 0; m < R; ++m) X[PIDX(i0 + (m << sl))] = x[m];
;   }
	v_add_f32_e32 v32, v38, v34
	v_add_f32_e32 v33, v39, v35
	v_sub_f32_e32 v34, v38, v34
	v_sub_f32_e32 v35, v39, v35
	ds_write_b64 v50, v[32:33] offset:3264
	v_mul_f32_e32 v32, v14, v35
	v_mul_f32_e32 v33, v15, v35
	v_fma_f32 v36, v12, v34, -v32
	v_fma_f32 v32, v12, v34, v32
	v_fma_f32 v33, v13, v34, v33
	v_mov_b32_e32 v37, v33
	ds_write_b64 v50, v[36:37] offset:3808
	s_andn2_b64 exec, exec, s[14:15]
	s_cbranch_execnz .LBB0_660

;     static __device__ __forceinline__ float sl(float g, float up) { return g * __builtin_amdgcn_rcpf(1.0f + __builtin_amdgcn_exp2f(-1.4426950408889634f * g)) * up; }
; #define tid ltid()
; template <int LR, bool INV>
; __device__ __forceinline__ void fft_pass(float2* X, const int N, const int sl, const int tid) {
;     ...
;   for (int g = tid; g < (N >> LR); g += NTHR) {
;     const int r = g & (s - 1);
;     const int i0 = ((g >> sl) << (sl + LR)) + r;
.LBB0_663:
	v_and_b32_e32 v32, 0xffffffc0, v30
	v_or_b32_e32 v33, v32, v29
	v_ashrrev_i32_e32 v34, 1, v32
	v_lshlrev_b32_e32 v33, 3, v33
	v_add3_u32 v52, s52, v34, v33
	v_or_b32_e32 v34, 16, v32
	v_ashrrev_i32_e32 v34, 4, v34
	v_lshlrev_b32_e32 v34, 3, v34
	v_add3_u32 v53, s52, v34, v33


;     static __device__ __forceinline__ float sl(float g, float up) { return g * __builtin_amdgcn_rcpf(1.0f + __builtin_amdgcn_exp2f(-1.4426950408889634f * g)) * up; }
; __device__ __forceinline__ float2 cmul(float2 a, float2 b) { return make_float2(a.x * b.x - a.y * b.y, a.x * b.y + a.y * b.x); }
; #define tid ltid()
; template <int LR, bool INV>
; __device__ __forceinline__ void fft_stages(float2 (&x)[1 << LR], const int r, const int s) {
;     ...
;     for (int m = 0; m < R; ++m) {
;       if (m & hl) continue;
;       const int k = m & (hl - 1); const int j = k * (8 / hl);
;       const float2 wc = make_float2(c16(j), INV ? s16(j) : -s16(j));
;       const float2 tw = cmul(wb, wc);
;       if (!INV) { const float2 p = x[m], q = x[m + hl]; x[m] = make_float2(p.x + q.x, p.y + q.y); x[m + hl] = cmul(make_float2(p.x - q.x, p.y - q.y), tw); }
;       else { const float2 p = x[m], q = cmul(x[m + hl], tw); x[m] = make_float2(p.x + q.x, p.y + q.y); x[m + hl] = make_float2(p.x - q.x, p.y - q.y); }
;     }
; template <int LR, bool INV>
; __device__ __forceinline__ void fft_pass(float2* X, const int N, const int sl, const int tid) {
;     ...
;   for (int g = tid; g < (N >> LR); g += NTHR) {
;     const int r = g & (s - 1);
;     const int i0 = ((g >> sl) << (sl + LR)) + r;
;     float2 x[R];
; #pragma unroll
;     for (int m = 0; m < R; ++m) x[m] = X[PIDX(i0 + (m << sl))];
;     fft_stages<LR, INV>(x, r, s);
; #pragma unroll
;     for (int m = 0; m < R; ++m) X[PIDX(i0 + (m << sl))] = x[m];
	ds_read2_b64 v[32:35], v52 offset1:8
	ds_read2_b64 v[36:39], v53 offset0:16 offset1:24
	ds_read2_b64 v[40:43], v53 offset0:33 offset1:41
	ds_read2_b64 v[44:47], v53 offset0:50 offset1:58
	v_add_u32_e32 v31, 0x200, v31
	v_cmp_le_i32_e64 s[40:41], s19, v31
	v_add_u32_e32 v30, 0x1000, v30
	s_waitcnt lgkmcnt(1)
	v_add_f32_e32 v48, v32, v40
	v_add_f32_e32 v49, v33, v41
	v_sub_f32_e32 v32, v32, v40
	v_sub_f32_e32 v33, v33, v41
	v_add_f32_e32 v40, v34, v42
	v_add_f32_e32 v41, v35, v43
	v_sub_f32_e32 v34, v34, v42
	v_sub_f32_e32 v35, v35, v43
	s_waitcnt lgkmcnt(0)
	v_add_f32_e32 v42, v36, v44
	v_add_f32_e32 v43, v37, v45
	v_sub_f32_e32 v36, v36, v44
	v_sub_f32_e32 v37, v37, v45
	v_add_f32_e32 v44, v38, v46
	v_add_f32_e32 v45, v39, v47
	v_sub_f32_e32 v38, v38, v46
	v_sub_f32_e32 v39, v39, v47
	v_add_f32_e32 v46, v48, v42
	v_add_f32_e32 v47, v49, v43
	v_sub_f32_e32 v42, v48, v42
	v_sub_f32_e32 v43, v49, v43
	v_add_f32_e32 v48, v40, v44
	v_add_f32_e32 v49, v41, v45
	v_sub_f32_e32 v40, v40, v44
	v_sub_f32_e32 v41, v41, v45
	v_add_f32_e32 v44, v46, v48
	v_add_f32_e32 v45, v47, v49
	v_sub_f32_e32 v46, v46, v48
	v_sub_f32_e32 v47, v47, v49
	s_or_b64 s[14:15], s[40:41], s[14:15]
	v_mul_f32_e32 v48, v14, v47
	v_mul_f32_e32 v49, v15, v47
	v_fma_f32 v50, v12, v46, -v48
	v_fma_f32 v51, v13, v46, v49

;     static __device__ __forceinline__ float sl(float g, float up) { return g * __builtin_amdgcn_rcpf(1.0f + __builtin_amdgcn_exp2f(-1.4426950408889634f * g)) * up; }
; __device__ __forceinline__ float2 cmul(float2 a, float2 b) { return make_float2(a.x * b.x - a.y * b.y, a.x * b.y + a.y * b.x); }
; template <int LR, bool INV>
; __device__ __forceinline__ void fft_stages(float2 (&x)[1 << LR], const int r, const int s) {
;     ...
;     for (int m = 0; m < R; ++m) {
;       if (m & hl) continue;
;       const int k = m & (hl - 1); const int j = k * (8 / hl);
;       const float2 wc = make_float2(c16(j), INV ? s16(j) : -s16(j));
;       const float2 tw = cmul(wb, wc);
;       if (!INV) { const float2 p = x[m], q = x[m + hl]; x[m] = make_float2(p.x + q.x, p.y + q.y); x[m + hl] = cmul(make_float2(p.x - q.x, p.y - q.y), tw); }
;       else { const float2 p = x[m], q = cmul(x[m + hl], tw); x[m] = make_float2(p.x + q.x, p.y + q.y); x[m + hl] = make_float2(p.x - q.x, p.y - q.y); }
;     }
; template <int LR, bool INV>
; __device__ __forceinline__ void fft_pass(float2* X, const int N, const int sl, const int tid) {
;     ...
;     for (int m = 0; m < R; ++m) X[PIDX(i0 + (m << sl))] = x[m];
	ds_write2_b64 v52, v[44:45], v[50:51] offset1:8
	v_mul_f32_e32 v44, v16, v43
	v_mul_f32_e32 v45, v17, v43
	v_fma_f32 v46, v8, v42, -v44
	v_fma_f32 v47, v9, v42, v45

; __device__ __forceinline__ float2 cmul(float2 a, float2 b) { return make_float2(a.x * b.x - a.y * b.y, a.x * b.y + a.y * b.x); }
; template <int LR, bool INV>
; __device__ __forceinline__ void fft_stages(float2 (&x)[1 << LR], const int r, const int s) {
;     ...
;     for (int m = 0; m < R; ++m) {
;       if (m & hl) continue;
;       const int k = m & (hl - 1); const int j = k * (8 / hl);
;       const float2 wc = make_float2(c16(j), INV ? s16(j) : -s16(j));
;       const float2 tw = cmul(wb, wc);
;       if (!INV) { const float2 p = x[m], q = x[m + hl]; x[m] = make_float2(p.x + q.x, p.y + q.y); x[m + hl] = cmul(make_float2(p.x - q.x, p.y - q.y), tw); }
;       else { const float2 p = x[m], q = cmul(x[m + hl], tw); x[m] = make_float2(p.x + q.x, p.y + q.y); x[m + hl] = make_float2(p.x - q.x, p.y - q.y); }
;     }
	v_mul_f32_e32 v42, v18, v41
	v_mul_f32_e32 v43, v19, v41
	v_fma_f32 v44, v10, v40, -v42
	v_fma_f32 v45, v11, v40, v43

; __device__ __forceinline__ float2 cmul(float2 a, float2 b) { return make_float2(a.x * b.x - a.y * b.y, a.x * b.y + a.y * b.x); }
; template <int LR, bool INV>
; __device__ __forceinline__ void fft_stages(float2 (&x)[1 << LR], const int r, const int s) {
;     ...
;     for (int m = 0; m < R; ++m) {
;       if (m & hl) continue;
;       const int k = m & (hl - 1); const int j = k * (8 / hl);
;       const float2 wc = make_float2(c16(j), INV ? s16(j) : -s16(j));
;       const float2 tw = cmul(wb, wc);
;       if (!INV) { const float2 p = x[m], q = x[m + hl]; x[m] = make_float2(p.x + q.x, p.y + q.y); x[m + hl] = cmul(make_float2(p.x - q.x, p.y - q.y), tw); }
;       else { const float2 p = x[m], q = cmul(x[m + hl], tw); x[m] = make_float2(p.x + q.x, p.y + q.y); x[m + hl] = make_float2(p.x - q.x, p.y - q.y); }
;     }
	v_sub_f32_e32 v42, v46, v44
	v_sub_f32_e32 v43, v47, v45
	v_add_f32_e32 v40, v46, v44
	v_add_f32_e32 v41, v47, v45
	v_mul_f32_e32 v44, v14, v43
	v_mul_f32_e32 v45, v15, v43
	v_fma_f32 v46, v12, v42, -v44
	v_fma_f32 v47, v13, v42, v45

;     static __device__ __forceinline__ float sl(float g, float up) { return g * __builtin_amdgcn_rcpf(1.0f + __builtin_amdgcn_exp2f(-1.4426950408889634f * g)) * up; }
; __device__ __forceinline__ float2 cmul(float2 a, float2 b) { return make_float2(a.x * b.x - a.y * b.y, a.x * b.y + a.y * b.x); }
; template <int LR, bool INV>
; __device__ __forceinline__ void fft_stages(float2 (&x)[1 << LR], const int r, const int s) {
;     ...
;     for (int m = 0; m < R; ++m) {
;       if (m & hl) continue;
;       const int k = m & (hl - 1); const int j = k * (8 / hl);
;       const float2 wc = make_float2(c16(j), INV ? s16(j) : -s16(j));
;       const float2 tw = cmul(wb, wc);
;       if (!INV) { const float2 p = x[m], q = x[m + hl]; x[m] = make_float2(p.x + q.x, p.y + q.y); x[m + hl] = cmul(make_float2(p.x - q.x, p.y - q.y), tw); }
;       else { const float2 p = x[m], q = cmul(x[m + hl], tw); x[m] = make_float2(p.x + q.x, p.y + q.y); x[m + hl] = make_float2(p.x - q.x, p.y - q.y); }
;     }
; template <int LR, bool INV>
; __device__ __forceinline__ void fft_pass(float2* X, const int N, const int sl, const int tid) {
;     ...
;     for (int m = 0; m < R; ++m) X[PIDX(i0 + (m << sl))] = x[m];
	ds_write2_b64 v53, v[40:41], v[46:47] offset0:16 offset1:24
	v_mul_f32_e32 v40, v20, v33
	v_mul_f32_e32 v41, v21, v33
	v_fma_f32 v42, v0, v32, -v40
	v_fma_f32 v43, v1, v32, v41

; __device__ __forceinline__ float2 cmul(float2 a, float2 b) { return make_float2(a.x * b.x - a.y * b.y, a.x * b.y + a.y * b.x); }
; template <int LR, bool INV>
; __device__ __forceinline__ void fft_stages(float2 (&x)[1 << LR], const int r, const int s) {
;     ...
;     for (int m = 0; m < R; ++m) {
;       if (m & hl) continue;
;       const int k = m & (hl - 1); const int j = k * (8 / hl);
;       const float2 wc = make_float2(c16(j), INV ? s16(j) : -s16(j));
;       const float2 tw = cmul(wb, wc);
;       if (!INV) { const float2 p = x[m], q = x[m + hl]; x[m] = make_float2(p.x + q.x, p.y + q.y); x[m + hl] = cmul(make_float2(p.x - q.x, p.y - q.y), tw); }
;       else { const float2 p = x[m], q = cmul(x[m + hl], tw); x[m] = make_float2(p.x + q.x, p.y + q.y); x[m + hl] = make_float2(p.x - q.x, p.y - q.y); }
;     }
	v_mul_f32_e32 v32, v22, v35
	v_mul_f32_e32 v33, v23, v35
	v_fma_f32 v40, v2, v34, -v32
	v_fma_f32 v41, v3, v34, v33

; __device__ __forceinline__ float2 cmul(float2 a, float2 b) { return make_float2(a.x * b.x - a.y * b.y, a.x * b.y + a.y * b.x); }
; template <int LR, bool INV>
; __device__ __forceinline__ void fft_stages(float2 (&x)[1 << LR], const int r, const int s) {
;     ...
;     for (int m = 0; m < R; ++m) {
;       if (m & hl) continue;
;       const int k = m & (hl - 1); const int j = k * (8 / hl);
;       const float2 wc = make_float2(c16(j), INV ? s16(j) : -s16(j));
;       const float2 tw = cmul(wb, wc);
;       if (!INV) { const float2 p = x[m], q = x[m + hl]; x[m] = make_float2(p.x + q.x, p.y + q.y); x[m + hl] = cmul(make_float2(p.x - q.x, p.y - q.y), tw); }
;       else { const float2 p = x[m], q = cmul(x[m + hl], tw); x[m] = make_float2(p.x + q.x, p.y + q.y); x[m + hl] = make_float2(p.x - q.x, p.y - q.y); }
;     }
	v_mul_f32_e32 v32, v24, v37
	v_mul_f32_e32 v33, v25, v37
	v_fma_f32 v34, v4, v36, -v32
	v_fma_f32 v35, v5, v36, v33

; __device__ __forceinline__ float2 cmul(float2 a, float2 b) { return make_float2(a.x * b.x - a.y * b.y, a.x * b.y + a.y * b.x); }
; template <int LR, bool INV>
; __device__ __forceinline__ void fft_stages(float2 (&x)[1 << LR], const int r, const int s) {
;     ...
;     for (int m = 0; m < R; ++m) {
;       if (m & hl) continue;
;       const int k = m & (hl - 1); const int j = k * (8 / hl);
;       const float2 wc = make_float2(c16(j), INV ? s16(j) : -s16(j));
;       const float2 tw = cmul(wb, wc);
;       if (!INV) { const float2 p = x[m], q = x[m + hl]; x[m] = make_float2(p.x + q.x, p.y + q.y); x[m + hl] = cmul(make_float2(p.x - q.x, p.y - q.y), tw); }
;       else { const float2 p = x[m], q = cmul(x[m + hl], tw); x[m] = make_float2(p.x + q.x, p.y + q.y); x[m + hl] = make_float2(p.x - q.x, p.y - q.y); }
;     }
	v_mul_f32_e32 v32, v26, v39
	v_mul_f32_e32 v33, v27, v39
	v_fma_f32 v36, v6, v38, -v32
	v_fma_f32 v37, v7, v38, v33

; __device__ __forceinline__ float2 cmul(float2 a, float2 b) { return make_float2(a.x * b.x - a.y * b.y, a.x * b.y + a.y * b.x); }
; template <int LR, bool INV>
; __device__ __forceinline__ void fft_stages(float2 (&x)[1 << LR], const int r, const int s) {
;     ...
;     for (int m = 0; m < R; ++m) {
;       if (m & hl) continue;
;       const int k = m & (hl - 1); const int j = k * (8 / hl);
;       const float2 wc = make_float2(c16(j), INV ? s16(j) : -s16(j));
;       const float2 tw = cmul(wb, wc);
;       if (!INV) { const float2 p = x[m], q = x[m + hl]; x[m] = make_float2(p.x + q.x, p.y + q.y); x[m + hl] = cmul(make_float2(p.x - q.x, p.y - q.y), tw); }
;       else { const float2 p = x[m], q = cmul(x[m + hl], tw); x[m] = make_float2(p.x + q.x, p.y + q.y); x[m + hl] = make_float2(p.x - q.x, p.y - q.y); }
;     }
	v_add_f32_e32 v32, v42, v34
	v_add_f32_e32 v33, v43, v35
	v_add_f32_e32 v38, v40, v36
	v_add_f32_e32 v39, v41, v37
	v_sub_f32_e32 v36, v40, v36
	v_sub_f32_e32 v37, v41, v37
	v_add_f32_e32 v40, v32, v38
	v_add_f32_e32 v41, v33, v39
	v_sub_f32_e32 v32, v32, v38
	v_sub_f32_e32 v33, v33, v39
	v_sub_f32_e32 v34, v42, v34
	v_sub_f32_e32 v35, v43, v35
	v_mul_f32_e32 v38, v14, v33
	v_mul_f32_e32 v39, v15, v33
	v_fma_f32 v42, v12, v32, -v38
	v_fma_f32 v43, v13, v32, v39

;     static __device__ __forceinline__ float sl(float g, float up) { return g * __builtin_amdgcn_rcpf(1.0f + __builtin_amdgcn_exp2f(-1.4426950408889634f * g)) * up; }
; __device__ __forceinline__ float2 cmul(float2 a, float2 b) { return make_float2(a.x * b.x - a.y * b.y, a.x * b.y + a.y * b.x); }
; template <int LR, bool INV>
; __device__ __forceinline__ void fft_stages(float2 (&x)[1 << LR], const int r, const int s) {
;     ...
;     for (int m = 0; m < R; ++m) {
;       if (m & hl) continue;
;       const int k = m & (hl - 1); const int j = k * (8 / hl);
;       const float2 wc = make_float2(c16(j), INV ? s16(j) : -s16(j));
;       const float2 tw = cmul(wb, wc);
;       if (!INV) { const float2 p = x[m], q = x[m + hl]; x[m] = make_float2(p.x + q.x, p.y + q.y); x[m + hl] = cmul(make_float2(p.x - q.x, p.y - q.y), tw); }
;       else { const float2 p = x[m], q = cmul(x[m + hl], tw); x[m] = make_float2(p.x + q.x, p.y + q.y); x[m + hl] = make_float2(p.x - q.x, p.y - q.y); }
;     }
; template <int LR, bool INV>
; __device__ __forceinline__ void fft_pass(float2* X, const int N, const int sl, const int tid) {
;     ...
;     for (int m = 0; m < R; ++m) X[PIDX(i0 + (m << sl))] = x[m];
	v_mul_f32_e32 v32, v16, v35
	v_mul_f32_e32 v33, v17, v35
	ds_write2_b64 v53, v[40:41], v[42:43] offset0:33 offset1:41
	v_fma_f32 v38, v8, v34, -v32
	v_fma_f32 v39, v9, v34, v33

; __device__ __forceinline__ float2 cmul(float2 a, float2 b) { return make_float2(a.x * b.x - a.y * b.y, a.x * b.y + a.y * b.x); }
; template <int LR, bool INV>
; __device__ __forceinline__ void fft_stages(float2 (&x)[1 << LR], const int r, const int s) {
;     ...
;     for (int m = 0; m < R; ++m) {
;       if (m & hl) continue;
;       const int k = m & (hl - 1); const int j = k * (8 / hl);
;       const float2 wc = make_float2(c16(j), INV ? s16(j) : -s16(j));
;       const float2 tw = cmul(wb, wc);
;       if (!INV) { const float2 p = x[m], q = x[m + hl]; x[m] = make_float2(p.x + q.x, p.y + q.y); x[m + hl] = cmul(make_float2(p.x - q.x, p.y - q.y), tw); }
;       else { const float2 p = x[m], q = cmul(x[m + hl], tw); x[m] = make_float2(p.x + q.x, p.y + q.y); x[m + hl] = make_float2(p.x - q.x, p.y - q.y); }
;     }
	v_mul_f32_e32 v32, v18, v37
	v_mul_f32_e32 v33, v19, v37
	v_fma_f32 v34, v10, v36, -v32
	v_fma_f32 v35, v11, v36, v33

;     static __device__ __forceinline__ float sl(float g, float up) { return g * __builtin_amdgcn_rcpf(1.0f + __builtin_amdgcn_exp2f(-1.4426950408889634f * g)) * up; }
; __device__ __forceinline__ float2 cmul(float2 a, float2 b) { return make_float2(a.x * b.x - a.y * b.y, a.x * b.y + a.y * b.x); }
; template <int LR, bool INV>
; __device__ __forceinline__ void fft_stages(float2 (&x)[1 << LR], const int r, const int s) {
;     ...
;     for (int m = 0; m < R; ++m) {
;       if (m & hl) continue;
;       const int k = m & (hl - 1); const int j = k * (8 / hl);
;       const float2 wc = make_float2(c16(j), INV ? s16(j) : -s16(j));
;       const float2 tw = cmul(wb, wc);
;       if (!INV) { const float2 p = x[m], q = x[m + hl]; x[m] = make_float2(p.x + q.x, p.y + q.y); x[m + hl] = cmul(make_float2(p.x - q.x, p.y - q.y), tw); }
;       else { const float2 p = x[m], q = cmul(x[m + hl], tw); x[m] = make_float2(p.x + q.x, p.y + q.y); x[m + hl] = make_float2(p.x - q.x, p.y - q.y); }
;     }
; template <int LR, bool INV>
; __device__ __forceinline__ void fft_pass(float2* X, const int N, const int sl, const int tid) {
;     ...
;     for (int m = 0; m < R; ++m) X[PIDX(i0 + (m << sl))] = x[m];
	v_add_f32_e32 v32, v38, v34
	v_add_f32_e32 v33, v39, v35
	v_sub_f32_e32 v34, v38, v34
	v_sub_f32_e32 v35, v39, v35
	v_mul_f32_e32 v36, v14, v35
	v_mul_f32_e32 v37, v15, v35
	v_fma_f32 v38, v12, v34, -v36
	v_fma_f32 v35, v13, v34, v37
	v_fma_f32 v34, v12, v34, v36
	v_mov_b32_e32 v39, v35
	ds_write2_b64 v53, v[32:33], v[38:39] offset0:50 offset1:58
	s_andn2_b64 exec, exec, s[14:15]
	s_cbranch_execnz .LBB0_663

;     static __device__ __forceinline__ float sl(float g, float up) { return g * __builtin_amdgcn_rcpf(1.0f + __builtin_amdgcn_exp2f(-1.4426950408889634f * g)) * up; }
; __device__ __forceinline__ float2 cmul(float2 a, float2 b) { return make_float2(a.x * b.x - a.y * b.y, a.x * b.y + a.y * b.x); }
; #define tid ltid()
; template <int LR, bool INV>
; __device__ __forceinline__ void fft_stages(float2 (&x)[1 << LR], const int r, const int s) {
;     ...
;   for (int st = 0; st < LR; ++st) {
;     const int hl = INV ? (1 << st) : (R >> (st + 1));
;     const float fb = (float)r * (0.5f / (float)(hl * s));
;     const float2 wb = make_float2(__builtin_amdgcn_cosf(fb), INV ? __builtin_amdgcn_sinf(fb) : -__builtin_amdgcn_sinf(fb));
; #pragma unroll
;     for (int m = 0; m < R; ++m) {
;       if (m & hl) continue;
;       const int k = m & (hl - 1); const int j = k * (8 / hl);
;       const float2 wc = make_float2(c16(j), INV ? s16(j) : -s16(j));
;       const float2 tw = cmul(wb, wc);
;       if (!INV) { const float2 p = x[m], q = x[m + hl]; x[m] = make_float2(p.x + q.x, p.y + q.y); x[m + hl] = cmul(make_float2(p.x - q.x, p.y - q.y), tw); }
;       else { const float2 p = x[m], q = cmul(x[m + hl], tw); x[m] = make_float2(p.x + q.x, p.y + q.y); x[m + hl] = make_float2(p.x - q.x, p.y - q.y); }
;     }
; template <int LR, bool INV>
; __device__ __forceinline__ void fft_pass(float2* X, const int N, const int sl, const int tid) {
;     ...
;   for (int g = tid; g < (N >> LR); g += NTHR) {
;     const int r = g & (s - 1);
;     const int i0 = ((g >> sl) << (sl + LR)) + r;
;     float2 x[R];
; #pragma unroll
;     for (int m = 0; m < R; ++m) x[m] = X[PIDX(i0 + (m << sl))];
.LBB0_666:
	v_ashrrev_i32_e32 v0, 4, v28
	v_lshl_add_u32 v5, v0, 3, v4
	ds_read2_b64 v[6:9], v5 offset1:1
	ds_read2_b64 v[10:13], v5 offset0:2 offset1:3
	ds_read2_b64 v[14:17], v5 offset0:4 offset1:5
	ds_read2_b64 v[18:21], v5 offset0:6 offset1:7
	s_mov_b32 s74, s71
	s_mov_b32 s20, s75
	s_mov_b32 s21, s71
	s_waitcnt lgkmcnt(1)
	v_add_f32_e32 v0, v6, v14
	v_add_f32_e32 v1, v7, v15
	v_add_f32_e32 v2, v8, v16
	v_add_f32_e32 v3, v9, v17
	s_waitcnt lgkmcnt(0)
	v_add_f32_e32 v24, v10, v18
	v_add_f32_e32 v25, v11, v19
	v_add_f32_e32 v26, v12, v20
	v_add_f32_e32 v27, v13, v21
	v_add_f32_e32 v30, v0, v24
	v_add_f32_e32 v31, v1, v25
	v_add_f32_e32 v32, v2, v26
	v_add_f32_e32 v33, v3, v27
	v_sub_f32_e32 v0, v0, v24
	v_sub_f32_e32 v1, v1, v25
	v_add_f32_e32 v34, v30, v32
	v_add_f32_e32 v35, v31, v33
	v_sub_f32_e32 v30, v30, v32
	v_sub_f32_e32 v31, v31, v33
	v_mul_f32_e32 v24, 0, v0
	v_mul_f32_e32 v25, 0, v1
	v_mul_f32_e32 v32, 0, v30
	v_mul_f32_e32 v33, 0, v31
	v_sub_f32_e32 v22, v8, v16
	v_add_f32_e32 v36, v30, v33
	v_sub_f32_e32 v37, v31, v32
	v_mul_f32_e32 v22, 0x3f3504f3, v22

; __device__ __forceinline__ float2 cmul(float2 a, float2 b) { return make_float2(a.x * b.x - a.y * b.y, a.x * b.y + a.y * b.x); }
; template <int LR, bool INV>
; __device__ __forceinline__ void fft_stages(float2 (&x)[1 << LR], const int r, const int s) {
;     ...
;     for (int m = 0; m < R; ++m) {
;       if (m & hl) continue;
;       const int k = m & (hl - 1); const int j = k * (8 / hl);
;       const float2 wc = make_float2(c16(j), INV ? s16(j) : -s16(j));
;       const float2 tw = cmul(wb, wc);
;       if (!INV) { const float2 p = x[m], q = x[m + hl]; x[m] = make_float2(p.x + q.x, p.y + q.y); x[m + hl] = cmul(make_float2(p.x - q.x, p.y - q.y), tw); }
;       else { const float2 p = x[m], q = cmul(x[m + hl], tw); x[m] = make_float2(p.x + q.x, p.y + q.y); x[m + hl] = make_float2(p.x - q.x, p.y - q.y); }
;     }
	v_add_f32_e32 v30, v0, v25
	v_sub_f32_e32 v31, v1, v24
	v_add_u32_e32 v60, 0x200, v60

; __device__ __forceinline__ float2 cmul(float2 a, float2 b) { return make_float2(a.x * b.x - a.y * b.y, a.x * b.y + a.y * b.x); }
; template <int LR, bool INV>
; __device__ __forceinline__ void fft_stages(float2 (&x)[1 << LR], const int r, const int s) {
;     ...
;     for (int m = 0; m < R; ++m) {
;       if (m & hl) continue;
;       const int k = m & (hl - 1); const int j = k * (8 / hl);
;       const float2 wc = make_float2(c16(j), INV ? s16(j) : -s16(j));
;       const float2 tw = cmul(wb, wc);
;       if (!INV) { const float2 p = x[m], q = x[m + hl]; x[m] = make_float2(p.x + q.x, p.y + q.y); x[m + hl] = cmul(make_float2(p.x - q.x, p.y - q.y), tw); }
;       else { const float2 p = x[m], q = cmul(x[m + hl], tw); x[m] = make_float2(p.x + q.x, p.y + q.y); x[m + hl] = make_float2(p.x - q.x, p.y - q.y); }
;     }
	v_sub_f32_e32 v0, v2, v26
	v_sub_f32_e32 v1, v3, v27
	v_cmp_le_i32_e32 vcc, s19, v60
	v_fma_f32 v2, v0, 0, v1
	v_fma_f32 v3, v1, 0, -v0
	v_add_u32_e32 v4, 0x8000, v4

;     static __device__ __forceinline__ float sl(float g, float up) { return g * __builtin_amdgcn_rcpf(1.0f + __builtin_amdgcn_exp2f(-1.4426950408889634f * g)) * up; }
; __device__ __forceinline__ float2 cmul(float2 a, float2 b) { return make_float2(a.x * b.x - a.y * b.y, a.x * b.y + a.y * b.x); }
; template <int LR, bool INV>
; __device__ __forceinline__ void fft_stages(float2 (&x)[1 << LR], const int r, const int s) {
;     ...
;     for (int m = 0; m < R; ++m) {
;       if (m & hl) continue;
;       const int k = m & (hl - 1); const int j = k * (8 / hl);
;       const float2 wc = make_float2(c16(j), INV ? s16(j) : -s16(j));
;       const float2 tw = cmul(wb, wc);
;       if (!INV) { const float2 p = x[m], q = x[m + hl]; x[m] = make_float2(p.x + q.x, p.y + q.y); x[m + hl] = cmul(make_float2(p.x - q.x, p.y - q.y), tw); }
;       else { const float2 p = x[m], q = cmul(x[m + hl], tw); x[m] = make_float2(p.x + q.x, p.y + q.y); x[m + hl] = make_float2(p.x - q.x, p.y - q.y); }
;     }
; template <int LR, bool INV>
; __device__ __forceinline__ void fft_pass(float2* X, const int N, const int sl, const int tid) {
;     ...
;     for (int m = 0; m < R; ++m) X[PIDX(i0 + (m << sl))] = x[m];
	v_add_f32_e32 v0, v30, v2
	v_add_f32_e32 v1, v31, v3
	v_sub_f32_e32 v2, v30, v2
	v_sub_f32_e32 v3, v31, v3
	v_add_u32_e32 v28, 0x1000, v28
	v_mul_f32_e32 v24, 0, v2
	v_mul_f32_e32 v25, 0, v3
	s_or_b64 s[14:15], vcc, s[14:15]
	v_add_f32_e32 v26, v2, v25
	v_sub_f32_e32 v27, v3, v24
	ds_write2_b64 v5, v[34:35], v[36:37] offset1:1

;     static __device__ __forceinline__ float sl(float g, float up) { return g * __builtin_amdgcn_rcpf(1.0f + __builtin_amdgcn_exp2f(-1.4426950408889634f * g)) * up; }
; __device__ __forceinline__ float2 cmul(float2 a, float2 b) { return make_float2(a.x * b.x - a.y * b.y, a.x * b.y + a.y * b.x); }
; template <int LR, bool INV>
; __device__ __forceinline__ void fft_stages(float2 (&x)[1 << LR], const int r, const int s) {
;     ...
;     for (int m = 0; m < R; ++m) {
;       if (m & hl) continue;
;       const int k = m & (hl - 1); const int j = k * (8 / hl);
;       const float2 wc = make_float2(c16(j), INV ? s16(j) : -s16(j));
;       const float2 tw = cmul(wb, wc);
;       if (!INV) { const float2 p = x[m], q = x[m + hl]; x[m] = make_float2(p.x + q.x, p.y + q.y); x[m + hl] = cmul(make_float2(p.x - q.x, p.y - q.y), tw); }
;       else { const float2 p = x[m], q = cmul(x[m + hl], tw); x[m] = make_float2(p.x + q.x, p.y + q.y); x[m + hl] = make_float2(p.x - q.x, p.y - q.y); }
;     }
; template <int LR, bool INV>
; __device__ __forceinline__ void fft_pass(float2* X, const int N, const int sl, const int tid) {
;     ...
;     for (int m = 0; m < R; ++m) X[PIDX(i0 + (m << sl))] = x[m];
	ds_write2_b64 v5, v[0:1], v[26:27] offset0:2 offset1:3
	v_pk_mov_b32 v[0:1], v[8:9], v[6:7] op_sel:[1,0]
	v_pk_mov_b32 v[2:3], v[16:17], v[14:15] op_sel:[1,0]
	v_mov_b32_e32 v8, v10
	v_mov_b32_e32 v16, v18
	v_sub_f32_e32 v0, v0, v2
	v_sub_f32_e32 v1, v1, v3
	v_sub_f32_e32 v2, v8, v16
	v_sub_f32_e32 v3, v9, v17
	v_mov_b32_e32 v6, v7
	v_mov_b32_e32 v7, v13
	v_mov_b32_e32 v8, v15
	v_mov_b32_e32 v9, v21
	v_sub_f32_e32 v6, v6, v8
	v_sub_f32_e32 v7, v7, v9
	v_mov_b32_e32 v13, v11
	v_mov_b32_e32 v21, v19
	v_mov_b32_e32 v23, v6
	v_sub_f32_e32 v10, v12, v20
	v_sub_f32_e32 v11, v13, v21
	v_fma_f32 v8, v0, s74, v22
	v_pk_mov_b32 v[12:13], v[10:11], v[22:23] op_sel:[1,0]
	v_fma_f32 v15, -v1, s75, v23
	v_fma_f32 v16, v2, s20, v12
	v_fma_f32 v13, v3, s21, -v13
	s_mov_b32 s74, s70
	s_mov_b32 s21, s70
	v_mul_f32_e32 v18, s74, v10
	v_mul_f32_e32 v19, s75, v11
	v_mul_f32_e32 v20, s20, v6
	v_mul_f32_e32 v21, s21, v7
	v_pk_mov_b32 v[0:1], v[0:1], v[18:19] op_sel:[1,0]
	v_pk_mov_b32 v[2:3], v[20:21], v[2:3] op_sel:[1,0]
	v_mov_b32_e32 v9, v15
	v_mov_b32_e32 v17, v13
	v_fma_f32 v2, v10, s74, -v2
	v_fma_f32 v3, v11, s75, -v3
	v_fma_f32 v0, v6, s20, v0
	v_fma_f32 v1, v7, s21, v1
	v_add_f32_e32 v6, v8, v2
	v_add_f32_e32 v7, v9, v3
	v_add_f32_e32 v10, v0, v16
	v_add_f32_e32 v11, v1, v17
	v_mov_b32_e32 v21, v7
	v_add_f32_e32 v18, v6, v10
	v_add_f32_e32 v19, v7, v11
	v_mov_b32_e32 v20, v10
	v_mov_b32_e32 v7, v11
	v_sub_f32_e32 v6, v20, v6
	v_sub_f32_e32 v7, v21, v7
	v_mov_b32_e32 v14, v0
	v_mul_f32_e32 v10, 0, v6
	v_mul_f32_e32 v11, 0, v7
	v_mov_b32_e32 v17, v3
	v_add_f32_e32 v20, v6, v11
	v_sub_f32_e32 v21, v7, v10
	v_mov_b32_e32 v9, v13

; __device__ __forceinline__ float2 cmul(float2 a, float2 b) { return make_float2(a.x * b.x - a.y * b.y, a.x * b.y + a.y * b.x); }
; template <int LR, bool INV>
; __device__ __forceinline__ void fft_stages(float2 (&x)[1 << LR], const int r, const int s) {
;     ...
;   for (int st = 0; st < LR; ++st) {
;     const int hl = INV ? (1 << st) : (R >> (st + 1));
;     const float fb = (float)r * (0.5f / (float)(hl * s));
;     const float2 wb = make_float2(__builtin_amdgcn_cosf(fb), INV ? __builtin_amdgcn_sinf(fb) : -__builtin_amdgcn_sinf(fb));
; #pragma unroll
;     for (int m = 0; m < R; ++m) {
;       if (m & hl) continue;
;       const int k = m & (hl - 1); const int j = k * (8 / hl);
;       const float2 wc = make_float2(c16(j), INV ? s16(j) : -s16(j));
;       const float2 tw = cmul(wb, wc);
;       if (!INV) { const float2 p = x[m], q = x[m + hl]; x[m] = make_float2(p.x + q.x, p.y + q.y); x[m + hl] = cmul(make_float2(p.x - q.x, p.y - q.y), tw); }
;       else { const float2 p = x[m], q = cmul(x[m + hl], tw); x[m] = make_float2(p.x + q.x, p.y + q.y); x[m + hl] = make_float2(p.x - q.x, p.y - q.y); }
;     }
	v_sub_f32_e32 v6, v14, v16
	v_sub_f32_e32 v7, v15, v17
	v_mov_b32_e32 v3, v1
	v_mul_f32_e32 v10, 0, v6
	v_mul_f32_e32 v11, 0, v7
	v_sub_f32_e32 v0, v8, v2
	v_sub_f32_e32 v1, v9, v3
	v_add_f32_e32 v14, v6, v11
	v_sub_f32_e32 v15, v7, v10
	v_fma_f32 v2, v0, 0, v1
	v_fma_f32 v3, v1, 0, -v0


;     static __device__ __forceinline__ float sl(float g, float up) { return g * __builtin_amdgcn_rcpf(1.0f + __builtin_amdgcn_exp2f(-1.4426950408889634f * g)) * up; }
; __device__ __forceinline__ float2 cmul(float2 a, float2 b) { return make_float2(a.x * b.x - a.y * b.y, a.x * b.y + a.y * b.x); }
; template <int LR, bool INV>
; __device__ __forceinline__ void fft_stages(float2 (&x)[1 << LR], const int r, const int s) {
;     ...
;   for (int st = 0; st < LR; ++st) {
;     const int hl = INV ? (1 << st) : (R >> (st + 1));
;     const float fb = (float)r * (0.5f / (float)(hl * s));
;     const float2 wb = make_float2(__builtin_amdgcn_cosf(fb), INV ? __builtin_amdgcn_sinf(fb) : -__builtin_amdgcn_sinf(fb));
; #pragma unroll
;     for (int m = 0; m < R; ++m) {
;       if (m & hl) continue;
;       const int k = m & (hl - 1); const int j = k * (8 / hl);
;       const float2 wc = make_float2(c16(j), INV ? s16(j) : -s16(j));
;       const float2 tw = cmul(wb, wc);
;       if (!INV) { const float2 p = x[m], q = x[m + hl]; x[m] = make_float2(p.x + q.x, p.y + q.y); x[m + hl] = cmul(make_float2(p.x - q.x, p.y - q.y), tw); }
;       else { const float2 p = x[m], q = cmul(x[m + hl], tw); x[m] = make_float2(p.x + q.x, p.y + q.y); x[m + hl] = make_float2(p.x - q.x, p.y - q.y); }
;     }
; template <int LR, bool INV>
; __device__ __forceinline__ void fft_pass(float2* X, const int N, const int sl, const int tid) {
;     ...
;     for (int m = 0; m < R; ++m) X[PIDX(i0 + (m << sl))] = x[m];
	v_add_f32_e32 v0, v14, v2
	v_add_f32_e32 v1, v15, v3
	v_sub_f32_e32 v2, v14, v2
	v_sub_f32_e32 v3, v15, v3
	ds_write2_b64 v5, v[18:19], v[20:21] offset0:4 offset1:5
	v_mul_f32_e32 v6, 0, v2
	v_mul_f32_e32 v7, 0, v3
	v_add_f32_e32 v8, v2, v7
	v_sub_f32_e32 v3, v3, v6
	v_mov_b32_e32 v9, v3
	ds_write2_b64 v5, v[0:1], v[8:9] offset0:6 offset1:7
	s_andn2_b64 exec, exec, s[14:15]
	s_cbranch_execnz .LBB0_666

; __device__ __forceinline__ float bfl(unsigned w) { return __uint_as_float(w << 16); }
; #define tid ltid()
; template <int LR>
; __device__ __forceinline__ void fft_first(float2* X, const bf16* __restrict__ u0, const bf16* __restrict__ u1, const int tid) {
;   constexpr int R = 1 << LR;
;   float2 x[R];
; #pragma unroll
;   for (int m = 0; m < R / 2; ++m) x[m] = make_float2(bfl(u0[tid + 512 * m]), bfl(u1[tid + 512 * m]));
; #pragma unroll
;   for (int m = R / 2; m < R; ++m) x[m] = make_float2(0.f, 0.f);
;   fft_stages<LR, false>(x, tid, 512);
; #pragma unroll
;   for (int m = 0; m < R; ++m) X[PIDX(tid + 512 * m)] = x[m];
;   __syncthreads();
; }
; __global__ void __launch_bounds__(NTHR, 2) mega_fwd(Args a_unused) {
;     ...
;           for (int pr = 0; pr < 4; ++pr) {
;             bf16* u0 = urow + (size_t)(2 * pr) * L; bf16* u1 = u0 + L;
;             if (gsel) fft_first<4>(A, u0, u1, tid); else fft_first<3>(A, u0, u1, tid);
.LBB0_669:
	s_lshl_b32 s12, s18, 1
	s_lshl_b32 s12, s12, s20
	s_lshl_b32 s12, s12, 1
	s_add_u32 s40, s17, s12
	s_addc_u32 s41, s19, 0
	s_add_u32 s42, s40, s16
	s_addc_u32 s43, s41, 0
	s_mov_b64 s[12:13], -1
	s_and_b64 vcc, exec, s[10:11]
	s_cbranch_vccz .LBB0_671
	v_mov_b32_e32 v2, v208
	s_mov_b32 s12, s71
	v_ashrrev_i32_e32 v3, 31, v2
	v_lshlrev_b64 v[4:5], 1, v[2:3]
	v_lshl_add_u64 v[6:7], s[40:41], 0, v[4:5]
	v_lshl_add_u64 v[4:5], s[42:43], 0, v[4:5]
	global_load_ushort v9, v[4:5], off
	global_load_ushort v11, v[6:7], off
	global_load_ushort v13, v[4:5], off offset:1024
	global_load_ushort v15, v[6:7], off offset:1024
	global_load_ushort v22, v[4:5], off offset:2048
	global_load_ushort v24, v[6:7], off offset:2048
	s_nop 0
	global_load_ushort v5, v[4:5], off offset:3072
	s_nop 0
	global_load_ushort v7, v[6:7], off offset:3072
	v_cvt_f32_i32_e32 v8, v2
	v_add_u32_e32 v4, 0x400, v2
	v_add_u32_e32 v3, 0x200, v2
	v_add_u32_e32 v6, 0x600, v2
	v_ashrrev_i32_e32 v10, 4, v2
	v_lshl_add_u32 v12, v2, 3, 0
	v_add_u32_e32 v14, 0x800, v2
	v_add_u32_e32 v16, 0xa00, v2
	v_add_u32_e32 v17, 0xc00, v2
	v_add_u32_e32 v2, 0xe00, v2
	v_ashrrev_i32_e32 v4, 4, v4
	v_lshl_add_u32 v40, v10, 3, v12
	v_ashrrev_i32_e32 v3, 4, v3
	v_ashrrev_i32_e32 v6, 4, v6
	v_ashrrev_i32_e32 v10, 4, v14
	v_ashrrev_i32_e32 v14, 4, v16
	v_ashrrev_i32_e32 v16, 4, v17
	v_ashrrev_i32_e32 v2, 4, v2
	v_lshl_add_u32 v42, v4, 3, v12
	v_mul_f32_e32 v4, 0x3a000000, v8
	v_lshl_add_u32 v41, v3, 3, v12
	v_lshl_add_u32 v43, v6, 3, v12
	v_lshl_add_u32 v44, v10, 3, v12
	v_lshl_add_u32 v45, v14, 3, v12
	v_lshl_add_u32 v46, v16, 3, v12
	v_lshl_add_u32 v47, v2, 3, v12
	v_cos_f32_e32 v10, v4
	v_sin_f32_e32 v12, v4
	v_mul_f32_e32 v6, 0x3a800000, v8
	v_cos_f32_e32 v14, v6
	v_sin_f32_e32 v16, v6
	v_mul_f32_e32 v2, 0x39800000, v8
	v_fmamk_f32 v4, v12, 0x80000000, v10
	v_fma_f32 v6, v10, s91, -v12
	v_fma_f32 v8, v10, 0, -v12
	v_fma_f32 v10, v12, s91, -v10
	v_cos_f32_e32 v3, v2
	v_sin_f32_e32 v2, v2
	v_fmamk_f32 v12, v16, 0x80000000, v14
	v_fma_f32 v14, v14, s91, -v16
	s_mov_b32 s13, s70
	v_xor_b32_e32 v48, 0x80000000, v2
	v_pk_mov_b32 v[16:17], v[2:3], v[2:3] op_sel:[1,0]
	s_mov_b32 s90, s75
	v_mov_b32_e32 v17, v48
	v_fma_f32 v16, -v2, 0, v16
	v_fma_f32 v17, -v3, 0, v17
	s_waitcnt vmcnt(7)
	v_lshlrev_b32_e32 v19, 16, v9
	s_waitcnt vmcnt(6)
	v_lshlrev_b32_e32 v18, 16, v11
	s_waitcnt vmcnt(5)
	v_lshlrev_b32_e32 v21, 16, v13
	s_waitcnt vmcnt(4)
	v_lshlrev_b32_e32 v20, 16, v15
	s_waitcnt vmcnt(3)
	v_lshlrev_b32_e32 v23, 16, v22
	s_waitcnt vmcnt(2)
	v_lshlrev_b32_e32 v22, 16, v24
	s_waitcnt vmcnt(1)
	v_lshlrev_b32_e32 v25, 16, v5
	s_waitcnt vmcnt(0)
	v_lshlrev_b32_e32 v24, 16, v7
	v_add_f32_e32 v26, 0, v18
	v_add_f32_e32 v27, 0, v19
	v_add_f32_e32 v28, 0, v20
	v_add_f32_e32 v29, 0, v21
	v_add_f32_e32 v30, 0, v22
	v_add_f32_e32 v31, 0, v23
	v_add_f32_e32 v32, 0, v24
	v_add_f32_e32 v33, 0, v25
	v_sub_f32_e32 v34, v26, v30
	v_sub_f32_e32 v35, v27, v31
	v_sub_f32_e32 v36, v28, v32
	v_sub_f32_e32 v37, v29, v33
	v_add_f32_e32 v26, v26, v30
	v_add_f32_e32 v27, v27, v31
	v_add_f32_e32 v28, v28, v32
	v_add_f32_e32 v29, v29, v33
	v_mul_f32_e32 v30, v6, v34
	v_mul_f32_e32 v31, v6, v35
	v_mul_f32_e32 v32, v10, v36
	v_mul_f32_e32 v33, v10, v37
	v_sub_f32_e32 v38, v26, v28
	v_sub_f32_e32 v39, v27, v29
	v_add_f32_e32 v26, v26, v28
	v_add_f32_e32 v27, v27, v29
	v_fma_f32 v28, v4, v34, -v31
	v_fma_f32 v29, v4, v35, v30
	v_fma_f32 v34, v8, v36, -v33
	v_fma_f32 v35, v8, v37, v32
	v_mul_f32_e32 v36, v14, v38
	v_mul_f32_e32 v37, v14, v39


; __device__ __forceinline__ float2 cmul(float2 a, float2 b) { return make_float2(a.x * b.x - a.y * b.y, a.x * b.y + a.y * b.x); }
; #define tid ltid()
; template <int LR, bool INV>
; __device__ __forceinline__ void fft_stages(float2 (&x)[1 << LR], const int r, const int s) {
;     ...
;     for (int m = 0; m < R; ++m) {
;       if (m & hl) continue;
;       const int k = m & (hl - 1); const int j = k * (8 / hl);
;       const float2 wc = make_float2(c16(j), INV ? s16(j) : -s16(j));
;       const float2 tw = cmul(wb, wc);
;       if (!INV) { const float2 p = x[m], q = x[m + hl]; x[m] = make_float2(p.x + q.x, p.y + q.y); x[m + hl] = cmul(make_float2(p.x - q.x, p.y - q.y), tw); }
;       else { const float2 p = x[m], q = cmul(x[m + hl], tw); x[m] = make_float2(p.x + q.x, p.y + q.y); x[m + hl] = make_float2(p.x - q.x, p.y - q.y); }
;     }
; template <int LR>
; __device__ __forceinline__ void fft_first(float2* X, const bf16* __restrict__ u0, const bf16* __restrict__ u1, const int tid) {
;     ...
;   for (int m = 0; m < R; ++m) X[PIDX(tid + 512 * m)] = x[m];
	ds_write_b64 v40, v[26:27]
	v_fma_f32 v26, v12, v38, -v37
	v_fma_f32 v27, v12, v39, v36
	v_sub_f32_e32 v32, v28, v34
	v_sub_f32_e32 v33, v29, v35

; __device__ __forceinline__ float2 cmul(float2 a, float2 b) { return make_float2(a.x * b.x - a.y * b.y, a.x * b.y + a.y * b.x); }
; #define tid ltid()
; template <int LR, bool INV>
; __device__ __forceinline__ void fft_stages(float2 (&x)[1 << LR], const int r, const int s) {
;     ...
;     for (int m = 0; m < R; ++m) {
;       if (m & hl) continue;
;       const int k = m & (hl - 1); const int j = k * (8 / hl);
;       const float2 wc = make_float2(c16(j), INV ? s16(j) : -s16(j));
;       const float2 tw = cmul(wb, wc);
;       if (!INV) { const float2 p = x[m], q = x[m + hl]; x[m] = make_float2(p.x + q.x, p.y + q.y); x[m + hl] = cmul(make_float2(p.x - q.x, p.y - q.y), tw); }
;       else { const float2 p = x[m], q = cmul(x[m + hl], tw); x[m] = make_float2(p.x + q.x, p.y + q.y); x[m + hl] = make_float2(p.x - q.x, p.y - q.y); }
;     }
; template <int LR>
; __device__ __forceinline__ void fft_first(float2* X, const bf16* __restrict__ u0, const bf16* __restrict__ u1, const int tid) {
;     ...
;   for (int m = 0; m < R; ++m) X[PIDX(tid + 512 * m)] = x[m];
	v_add_f32_e32 v28, v28, v34
	v_add_f32_e32 v29, v29, v35
	v_mul_f32_e32 v30, v14, v32
	v_mul_f32_e32 v31, v14, v33
	ds_write_b64 v41, v[26:27] offset:4096
	ds_write_b64 v42, v[28:29] offset:8192
	v_fma_f32 v26, v12, v32, -v31
	v_fma_f32 v27, v12, v33, v30

; __device__ __forceinline__ float2 cmul(float2 a, float2 b) { return make_float2(a.x * b.x - a.y * b.y, a.x * b.y + a.y * b.x); }
; template <int LR, bool INV>
; __device__ __forceinline__ void fft_stages(float2 (&x)[1 << LR], const int r, const int s) {
;     ...
;     for (int m = 0; m < R; ++m) {
;       if (m & hl) continue;
;       const int k = m & (hl - 1); const int j = k * (8 / hl);
;       const float2 wc = make_float2(c16(j), INV ? s16(j) : -s16(j));
;       const float2 tw = cmul(wb, wc);
;       if (!INV) { const float2 p = x[m], q = x[m + hl]; x[m] = make_float2(p.x + q.x, p.y + q.y); x[m + hl] = cmul(make_float2(p.x - q.x, p.y - q.y), tw); }
;       else { const float2 p = x[m], q = cmul(x[m + hl], tw); x[m] = make_float2(p.x + q.x, p.y + q.y); x[m + hl] = make_float2(p.x - q.x, p.y - q.y); }
;     }
	ds_write_b64 v43, v[26:27] offset:12288
	v_mov_b32_e32 v26, v19
	v_mul_f32_e32 v27, v16, v26
	v_mul_f32_e32 v26, v17, v26
	v_fma_f32 v28, v16, v18, -v26
	v_fma_f32 v29, v17, v18, v27
	v_mov_b32_e32 v26, v21

; __device__ __forceinline__ float2 cmul(float2 a, float2 b) { return make_float2(a.x * b.x - a.y * b.y, a.x * b.y + a.y * b.x); }
; template <int LR, bool INV>
; __device__ __forceinline__ void fft_stages(float2 (&x)[1 << LR], const int r, const int s) {
;     ...
;     const int hl = INV ? (1 << st) : (R >> (st + 1));
;     const float fb = (float)r * (0.5f / (float)(hl * s));
;     const float2 wb = make_float2(__builtin_amdgcn_cosf(fb), INV ? __builtin_amdgcn_sinf(fb) : -__builtin_amdgcn_sinf(fb));
; #pragma unroll
;     for (int m = 0; m < R; ++m) {
;       if (m & hl) continue;
;       const int k = m & (hl - 1); const int j = k * (8 / hl);
;       const float2 wc = make_float2(c16(j), INV ? s16(j) : -s16(j));
;       const float2 tw = cmul(wb, wc);
;       if (!INV) { const float2 p = x[m], q = x[m + hl]; x[m] = make_float2(p.x + q.x, p.y + q.y); x[m + hl] = cmul(make_float2(p.x - q.x, p.y - q.y), tw); }
;       else { const float2 p = x[m], q = cmul(x[m + hl], tw); x[m] = make_float2(p.x + q.x, p.y + q.y); x[m + hl] = make_float2(p.x - q.x, p.y - q.y); }
;     }
	v_mul_f32_e32 v16, s70, v2
	v_mul_f32_e32 v17, s70, v3
	v_fma_f32 v18, v3, s12, v16
	v_fma_f32 v19, v2, s13, v17
	v_mul_f32_e32 v27, v18, v26
	v_mul_f32_e32 v26, v19, v26
	v_fma_f32 v30, v18, v20, -v26
	v_fma_f32 v31, v19, v20, v27
	v_mov_b32_e32 v20, v23

; __device__ __forceinline__ float2 cmul(float2 a, float2 b) { return make_float2(a.x * b.x - a.y * b.y, a.x * b.y + a.y * b.x); }
; template <int LR, bool INV>
; __device__ __forceinline__ void fft_stages(float2 (&x)[1 << LR], const int r, const int s) {
;     ...
;     const int hl = INV ? (1 << st) : (R >> (st + 1));
;     const float fb = (float)r * (0.5f / (float)(hl * s));
;     const float2 wb = make_float2(__builtin_amdgcn_cosf(fb), INV ? __builtin_amdgcn_sinf(fb) : -__builtin_amdgcn_sinf(fb));
; #pragma unroll
;     for (int m = 0; m < R; ++m) {
;       if (m & hl) continue;
;       const int k = m & (hl - 1); const int j = k * (8 / hl);
;       const float2 wc = make_float2(c16(j), INV ? s16(j) : -s16(j));
;       const float2 tw = cmul(wb, wc);
;       if (!INV) { const float2 p = x[m], q = x[m + hl]; x[m] = make_float2(p.x + q.x, p.y + q.y); x[m + hl] = cmul(make_float2(p.x - q.x, p.y - q.y), tw); }
;       else { const float2 p = x[m], q = cmul(x[m + hl], tw); x[m] = make_float2(p.x + q.x, p.y + q.y); x[m + hl] = make_float2(p.x - q.x, p.y - q.y); }
;     }
	v_fma_f32 v18, v3, s90, -v2
	v_fma_f32 v19, v2, s91, -v3
	v_mul_f32_e32 v21, v18, v20
	v_mul_f32_e32 v20, v19, v20
	v_pk_fma_f32 v[2:3], v[2:3], s[70:71], v[16:17] op_sel:[1,0,0] op_sel_hi:[0,1,1]
	v_mov_b32_e32 v16, v25
	v_fma_f32 v26, v18, v22, -v20
	v_fma_f32 v27, v19, v22, v21
	v_mul_f32_e32 v17, v2, v16
	v_mul_f32_e32 v16, v3, v16

; __device__ __forceinline__ float2 cmul(float2 a, float2 b) { return make_float2(a.x * b.x - a.y * b.y, a.x * b.y + a.y * b.x); }
; template <int LR, bool INV>
; __device__ __forceinline__ void fft_stages(float2 (&x)[1 << LR], const int r, const int s) {
;     ...
;     for (int m = 0; m < R; ++m) {
;       if (m & hl) continue;
;       const int k = m & (hl - 1); const int j = k * (8 / hl);
;       const float2 wc = make_float2(c16(j), INV ? s16(j) : -s16(j));
;       const float2 tw = cmul(wb, wc);
;       if (!INV) { const float2 p = x[m], q = x[m + hl]; x[m] = make_float2(p.x + q.x, p.y + q.y); x[m + hl] = cmul(make_float2(p.x - q.x, p.y - q.y), tw); }
;       else { const float2 p = x[m], q = cmul(x[m + hl], tw); x[m] = make_float2(p.x + q.x, p.y + q.y); x[m + hl] = make_float2(p.x - q.x, p.y - q.y); }
;     }
	v_fma_f32 v18, v2, v24, -v16
	v_fma_f32 v19, v3, v24, v17
	s_mov_b64 s[12:13], 0

; __device__ __forceinline__ float2 cmul(float2 a, float2 b) { return make_float2(a.x * b.x - a.y * b.y, a.x * b.y + a.y * b.x); }
; template <int LR, bool INV>
; __device__ __forceinline__ void fft_stages(float2 (&x)[1 << LR], const int r, const int s) {
;     ...
;     for (int m = 0; m < R; ++m) {
;       if (m & hl) continue;
;       const int k = m & (hl - 1); const int j = k * (8 / hl);
;       const float2 wc = make_float2(c16(j), INV ? s16(j) : -s16(j));
;       const float2 tw = cmul(wb, wc);
;       if (!INV) { const float2 p = x[m], q = x[m + hl]; x[m] = make_float2(p.x + q.x, p.y + q.y); x[m + hl] = cmul(make_float2(p.x - q.x, p.y - q.y), tw); }
;       else { const float2 p = x[m], q = cmul(x[m + hl], tw); x[m] = make_float2(p.x + q.x, p.y + q.y); x[m + hl] = make_float2(p.x - q.x, p.y - q.y); }
;     }
	v_sub_f32_e32 v2, v28, v26
	v_sub_f32_e32 v3, v29, v27
	v_mul_f32_e32 v7, v6, v3
	v_mul_f32_e32 v6, v6, v2
	v_fma_f32 v16, v4, v2, -v7
	v_fma_f32 v17, v4, v3, v6

; __device__ __forceinline__ float2 cmul(float2 a, float2 b) { return make_float2(a.x * b.x - a.y * b.y, a.x * b.y + a.y * b.x); }
; template <int LR, bool INV>
; __device__ __forceinline__ void fft_stages(float2 (&x)[1 << LR], const int r, const int s) {
;     ...
;     for (int m = 0; m < R; ++m) {
;       if (m & hl) continue;
;       const int k = m & (hl - 1); const int j = k * (8 / hl);
;       const float2 wc = make_float2(c16(j), INV ? s16(j) : -s16(j));
;       const float2 tw = cmul(wb, wc);
;       if (!INV) { const float2 p = x[m], q = x[m + hl]; x[m] = make_float2(p.x + q.x, p.y + q.y); x[m + hl] = cmul(make_float2(p.x - q.x, p.y - q.y), tw); }
;       else { const float2 p = x[m], q = cmul(x[m + hl], tw); x[m] = make_float2(p.x + q.x, p.y + q.y); x[m + hl] = make_float2(p.x - q.x, p.y - q.y); }
;     }
	v_sub_f32_e32 v2, v30, v18
	v_sub_f32_e32 v3, v31, v19
	v_mul_f32_e32 v4, v10, v2
	v_mul_f32_e32 v5, v10, v3
	v_fma_f32 v6, v8, v2, -v5
	v_fma_f32 v7, v8, v3, v4

; __device__ __forceinline__ float2 cmul(float2 a, float2 b) { return make_float2(a.x * b.x - a.y * b.y, a.x * b.y + a.y * b.x); }
; template <int LR, bool INV>
; __device__ __forceinline__ void fft_stages(float2 (&x)[1 << LR], const int r, const int s) {
;     ...
;     for (int m = 0; m < R; ++m) {
;       if (m & hl) continue;
;       const int k = m & (hl - 1); const int j = k * (8 / hl);
;       const float2 wc = make_float2(c16(j), INV ? s16(j) : -s16(j));
;       const float2 tw = cmul(wb, wc);
;       if (!INV) { const float2 p = x[m], q = x[m + hl]; x[m] = make_float2(p.x + q.x, p.y + q.y); x[m + hl] = cmul(make_float2(p.x - q.x, p.y - q.y), tw); }
;       else { const float2 p = x[m], q = cmul(x[m + hl], tw); x[m] = make_float2(p.x + q.x, p.y + q.y); x[m + hl] = make_float2(p.x - q.x, p.y - q.y); }
;     }
	v_sub_f32_e32 v2, v16, v6
	v_sub_f32_e32 v3, v17, v7
	v_mul_f32_e32 v4, v14, v2
	v_mul_f32_e32 v5, v14, v3
	v_fma_f32 v8, v12, v2, -v5
	v_fma_f32 v9, v12, v3, v4

;     static __device__ __forceinline__ float sl(float g, float up) { return g * __builtin_amdgcn_rcpf(1.0f + __builtin_amdgcn_exp2f(-1.4426950408889634f * g)) * up; }
; __device__ __forceinline__ float bfl(unsigned w) { return __uint_as_float(w << 16); }
; __device__ __forceinline__ float2 cmul(float2 a, float2 b) { return make_float2(a.x * b.x - a.y * b.y, a.x * b.y + a.y * b.x); }
; #define tid ltid()
; template <int LR, bool INV>
; __device__ __forceinline__ void fft_stages(float2 (&x)[1 << LR], const int r, const int s) {
;     ...
;     for (int m = 0; m < R; ++m) {
;       if (m & hl) continue;
;       const int k = m & (hl - 1); const int j = k * (8 / hl);
;       const float2 wc = make_float2(c16(j), INV ? s16(j) : -s16(j));
;       const float2 tw = cmul(wb, wc);
;       if (!INV) { const float2 p = x[m], q = x[m + hl]; x[m] = make_float2(p.x + q.x, p.y + q.y); x[m + hl] = cmul(make_float2(p.x - q.x, p.y - q.y), tw); }
;       else { const float2 p = x[m], q = cmul(x[m + hl], tw); x[m] = make_float2(p.x + q.x, p.y + q.y); x[m + hl] = make_float2(p.x - q.x, p.y - q.y); }
;     }
;   }
; }
; template <int LR, bool INV>
; __device__ __forceinline__ void fft_pass(float2* X, const int N, const int sl, const int tid) {
;   constexpr int R = 1 << LR;
;   const int s = 1 << sl;
;   for (int g = tid; g < (N >> LR); g += NTHR) {
;     const int r = g & (s - 1);
;     const int i0 = ((g >> sl) << (sl + LR)) + r;
;     float2 x[R];
; #pragma unroll
;     for (int m = 0; m < R; ++m) x[m] = X[PIDX(i0 + (m << sl))];
;     fft_stages<LR, INV>(x, r, s);
; #pragma unroll
;     for (int m = 0; m < R; ++m) X[PIDX(i0 + (m << sl))] = x[m];
;   }
;   __syncthreads();
; }
; template <int LR>
; __device__ __forceinline__ void fft_first(float2* X, const bf16* __restrict__ u0, const bf16* __restrict__ u1, const int tid) {
;   constexpr int R = 1 << LR;
;   float2 x[R];
; #pragma unroll
;   for (int m = 0; m < R / 2; ++m) x[m] = make_float2(bfl(u0[tid + 512 * m]), bfl(u1[tid + 512 * m]));
; #pragma unroll
;   for (int m = R / 2; m < R; ++m) x[m] = make_float2(0.f, 0.f);
;   fft_stages<LR, false>(x, tid, 512);
; #pragma unroll
;   for (int m = 0; m < R; ++m) X[PIDX(tid + 512 * m)] = x[m];
;   __syncthreads();
; }
	v_add_f32_e32 v2, v28, v26
	v_add_f32_e32 v3, v29, v27
	v_add_f32_e32 v4, v30, v18
	v_add_f32_e32 v5, v31, v19
	v_sub_f32_e32 v10, v2, v4
	v_sub_f32_e32 v11, v3, v5
	v_add_f32_e32 v2, v2, v4
	v_add_f32_e32 v3, v3, v5
	v_mul_f32_e32 v15, v14, v11
	v_mul_f32_e32 v14, v14, v10
	v_fma_f32 v18, v12, v10, -v15
	v_fma_f32 v11, v12, v11, v14
	v_mov_b32_e32 v19, v11
	ds_write_b64 v44, v[2:3] offset:16384
	ds_write_b64 v45, v[18:19] offset:20480
	v_add_f32_e32 v2, v16, v6
	v_add_f32_e32 v3, v17, v7
	ds_write_b64 v46, v[2:3] offset:24576
	ds_write_b64 v47, v[8:9] offset:28672
	s_waitcnt lgkmcnt(0)
	s_barrier
.LBB0_671:
	s_andn2_b64 vcc, exec, s[12:13]
	s_cbranch_vccnz .LBB0_673
	v_mov_b32_e32 v2, v208
	s_mov_b32 s14, s71
	v_ashrrev_i32_e32 v3, 31, v2
	v_lshlrev_b64 v[4:5], 1, v[2:3]
	v_lshl_add_u64 v[6:7], s[40:41], 0, v[4:5]
	v_lshl_add_u64 v[4:5], s[42:43], 0, v[4:5]
	global_load_ushort v3, v[6:7], off
	global_load_ushort v20, v[4:5], off
	global_load_ushort v21, v[6:7], off offset:1024
	global_load_ushort v26, v[4:5], off offset:1024
	global_load_ushort v27, v[6:7], off offset:2048
	global_load_ushort v28, v[4:5], off offset:2048
	global_load_ushort v33, v[4:5], off offset:3072
	global_load_ushort v44, v[6:7], off offset:3072
	v_add_co_u32_e32 v6, vcc, s64, v6
	v_cvt_f32_i32_e32 v64, v2
	s_nop 0
	v_addc_co_u32_e32 v7, vcc, 0, v7, vcc
	v_add_co_u32_e32 v4, vcc, s64, v4
	s_mov_b32 s15, s70
	s_nop 0
	v_addc_co_u32_e32 v5, vcc, 0, v5, vcc
	global_load_ushort v45, v[6:7], off
	global_load_ushort v46, v[4:5], off
	global_load_ushort v47, v[6:7], off offset:1024
	global_load_ushort v48, v[4:5], off offset:1024
	global_load_ushort v49, v[6:7], off offset:2048
	global_load_ushort v50, v[4:5], off offset:2048
	global_load_ushort v51, v[4:5], off offset:3072
	global_load_ushort v52, v[6:7], off offset:3072
	v_mul_f32_e32 v4, 0x39000000, v64
	v_sin_f32_e32 v9, v4
	v_cos_f32_e32 v8, v4
	v_mul_f32_e32 v53, 0x39800000, v64
	s_mov_b32 s90, s75
	v_xor_b32_e32 v5, 0x80000000, v9
	v_mul_f32_e32 v10, 0, v9
	v_mov_b32_e32 v4, v8
	v_mul_f32_e32 v11, 0, v8
	v_mov_b32_e32 v36, v9
	v_mov_b32_e32 v37, v8
	s_mov_b32 s12, s71
	v_cos_f32_e32 v29, v53
	v_mul_f32_e32 v13, 0xbf3504f3, v9
	v_mul_f32_e32 v12, 0x3f3504f3, v8
	v_sub_f32_e32 v22, v4, v10
	v_sub_f32_e32 v23, v5, v11
	v_mul_f32_e32 v4, s14, v36
	v_mul_f32_e32 v5, s15, v37
	v_mul_f32_e32 v10, s94, v36
	v_mul_f32_e32 v11, s94, v37
	v_mul_f32_e32 v38, s72, v36
	v_mul_f32_e32 v39, s73, v37
	v_fma_f32 v6, v8, s90, -v9
	v_fma_f32 v7, v9, s91, -v8
	v_mul_f32_e32 v32, 0xbec3ef15, v8
	v_mul_f32_e32 v41, s72, v8
	v_fma_f32 v14, -v36, s12, v12
	v_fma_f32 v15, -v37, s12, v13
	v_pk_fma_f32 v[4:5], v[36:37], s[12:13], v[4:5] op_sel:[0,0,1] op_sel_hi:[1,0,0] neg_lo:[1,0,0] neg_hi:[1,0,0]
	v_fma_f32 v24, v8, s72, -v10
	v_fma_f32 v25, v9, s73, -v11
	v_pk_mov_b32 v[42:43], v[10:11], v[10:11] op_sel:[1,0]

; __device__ __forceinline__ float bfl(unsigned w) { return __uint_as_float(w << 16); }
; __device__ __forceinline__ float2 cmul(float2 a, float2 b) { return make_float2(a.x * b.x - a.y * b.y, a.x * b.y + a.y * b.x); }
; #define tid ltid()
; template <int LR, bool INV>
; __device__ __forceinline__ void fft_stages(float2 (&x)[1 << LR], const int r, const int s) {
;     ...
;     const int hl = INV ? (1 << st) : (R >> (st + 1));
;     const float fb = (float)r * (0.5f / (float)(hl * s));
;     const float2 wb = make_float2(__builtin_amdgcn_cosf(fb), INV ? __builtin_amdgcn_sinf(fb) : -__builtin_amdgcn_sinf(fb));
; #pragma unroll
;     for (int m = 0; m < R; ++m) {
;       if (m & hl) continue;
;       const int k = m & (hl - 1); const int j = k * (8 / hl);
;       const float2 wc = make_float2(c16(j), INV ? s16(j) : -s16(j));
;       const float2 tw = cmul(wb, wc);
;       if (!INV) { const float2 p = x[m], q = x[m + hl]; x[m] = make_float2(p.x + q.x, p.y + q.y); x[m + hl] = cmul(make_float2(p.x - q.x, p.y - q.y), tw); }
;       else { const float2 p = x[m], q = cmul(x[m + hl], tw); x[m] = make_float2(p.x + q.x, p.y + q.y); x[m + hl] = make_float2(p.x - q.x, p.y - q.y); }
;     }
; template <int LR>
; __device__ __forceinline__ void fft_first(float2* X, const bf16* __restrict__ u0, const bf16* __restrict__ u1, const int tid) {
;   constexpr int R = 1 << LR;
;   float2 x[R];
; #pragma unroll
;   for (int m = 0; m < R / 2; ++m) x[m] = make_float2(bfl(u0[tid + 512 * m]), bfl(u1[tid + 512 * m]));
; #pragma unroll
;   for (int m = R / 2; m < R; ++m) x[m] = make_float2(0.f, 0.f);
;   fft_stages<LR, false>(x, tid, 512);
	v_mov_b32_e32 v40, v38
	v_add_u32_e32 v60, 0x200, v2
	v_add_u32_e32 v61, 0x400, v2
	v_mul_f32_e32 v17, 0xbec3ef15, v9
	v_mov_b32_e32 v16, v42
	v_sub_f32_e32 v16, v16, v40
	v_sub_f32_e32 v17, v17, v41
	v_add_u32_e32 v62, 0x600, v2
	v_add_u32_e32 v63, 0x800, v2
	v_add_u32_e32 v65, 0xa00, v2
	v_add_u32_e32 v67, 0xe00, v2
	v_add_u32_e32 v66, 0xc00, v2
	s_waitcnt vmcnt(15)
	v_lshlrev_b32_e32 v34, 16, v3
	v_mul_f32_e32 v3, 0x3a000000, v64
	s_waitcnt vmcnt(13)
	v_lshlrev_b32_e32 v30, 16, v21
	s_waitcnt vmcnt(12)
	v_lshlrev_b32_e32 v31, 16, v26
	s_waitcnt vmcnt(11)
	v_lshlrev_b32_e32 v26, 16, v27
	s_waitcnt vmcnt(10)
	v_lshlrev_b32_e32 v27, 16, v28
	v_sin_f32_e32 v28, v53
	s_waitcnt vmcnt(9)
	v_lshlrev_b32_e32 v21, 16, v33
	v_mov_b32_e32 v33, v43
	v_lshlrev_b32_e32 v35, 16, v20
	v_sub_f32_e32 v54, v32, v40
	v_sub_f32_e32 v55, v33, v41
	s_waitcnt vmcnt(7)
	v_lshlrev_b32_e32 v18, 16, v45
	s_waitcnt vmcnt(6)
	v_lshlrev_b32_e32 v19, 16, v46
	v_mov_b32_e32 v32, v29
	v_mov_b32_e32 v33, v28
	v_mul_f32_e32 v58, s70, v32
	v_mul_f32_e32 v59, s71, v33
	v_ashrrev_i32_e32 v33, 4, v60
	v_add_f32_e32 v68, 0, v18
	v_add_f32_e32 v69, 0, v19
	s_waitcnt vmcnt(0)
	v_lshlrev_b32_e32 v8, 16, v52
	v_fma_f32 v52, -v36, s94, v39
	v_fma_f32 v53, -v37, s94, v38
	v_cos_f32_e32 v37, v3
	v_sin_f32_e32 v3, v3
	v_lshlrev_b32_e32 v20, 16, v44
	v_lshlrev_b32_e32 v13, 16, v48
	v_lshlrev_b32_e32 v11, 16, v50
	v_fmamk_f32 v36, v3, 0x80000000, v37
	v_fma_f32 v42, v37, s91, -v3
	v_fma_f32 v38, v37, 0, -v3
	v_fma_f32 v40, v3, s91, -v37
	v_ashrrev_i32_e32 v37, 4, v61
	v_add_f32_e32 v60, 0, v34
	v_add_f32_e32 v61, 0, v35
	v_fmamk_f32 v48, v28, 0x80000000, v29
	v_fma_f32 v50, v29, s91, -v28
	v_mul_f32_e32 v56, s70, v28
	v_mul_f32_e32 v57, s71, v29
	v_fma_f32 v44, v29, 0, -v28
	v_fma_f32 v46, v28, s91, -v29
	v_mul_f32_e32 v28, 0x3a800000, v64
	v_sub_f32_e32 v76, v60, v68
	v_sub_f32_e32 v77, v61, v69
	v_lshlrev_b32_e32 v12, 16, v47
	v_cos_f32_e32 v29, v28
	v_sin_f32_e32 v32, v28
	v_mul_f32_e32 v78, v50, v76
	v_mul_f32_e32 v79, v50, v77
	v_ashrrev_i32_e32 v39, 4, v62
	v_ashrrev_i32_e32 v41, 4, v63
	v_add_f32_e32 v62, 0, v30
	v_add_f32_e32 v63, 0, v31
	v_add_f32_e32 v70, 0, v12
	v_add_f32_e32 v71, 0, v13
	v_fma_f32 v80, v48, v76, -v79
	v_fma_f32 v81, v48, v77, v78

; __device__ __forceinline__ float2 cmul(float2 a, float2 b) { return make_float2(a.x * b.x - a.y * b.y, a.x * b.y + a.y * b.x); }
; template <int LR, bool INV>
; __device__ __forceinline__ void fft_stages(float2 (&x)[1 << LR], const int r, const int s) {
;     ...
;     for (int m = 0; m < R; ++m) {
;       if (m & hl) continue;
;       const int k = m & (hl - 1); const int j = k * (8 / hl);
;       const float2 wc = make_float2(c16(j), INV ? s16(j) : -s16(j));
;       const float2 tw = cmul(wb, wc);
;       if (!INV) { const float2 p = x[m], q = x[m + hl]; x[m] = make_float2(p.x + q.x, p.y + q.y); x[m + hl] = cmul(make_float2(p.x - q.x, p.y - q.y), tw); }
;       else { const float2 p = x[m], q = cmul(x[m + hl], tw); x[m] = make_float2(p.x + q.x, p.y + q.y); x[m + hl] = make_float2(p.x - q.x, p.y - q.y); }
;     }
	v_sub_f32_e32 v76, v62, v70
	v_sub_f32_e32 v77, v63, v71
	v_sub_f32_e32 v78, v56, v57
	v_sub_f32_e32 v79, v56, v57
	v_lshlrev_b32_e32 v10, 16, v49
	v_mul_f32_e32 v82, v78, v76
	v_mul_f32_e32 v83, v79, v77
	v_sub_f32_e32 v56, v57, v59
	v_fmamk_f32 v28, v32, 0x80000000, v29
	v_fma_f32 v32, v29, s91, -v32
	v_lshl_add_u32 v29, v2, 3, 0
	v_ashrrev_i32_e32 v43, 4, v65
	v_ashrrev_i32_e32 v47, 4, v67
	v_add_f32_e32 v64, 0, v26
	v_add_f32_e32 v65, 0, v27
	v_add_f32_e32 v72, 0, v10
	v_add_f32_e32 v73, 0, v11
	v_fma_f32 v84, v56, v76, -v83
	v_fma_f32 v85, v56, v77, v82
	v_ashrrev_i32_e32 v45, 4, v66
	v_lshl_add_u32 v47, v47, 3, v29

; __device__ __forceinline__ float2 cmul(float2 a, float2 b) { return make_float2(a.x * b.x - a.y * b.y, a.x * b.y + a.y * b.x); }
; template <int LR, bool INV>
; __device__ __forceinline__ void fft_stages(float2 (&x)[1 << LR], const int r, const int s) {
;     ...
;     for (int m = 0; m < R; ++m) {
;       if (m & hl) continue;
;       const int k = m & (hl - 1); const int j = k * (8 / hl);
;       const float2 wc = make_float2(c16(j), INV ? s16(j) : -s16(j));
;       const float2 tw = cmul(wb, wc);
;       if (!INV) { const float2 p = x[m], q = x[m + hl]; x[m] = make_float2(p.x + q.x, p.y + q.y); x[m + hl] = cmul(make_float2(p.x - q.x, p.y - q.y), tw); }
;       else { const float2 p = x[m], q = cmul(x[m + hl], tw); x[m] = make_float2(p.x + q.x, p.y + q.y); x[m + hl] = make_float2(p.x - q.x, p.y - q.y); }
;     }
	v_sub_f32_e32 v76, v64, v72
	v_sub_f32_e32 v77, v65, v73
	v_lshlrev_b32_e32 v9, 16, v51
	v_lshl_add_u32 v45, v45, 3, v29
	v_mul_f32_e32 v82, v46, v76
	v_mul_f32_e32 v83, v46, v77
	v_add_f32_e32 v66, 0, v20
	v_add_f32_e32 v67, 0, v21
	v_add_f32_e32 v74, 0, v8
	v_add_f32_e32 v75, 0, v9
	v_fma_f32 v86, v44, v76, -v83
	v_fma_f32 v87, v44, v77, v82

; __device__ __forceinline__ float2 cmul(float2 a, float2 b) { return make_float2(a.x * b.x - a.y * b.y, a.x * b.y + a.y * b.x); }
; template <int LR, bool INV>
; __device__ __forceinline__ void fft_stages(float2 (&x)[1 << LR], const int r, const int s) {
;     ...
;     for (int m = 0; m < R; ++m) {
;       if (m & hl) continue;
;       const int k = m & (hl - 1); const int j = k * (8 / hl);
;       const float2 wc = make_float2(c16(j), INV ? s16(j) : -s16(j));
;       const float2 tw = cmul(wb, wc);
;       if (!INV) { const float2 p = x[m], q = x[m + hl]; x[m] = make_float2(p.x + q.x, p.y + q.y); x[m + hl] = cmul(make_float2(p.x - q.x, p.y - q.y), tw); }
;       else { const float2 p = x[m], q = cmul(x[m + hl], tw); x[m] = make_float2(p.x + q.x, p.y + q.y); x[m + hl] = make_float2(p.x - q.x, p.y - q.y); }
;     }
	v_sub_f32_e32 v76, v66, v74
	v_sub_f32_e32 v77, v67, v75
	v_sub_f32_e32 v82, v59, v57
	v_mul_f32_e32 v88, v82, v76
	v_mul_f32_e32 v89, v82, v77
	v_pk_add_f32 v[58:59], v[58:59], v[58:59] op_sel:[0,1] op_sel_hi:[0,1] neg_lo:[0,1] neg_hi:[0,1]
	v_fma_f32 v90, v58, v76, -v89
	v_fma_f32 v91, v59, v77, v88
	v_lshl_add_u32 v43, v43, 3, v29

; __device__ __forceinline__ float2 cmul(float2 a, float2 b) { return make_float2(a.x * b.x - a.y * b.y, a.x * b.y + a.y * b.x); }
; template <int LR, bool INV>
; __device__ __forceinline__ void fft_stages(float2 (&x)[1 << LR], const int r, const int s) {
;     ...
;     for (int m = 0; m < R; ++m) {
;       if (m & hl) continue;
;       const int k = m & (hl - 1); const int j = k * (8 / hl);
;       const float2 wc = make_float2(c16(j), INV ? s16(j) : -s16(j));
;       const float2 tw = cmul(wb, wc);
;       if (!INV) { const float2 p = x[m], q = x[m + hl]; x[m] = make_float2(p.x + q.x, p.y + q.y); x[m + hl] = cmul(make_float2(p.x - q.x, p.y - q.y), tw); }
;       else { const float2 p = x[m], q = cmul(x[m + hl], tw); x[m] = make_float2(p.x + q.x, p.y + q.y); x[m + hl] = make_float2(p.x - q.x, p.y - q.y); }
;     }
	v_sub_f32_e32 v76, v80, v86
	v_sub_f32_e32 v77, v81, v87
	v_add_f32_e32 v60, v60, v68
	v_add_f32_e32 v61, v61, v69
	v_add_f32_e32 v64, v64, v72
	v_add_f32_e32 v65, v65, v73
	v_lshl_add_u32 v37, v37, 3, v29
	v_mul_f32_e32 v88, v42, v76
	v_mul_f32_e32 v89, v42, v77
	v_sub_f32_e32 v68, v60, v64
	v_sub_f32_e32 v69, v61, v65
	v_fma_f32 v92, v36, v76, -v89
	v_fma_f32 v93, v36, v77, v88
	v_add_f32_e32 v62, v62, v70
	v_add_f32_e32 v63, v63, v71
	v_mul_f32_e32 v70, v42, v68
	v_mul_f32_e32 v71, v42, v69
	v_lshl_add_u32 v41, v41, 3, v29

; __device__ __forceinline__ float2 cmul(float2 a, float2 b) { return make_float2(a.x * b.x - a.y * b.y, a.x * b.y + a.y * b.x); }
; template <int LR, bool INV>
; __device__ __forceinline__ void fft_stages(float2 (&x)[1 << LR], const int r, const int s) {
;     ...
;     for (int m = 0; m < R; ++m) {
;       if (m & hl) continue;
;       const int k = m & (hl - 1); const int j = k * (8 / hl);
;       const float2 wc = make_float2(c16(j), INV ? s16(j) : -s16(j));
;       const float2 tw = cmul(wb, wc);
;       if (!INV) { const float2 p = x[m], q = x[m + hl]; x[m] = make_float2(p.x + q.x, p.y + q.y); x[m + hl] = cmul(make_float2(p.x - q.x, p.y - q.y), tw); }
;       else { const float2 p = x[m], q = cmul(x[m + hl], tw); x[m] = make_float2(p.x + q.x, p.y + q.y); x[m + hl] = make_float2(p.x - q.x, p.y - q.y); }
;     }
	v_sub_f32_e32 v76, v84, v90
	v_sub_f32_e32 v77, v85, v91
	v_add_f32_e32 v66, v66, v74
	v_add_f32_e32 v67, v67, v75
	v_fma_f32 v72, v36, v68, -v71
	v_fma_f32 v73, v36, v69, v70
	v_lshl_add_u32 v39, v39, 3, v29
	v_mul_f32_e32 v88, v40, v76
	v_mul_f32_e32 v89, v40, v77

; __device__ __forceinline__ float2 cmul(float2 a, float2 b) { return make_float2(a.x * b.x - a.y * b.y, a.x * b.y + a.y * b.x); }
; template <int LR, bool INV>
; __device__ __forceinline__ void fft_stages(float2 (&x)[1 << LR], const int r, const int s) {
;     ...
;     for (int m = 0; m < R; ++m) {
;       if (m & hl) continue;
;       const int k = m & (hl - 1); const int j = k * (8 / hl);
;       const float2 wc = make_float2(c16(j), INV ? s16(j) : -s16(j));
;       const float2 tw = cmul(wb, wc);
;       if (!INV) { const float2 p = x[m], q = x[m + hl]; x[m] = make_float2(p.x + q.x, p.y + q.y); x[m + hl] = cmul(make_float2(p.x - q.x, p.y - q.y), tw); }
;       else { const float2 p = x[m], q = cmul(x[m + hl], tw); x[m] = make_float2(p.x + q.x, p.y + q.y); x[m + hl] = make_float2(p.x - q.x, p.y - q.y); }
;     }
	v_sub_f32_e32 v68, v62, v66
	v_sub_f32_e32 v69, v63, v67
	v_fma_f32 v94, v38, v76, -v89
	v_fma_f32 v95, v38, v77, v88
	v_mul_f32_e32 v70, v40, v68
	v_mul_f32_e32 v71, v40, v69

; __device__ __forceinline__ float2 cmul(float2 a, float2 b) { return make_float2(a.x * b.x - a.y * b.y, a.x * b.y + a.y * b.x); }
; template <int LR, bool INV>
; __device__ __forceinline__ void fft_stages(float2 (&x)[1 << LR], const int r, const int s) {
;     ...
;     for (int m = 0; m < R; ++m) {
;       if (m & hl) continue;
;       const int k = m & (hl - 1); const int j = k * (8 / hl);
;       const float2 wc = make_float2(c16(j), INV ? s16(j) : -s16(j));
;       const float2 tw = cmul(wb, wc);
;       if (!INV) { const float2 p = x[m], q = x[m + hl]; x[m] = make_float2(p.x + q.x, p.y + q.y); x[m + hl] = cmul(make_float2(p.x - q.x, p.y - q.y), tw); }
;       else { const float2 p = x[m], q = cmul(x[m + hl], tw); x[m] = make_float2(p.x + q.x, p.y + q.y); x[m + hl] = make_float2(p.x - q.x, p.y - q.y); }
;     }
	v_fma_f32 v74, v38, v68, -v71
	v_fma_f32 v75, v38, v69, v70
	v_lshl_add_u32 v33, v33, 3, v29
	v_sub_f32_e32 v76, v92, v94
	v_sub_f32_e32 v77, v93, v95

; __device__ __forceinline__ float2 cmul(float2 a, float2 b) { return make_float2(a.x * b.x - a.y * b.y, a.x * b.y + a.y * b.x); }
; template <int LR, bool INV>
; __device__ __forceinline__ void fft_stages(float2 (&x)[1 << LR], const int r, const int s) {
;     ...
;     for (int m = 0; m < R; ++m) {
;       if (m & hl) continue;
;       const int k = m & (hl - 1); const int j = k * (8 / hl);
;       const float2 wc = make_float2(c16(j), INV ? s16(j) : -s16(j));
;       const float2 tw = cmul(wb, wc);
;       if (!INV) { const float2 p = x[m], q = x[m + hl]; x[m] = make_float2(p.x + q.x, p.y + q.y); x[m + hl] = cmul(make_float2(p.x - q.x, p.y - q.y), tw); }
;       else { const float2 p = x[m], q = cmul(x[m + hl], tw); x[m] = make_float2(p.x + q.x, p.y + q.y); x[m + hl] = make_float2(p.x - q.x, p.y - q.y); }
;     }
	v_mul_f32_e32 v88, v32, v76
	v_mul_f32_e32 v89, v32, v77
	v_sub_f32_e32 v68, v72, v74
	v_sub_f32_e32 v69, v73, v75
	v_add_f32_e32 v60, v60, v64
	v_add_f32_e32 v61, v61, v65
	v_add_f32_e32 v62, v62, v66
	v_add_f32_e32 v63, v63, v67
	v_fma_f32 v96, v28, v76, -v89
	v_fma_f32 v97, v28, v77, v88
	v_mul_f32_e32 v70, v32, v68
	v_mul_f32_e32 v71, v32, v69
	v_sub_f32_e32 v64, v60, v62
	v_sub_f32_e32 v65, v61, v63
	v_ashrrev_i32_e32 v3, 4, v2

; __device__ __forceinline__ float2 cmul(float2 a, float2 b) { return make_float2(a.x * b.x - a.y * b.y, a.x * b.y + a.y * b.x); }
; template <int LR, bool INV>
; __device__ __forceinline__ void fft_stages(float2 (&x)[1 << LR], const int r, const int s) {
;     ...
;     for (int m = 0; m < R; ++m) {
;       if (m & hl) continue;
;       const int k = m & (hl - 1); const int j = k * (8 / hl);
;       const float2 wc = make_float2(c16(j), INV ? s16(j) : -s16(j));
;       const float2 tw = cmul(wb, wc);
;       if (!INV) { const float2 p = x[m], q = x[m + hl]; x[m] = make_float2(p.x + q.x, p.y + q.y); x[m + hl] = cmul(make_float2(p.x - q.x, p.y - q.y), tw); }
;       else { const float2 p = x[m], q = cmul(x[m + hl], tw); x[m] = make_float2(p.x + q.x, p.y + q.y); x[m + hl] = make_float2(p.x - q.x, p.y - q.y); }
;     }
	v_fma_f32 v76, v28, v68, -v71
	v_fma_f32 v77, v28, v69, v70
	v_mul_f32_e32 v66, v32, v64
	v_mul_f32_e32 v67, v32, v65
	v_lshl_add_u32 v3, v3, 3, v29

; __device__ __forceinline__ float2 cmul(float2 a, float2 b) { return make_float2(a.x * b.x - a.y * b.y, a.x * b.y + a.y * b.x); }
; template <int LR, bool INV>
; __device__ __forceinline__ void fft_stages(float2 (&x)[1 << LR], const int r, const int s) {
;     ...
;     for (int m = 0; m < R; ++m) {
;       if (m & hl) continue;
;       const int k = m & (hl - 1); const int j = k * (8 / hl);
;       const float2 wc = make_float2(c16(j), INV ? s16(j) : -s16(j));
;       const float2 tw = cmul(wb, wc);
;       if (!INV) { const float2 p = x[m], q = x[m + hl]; x[m] = make_float2(p.x + q.x, p.y + q.y); x[m + hl] = cmul(make_float2(p.x - q.x, p.y - q.y), tw); }
;       else { const float2 p = x[m], q = cmul(x[m + hl], tw); x[m] = make_float2(p.x + q.x, p.y + q.y); x[m + hl] = make_float2(p.x - q.x, p.y - q.y); }
;     }
	v_fma_f32 v68, v28, v64, -v67
	v_fma_f32 v69, v28, v65, v66
	v_add_f32_e32 v60, v60, v62
	v_add_f32_e32 v61, v61, v63

;     static __device__ __forceinline__ float sl(float g, float up) { return g * __builtin_amdgcn_rcpf(1.0f + __builtin_amdgcn_exp2f(-1.4426950408889634f * g)) * up; }
; __device__ __forceinline__ float bfl(unsigned w) { return __uint_as_float(w << 16); }
; __device__ __forceinline__ float2 cmul(float2 a, float2 b) { return make_float2(a.x * b.x - a.y * b.y, a.x * b.y + a.y * b.x); }
; #define tid ltid()
; template <int LR, bool INV>
; __device__ __forceinline__ void fft_stages(float2 (&x)[1 << LR], const int r, const int s) {
;     ...
;     for (int m = 0; m < R; ++m) {
;       if (m & hl) continue;
;       const int k = m & (hl - 1); const int j = k * (8 / hl);
;       const float2 wc = make_float2(c16(j), INV ? s16(j) : -s16(j));
;       const float2 tw = cmul(wb, wc);
;       if (!INV) { const float2 p = x[m], q = x[m + hl]; x[m] = make_float2(p.x + q.x, p.y + q.y); x[m + hl] = cmul(make_float2(p.x - q.x, p.y - q.y), tw); }
;       else { const float2 p = x[m], q = cmul(x[m + hl], tw); x[m] = make_float2(p.x + q.x, p.y + q.y); x[m + hl] = make_float2(p.x - q.x, p.y - q.y); }
;     }
;   }
; }
; template <int LR, bool INV>
; __device__ __forceinline__ void fft_pass(float2* X, const int N, const int sl, const int tid) {
;   constexpr int R = 1 << LR;
;   const int s = 1 << sl;
;   for (int g = tid; g < (N >> LR); g += NTHR) {
;     const int r = g & (s - 1);
;     const int i0 = ((g >> sl) << (sl + LR)) + r;
;     float2 x[R];
; #pragma unroll
;     for (int m = 0; m < R; ++m) x[m] = X[PIDX(i0 + (m << sl))];
;     fft_stages<LR, INV>(x, r, s);
; #pragma unroll
;     for (int m = 0; m < R; ++m) X[PIDX(i0 + (m << sl))] = x[m];
;   }
;   __syncthreads();
; }
; template <int LR>
; __device__ __forceinline__ void fft_first(float2* X, const bf16* __restrict__ u0, const bf16* __restrict__ u1, const int tid) {
;   constexpr int R = 1 << LR;
;   float2 x[R];
; #pragma unroll
;   for (int m = 0; m < R / 2; ++m) x[m] = make_float2(bfl(u0[tid + 512 * m]), bfl(u1[tid + 512 * m]));
; #pragma unroll
;   for (int m = R / 2; m < R; ++m) x[m] = make_float2(0.f, 0.f);
;   fft_stages<LR, false>(x, tid, 512);
; #pragma unroll
;   for (int m = 0; m < R; ++m) X[PIDX(tid + 512 * m)] = x[m];
;   __syncthreads();
; }
	ds_write_b64 v3, v[60:61]
	ds_write_b64 v33, v[68:69] offset:4096
	v_add_f32_e32 v60, v72, v74
	v_add_f32_e32 v61, v73, v75
	ds_write_b64 v37, v[60:61] offset:8192
	ds_write_b64 v39, v[76:77] offset:12288
	v_add_f32_e32 v60, v80, v86
	v_add_f32_e32 v61, v81, v87
	v_add_f32_e32 v62, v84, v90
	v_add_f32_e32 v63, v85, v91
	v_add_u32_e32 v3, 0x1000, v2
	v_sub_f32_e32 v64, v60, v62
	v_sub_f32_e32 v65, v61, v63
	v_ashrrev_i32_e32 v3, 4, v3
	v_mul_f32_e32 v66, v32, v64
	v_mul_f32_e32 v67, v32, v65
	v_lshl_add_u32 v33, v3, 3, v29
	v_add_u32_e32 v3, 0x1200, v2
	v_ashrrev_i32_e32 v3, 4, v3
	v_lshl_add_u32 v37, v3, 3, v29
	v_add_u32_e32 v3, 0x1400, v2
	v_ashrrev_i32_e32 v3, 4, v3
	v_lshl_add_u32 v39, v3, 3, v29
	v_add_u32_e32 v3, 0x1600, v2
	v_fma_f32 v68, v28, v64, -v67
	v_fma_f32 v65, v28, v65, v66
	v_add_f32_e32 v60, v60, v62
	v_add_f32_e32 v61, v61, v63
	v_ashrrev_i32_e32 v3, 4, v3
	v_mov_b32_e32 v69, v65
	ds_write_b64 v41, v[60:61] offset:16384
	ds_write_b64 v43, v[68:69] offset:20480
	v_lshl_add_u32 v41, v3, 3, v29
	v_add_u32_e32 v3, 0x1800, v2
	v_ashrrev_i32_e32 v3, 4, v3
	v_lshl_add_u32 v43, v3, 3, v29
	v_add_u32_e32 v3, 0x1a00, v2
	v_add_f32_e32 v60, v92, v94
	v_add_f32_e32 v61, v93, v95
	v_ashrrev_i32_e32 v3, 4, v3
	ds_write_b64 v45, v[60:61] offset:24576
	ds_write_b64 v47, v[96:97] offset:28672
	v_lshl_add_u32 v47, v3, 3, v29
	v_add_u32_e32 v3, 0x1c00, v2
	v_add_u32_e32 v2, 0x1e00, v2
	v_ashrrev_i32_e32 v3, 4, v3
	v_ashrrev_i32_e32 v2, 4, v2
	v_lshl_add_u32 v49, v3, 3, v29
	v_lshl_add_u32 v29, v2, 3, v29
	v_mov_b32_e32 v2, v35
	v_mul_f32_e32 v3, v22, v2
	v_mul_f32_e32 v2, v23, v2
	v_fma_f32 v60, v22, v34, -v2
	v_fma_f32 v61, v23, v34, v3
	v_mov_b32_e32 v2, v31

; __device__ __forceinline__ float2 cmul(float2 a, float2 b) { return make_float2(a.x * b.x - a.y * b.y, a.x * b.y + a.y * b.x); }
; template <int LR, bool INV>
; __device__ __forceinline__ void fft_stages(float2 (&x)[1 << LR], const int r, const int s) {
;     ...
;     for (int m = 0; m < R; ++m) {
;       if (m & hl) continue;
;       const int k = m & (hl - 1); const int j = k * (8 / hl);
;       const float2 wc = make_float2(c16(j), INV ? s16(j) : -s16(j));
;       const float2 tw = cmul(wb, wc);
;       if (!INV) { const float2 p = x[m], q = x[m + hl]; x[m] = make_float2(p.x + q.x, p.y + q.y); x[m + hl] = cmul(make_float2(p.x - q.x, p.y - q.y), tw); }
;       else { const float2 p = x[m], q = cmul(x[m + hl], tw); x[m] = make_float2(p.x + q.x, p.y + q.y); x[m + hl] = make_float2(p.x - q.x, p.y - q.y); }
;     }
	v_mul_f32_e32 v3, v24, v2
	v_mul_f32_e32 v2, v25, v2
	v_fma_f32 v22, v24, v30, -v2
	v_fma_f32 v23, v25, v30, v3
	v_mov_b32_e32 v2, v27

; __device__ __forceinline__ float2 cmul(float2 a, float2 b) { return make_float2(a.x * b.x - a.y * b.y, a.x * b.y + a.y * b.x); }
; template <int LR, bool INV>
; __device__ __forceinline__ void fft_stages(float2 (&x)[1 << LR], const int r, const int s) {
;     ...
;     for (int m = 0; m < R; ++m) {
;       if (m & hl) continue;
;       const int k = m & (hl - 1); const int j = k * (8 / hl);
;       const float2 wc = make_float2(c16(j), INV ? s16(j) : -s16(j));
;       const float2 tw = cmul(wb, wc);
;       if (!INV) { const float2 p = x[m], q = x[m + hl]; x[m] = make_float2(p.x + q.x, p.y + q.y); x[m + hl] = cmul(make_float2(p.x - q.x, p.y - q.y), tw); }
;       else { const float2 p = x[m], q = cmul(x[m + hl], tw); x[m] = make_float2(p.x + q.x, p.y + q.y); x[m + hl] = make_float2(p.x - q.x, p.y - q.y); }
;     }
	v_mul_f32_e32 v3, v14, v2
	v_mul_f32_e32 v2, v15, v2
	v_fma_f32 v24, v14, v26, -v2
	v_fma_f32 v25, v15, v26, v3
	v_mov_b32_e32 v2, v21

; __device__ __forceinline__ float2 cmul(float2 a, float2 b) { return make_float2(a.x * b.x - a.y * b.y, a.x * b.y + a.y * b.x); }
; template <int LR, bool INV>
; __device__ __forceinline__ void fft_stages(float2 (&x)[1 << LR], const int r, const int s) {
;     ...
;     for (int m = 0; m < R; ++m) {
;       if (m & hl) continue;
;       const int k = m & (hl - 1); const int j = k * (8 / hl);
;       const float2 wc = make_float2(c16(j), INV ? s16(j) : -s16(j));
;       const float2 tw = cmul(wb, wc);
;       if (!INV) { const float2 p = x[m], q = x[m + hl]; x[m] = make_float2(p.x + q.x, p.y + q.y); x[m + hl] = cmul(make_float2(p.x - q.x, p.y - q.y), tw); }
;       else { const float2 p = x[m], q = cmul(x[m + hl], tw); x[m] = make_float2(p.x + q.x, p.y + q.y); x[m + hl] = make_float2(p.x - q.x, p.y - q.y); }
;     }
	v_mul_f32_e32 v3, v16, v2
	v_mul_f32_e32 v2, v17, v2
	v_fma_f32 v14, v16, v20, -v2
	v_fma_f32 v15, v17, v20, v3
	v_mov_b32_e32 v2, v19

; __device__ __forceinline__ float2 cmul(float2 a, float2 b) { return make_float2(a.x * b.x - a.y * b.y, a.x * b.y + a.y * b.x); }
; template <int LR, bool INV>
; __device__ __forceinline__ void fft_stages(float2 (&x)[1 << LR], const int r, const int s) {
;     ...
;     for (int m = 0; m < R; ++m) {
;       if (m & hl) continue;
;       const int k = m & (hl - 1); const int j = k * (8 / hl);
;       const float2 wc = make_float2(c16(j), INV ? s16(j) : -s16(j));
;       const float2 tw = cmul(wb, wc);
;       if (!INV) { const float2 p = x[m], q = x[m + hl]; x[m] = make_float2(p.x + q.x, p.y + q.y); x[m + hl] = cmul(make_float2(p.x - q.x, p.y - q.y), tw); }
;       else { const float2 p = x[m], q = cmul(x[m + hl], tw); x[m] = make_float2(p.x + q.x, p.y + q.y); x[m + hl] = make_float2(p.x - q.x, p.y - q.y); }
;     }
	v_mul_f32_e32 v3, v6, v2
	v_mul_f32_e32 v2, v7, v2
	v_fma_f32 v16, v6, v18, -v2
	v_fma_f32 v17, v7, v18, v3
	v_mov_b32_e32 v2, v13

; __device__ __forceinline__ float2 cmul(float2 a, float2 b) { return make_float2(a.x * b.x - a.y * b.y, a.x * b.y + a.y * b.x); }
; template <int LR, bool INV>
; __device__ __forceinline__ void fft_stages(float2 (&x)[1 << LR], const int r, const int s) {
;     ...
;     for (int m = 0; m < R; ++m) {
;       if (m & hl) continue;
;       const int k = m & (hl - 1); const int j = k * (8 / hl);
;       const float2 wc = make_float2(c16(j), INV ? s16(j) : -s16(j));
;       const float2 tw = cmul(wb, wc);
;       if (!INV) { const float2 p = x[m], q = x[m + hl]; x[m] = make_float2(p.x + q.x, p.y + q.y); x[m + hl] = cmul(make_float2(p.x - q.x, p.y - q.y), tw); }
;       else { const float2 p = x[m], q = cmul(x[m + hl], tw); x[m] = make_float2(p.x + q.x, p.y + q.y); x[m + hl] = make_float2(p.x - q.x, p.y - q.y); }
;     }
	v_mul_f32_e32 v3, v54, v2
	v_mul_f32_e32 v2, v55, v2
	v_fma_f32 v6, v54, v12, -v2
	v_fma_f32 v7, v55, v12, v3
	v_mov_b32_e32 v2, v11

; __device__ __forceinline__ float2 cmul(float2 a, float2 b) { return make_float2(a.x * b.x - a.y * b.y, a.x * b.y + a.y * b.x); }
; template <int LR, bool INV>
; __device__ __forceinline__ void fft_stages(float2 (&x)[1 << LR], const int r, const int s) {
;     ...
;     for (int m = 0; m < R; ++m) {
;       if (m & hl) continue;
;       const int k = m & (hl - 1); const int j = k * (8 / hl);
;       const float2 wc = make_float2(c16(j), INV ? s16(j) : -s16(j));
;       const float2 tw = cmul(wb, wc);
;       if (!INV) { const float2 p = x[m], q = x[m + hl]; x[m] = make_float2(p.x + q.x, p.y + q.y); x[m + hl] = cmul(make_float2(p.x - q.x, p.y - q.y), tw); }
;       else { const float2 p = x[m], q = cmul(x[m + hl], tw); x[m] = make_float2(p.x + q.x, p.y + q.y); x[m + hl] = make_float2(p.x - q.x, p.y - q.y); }
;     }
	v_mul_f32_e32 v3, v4, v2
	v_mul_f32_e32 v2, v5, v2
	v_fma_f32 v12, v4, v10, -v2
	v_fma_f32 v13, v5, v10, v3
	v_mov_b32_e32 v2, v9

; __device__ __forceinline__ float2 cmul(float2 a, float2 b) { return make_float2(a.x * b.x - a.y * b.y, a.x * b.y + a.y * b.x); }
; template <int LR, bool INV>
; __device__ __forceinline__ void fft_stages(float2 (&x)[1 << LR], const int r, const int s) {
;     ...
;     for (int m = 0; m < R; ++m) {
;       if (m & hl) continue;
;       const int k = m & (hl - 1); const int j = k * (8 / hl);
;       const float2 wc = make_float2(c16(j), INV ? s16(j) : -s16(j));
;       const float2 tw = cmul(wb, wc);
;       if (!INV) { const float2 p = x[m], q = x[m + hl]; x[m] = make_float2(p.x + q.x, p.y + q.y); x[m + hl] = cmul(make_float2(p.x - q.x, p.y - q.y), tw); }
;       else { const float2 p = x[m], q = cmul(x[m + hl], tw); x[m] = make_float2(p.x + q.x, p.y + q.y); x[m + hl] = make_float2(p.x - q.x, p.y - q.y); }
;     }
	v_mul_f32_e32 v3, v52, v2
	v_mul_f32_e32 v2, v53, v2
	v_fma_f32 v4, v52, v8, -v2
	v_fma_f32 v5, v53, v8, v3

; __device__ __forceinline__ float2 cmul(float2 a, float2 b) { return make_float2(a.x * b.x - a.y * b.y, a.x * b.y + a.y * b.x); }
; template <int LR, bool INV>
; __device__ __forceinline__ void fft_stages(float2 (&x)[1 << LR], const int r, const int s) {
;     ...
;     for (int m = 0; m < R; ++m) {
;       if (m & hl) continue;
;       const int k = m & (hl - 1); const int j = k * (8 / hl);
;       const float2 wc = make_float2(c16(j), INV ? s16(j) : -s16(j));
;       const float2 tw = cmul(wb, wc);
;       if (!INV) { const float2 p = x[m], q = x[m + hl]; x[m] = make_float2(p.x + q.x, p.y + q.y); x[m + hl] = cmul(make_float2(p.x - q.x, p.y - q.y), tw); }
;       else { const float2 p = x[m], q = cmul(x[m + hl], tw); x[m] = make_float2(p.x + q.x, p.y + q.y); x[m + hl] = make_float2(p.x - q.x, p.y - q.y); }
;     }
	v_sub_f32_e32 v2, v60, v16
	v_sub_f32_e32 v3, v61, v17
	v_mul_f32_e32 v8, v50, v2
	v_mul_f32_e32 v9, v50, v3
	v_fma_f32 v10, v48, v2, -v9
	v_fma_f32 v11, v48, v3, v8

; __device__ __forceinline__ float2 cmul(float2 a, float2 b) { return make_float2(a.x * b.x - a.y * b.y, a.x * b.y + a.y * b.x); }
; template <int LR, bool INV>
; __device__ __forceinline__ void fft_stages(float2 (&x)[1 << LR], const int r, const int s) {
;     ...
;     for (int m = 0; m < R; ++m) {
;       if (m & hl) continue;
;       const int k = m & (hl - 1); const int j = k * (8 / hl);
;       const float2 wc = make_float2(c16(j), INV ? s16(j) : -s16(j));
;       const float2 tw = cmul(wb, wc);
;       if (!INV) { const float2 p = x[m], q = x[m + hl]; x[m] = make_float2(p.x + q.x, p.y + q.y); x[m + hl] = cmul(make_float2(p.x - q.x, p.y - q.y), tw); }
;       else { const float2 p = x[m], q = cmul(x[m + hl], tw); x[m] = make_float2(p.x + q.x, p.y + q.y); x[m + hl] = make_float2(p.x - q.x, p.y - q.y); }
;     }
	v_sub_f32_e32 v2, v22, v6
	v_sub_f32_e32 v3, v23, v7
	v_add_f32_e32 v6, v22, v6
	v_add_f32_e32 v7, v23, v7
	v_mul_f32_e32 v8, v78, v2
	v_mul_f32_e32 v9, v79, v3
	v_fma_f32 v18, v56, v2, -v9
	v_fma_f32 v19, v56, v3, v8

; __device__ __forceinline__ float2 cmul(float2 a, float2 b) { return make_float2(a.x * b.x - a.y * b.y, a.x * b.y + a.y * b.x); }
; template <int LR, bool INV>
; __device__ __forceinline__ void fft_stages(float2 (&x)[1 << LR], const int r, const int s) {
;     ...
;     for (int m = 0; m < R; ++m) {
;       if (m & hl) continue;
;       const int k = m & (hl - 1); const int j = k * (8 / hl);
;       const float2 wc = make_float2(c16(j), INV ? s16(j) : -s16(j));
;       const float2 tw = cmul(wb, wc);
;       if (!INV) { const float2 p = x[m], q = x[m + hl]; x[m] = make_float2(p.x + q.x, p.y + q.y); x[m + hl] = cmul(make_float2(p.x - q.x, p.y - q.y), tw); }
;       else { const float2 p = x[m], q = cmul(x[m + hl], tw); x[m] = make_float2(p.x + q.x, p.y + q.y); x[m + hl] = make_float2(p.x - q.x, p.y - q.y); }
;     }
	v_sub_f32_e32 v2, v24, v12
	v_sub_f32_e32 v3, v25, v13
	v_mul_f32_e32 v8, v46, v2
	v_mul_f32_e32 v9, v46, v3
	v_fma_f32 v20, v44, v2, -v9
	v_fma_f32 v21, v44, v3, v8

; __device__ __forceinline__ float2 cmul(float2 a, float2 b) { return make_float2(a.x * b.x - a.y * b.y, a.x * b.y + a.y * b.x); }
; template <int LR, bool INV>
; __device__ __forceinline__ void fft_stages(float2 (&x)[1 << LR], const int r, const int s) {
;     ...
;     for (int m = 0; m < R; ++m) {
;       if (m & hl) continue;
;       const int k = m & (hl - 1); const int j = k * (8 / hl);
;       const float2 wc = make_float2(c16(j), INV ? s16(j) : -s16(j));
;       const float2 tw = cmul(wb, wc);
;       if (!INV) { const float2 p = x[m], q = x[m + hl]; x[m] = make_float2(p.x + q.x, p.y + q.y); x[m + hl] = cmul(make_float2(p.x - q.x, p.y - q.y), tw); }
;       else { const float2 p = x[m], q = cmul(x[m + hl], tw); x[m] = make_float2(p.x + q.x, p.y + q.y); x[m + hl] = make_float2(p.x - q.x, p.y - q.y); }
;     }
	v_sub_f32_e32 v2, v14, v4
	v_sub_f32_e32 v3, v15, v5
	v_add_f32_e32 v4, v14, v4
	v_add_f32_e32 v5, v15, v5
	v_mul_f32_e32 v8, v82, v2
	v_mul_f32_e32 v9, v82, v3
	v_fma_f32 v26, v58, v2, -v9
	v_fma_f32 v27, v59, v3, v8

; __device__ __forceinline__ float2 cmul(float2 a, float2 b) { return make_float2(a.x * b.x - a.y * b.y, a.x * b.y + a.y * b.x); }
; template <int LR, bool INV>
; __device__ __forceinline__ void fft_stages(float2 (&x)[1 << LR], const int r, const int s) {
;     ...
;     for (int m = 0; m < R; ++m) {
;       if (m & hl) continue;
;       const int k = m & (hl - 1); const int j = k * (8 / hl);
;       const float2 wc = make_float2(c16(j), INV ? s16(j) : -s16(j));
;       const float2 tw = cmul(wb, wc);
;       if (!INV) { const float2 p = x[m], q = x[m + hl]; x[m] = make_float2(p.x + q.x, p.y + q.y); x[m + hl] = cmul(make_float2(p.x - q.x, p.y - q.y), tw); }
;       else { const float2 p = x[m], q = cmul(x[m + hl], tw); x[m] = make_float2(p.x + q.x, p.y + q.y); x[m + hl] = make_float2(p.x - q.x, p.y - q.y); }
;     }
	v_sub_f32_e32 v2, v10, v20
	v_sub_f32_e32 v3, v11, v21
	v_mul_f32_e32 v8, v42, v2
	v_mul_f32_e32 v9, v42, v3
	v_fma_f32 v30, v36, v2, -v9
	v_fma_f32 v31, v36, v3, v8

; __device__ __forceinline__ float2 cmul(float2 a, float2 b) { return make_float2(a.x * b.x - a.y * b.y, a.x * b.y + a.y * b.x); }
; template <int LR, bool INV>
; __device__ __forceinline__ void fft_stages(float2 (&x)[1 << LR], const int r, const int s) {
;     ...
;     for (int m = 0; m < R; ++m) {
;       if (m & hl) continue;
;       const int k = m & (hl - 1); const int j = k * (8 / hl);
;       const float2 wc = make_float2(c16(j), INV ? s16(j) : -s16(j));
;       const float2 tw = cmul(wb, wc);
;       if (!INV) { const float2 p = x[m], q = x[m + hl]; x[m] = make_float2(p.x + q.x, p.y + q.y); x[m + hl] = cmul(make_float2(p.x - q.x, p.y - q.y), tw); }
;       else { const float2 p = x[m], q = cmul(x[m + hl], tw); x[m] = make_float2(p.x + q.x, p.y + q.y); x[m + hl] = make_float2(p.x - q.x, p.y - q.y); }
;     }
	v_sub_f32_e32 v2, v18, v26
	v_sub_f32_e32 v3, v19, v27
	v_mul_f32_e32 v8, v40, v2
	v_mul_f32_e32 v9, v40, v3
	v_fma_f32 v34, v38, v2, -v9
	v_fma_f32 v35, v38, v3, v8

; __device__ __forceinline__ float2 cmul(float2 a, float2 b) { return make_float2(a.x * b.x - a.y * b.y, a.x * b.y + a.y * b.x); }
; template <int LR, bool INV>
; __device__ __forceinline__ void fft_stages(float2 (&x)[1 << LR], const int r, const int s) {
;     ...
;     for (int m = 0; m < R; ++m) {
;       if (m & hl) continue;
;       const int k = m & (hl - 1); const int j = k * (8 / hl);
;       const float2 wc = make_float2(c16(j), INV ? s16(j) : -s16(j));
;       const float2 tw = cmul(wb, wc);
;       if (!INV) { const float2 p = x[m], q = x[m + hl]; x[m] = make_float2(p.x + q.x, p.y + q.y); x[m + hl] = cmul(make_float2(p.x - q.x, p.y - q.y), tw); }
;       else { const float2 p = x[m], q = cmul(x[m + hl], tw); x[m] = make_float2(p.x + q.x, p.y + q.y); x[m + hl] = make_float2(p.x - q.x, p.y - q.y); }
;     }
	v_sub_f32_e32 v2, v30, v34
	v_sub_f32_e32 v3, v31, v35
	v_mul_f32_e32 v8, v32, v2
	v_mul_f32_e32 v9, v32, v3
	v_fma_f32 v44, v28, v2, -v9
	v_fma_f32 v45, v28, v3, v8

; __device__ __forceinline__ float2 cmul(float2 a, float2 b) { return make_float2(a.x * b.x - a.y * b.y, a.x * b.y + a.y * b.x); }
; template <int LR, bool INV>
; __device__ __forceinline__ void fft_stages(float2 (&x)[1 << LR], const int r, const int s) {
;     ...
;     for (int m = 0; m < R; ++m) {
;       if (m & hl) continue;
;       const int k = m & (hl - 1); const int j = k * (8 / hl);
;       const float2 wc = make_float2(c16(j), INV ? s16(j) : -s16(j));
;       const float2 tw = cmul(wb, wc);
;       if (!INV) { const float2 p = x[m], q = x[m + hl]; x[m] = make_float2(p.x + q.x, p.y + q.y); x[m + hl] = cmul(make_float2(p.x - q.x, p.y - q.y), tw); }
;       else { const float2 p = x[m], q = cmul(x[m + hl], tw); x[m] = make_float2(p.x + q.x, p.y + q.y); x[m + hl] = make_float2(p.x - q.x, p.y - q.y); }
;     }
	v_add_f32_e32 v2, v60, v16
	v_add_f32_e32 v3, v61, v17
	v_add_f32_e32 v8, v24, v12
	v_add_f32_e32 v9, v25, v13
	v_sub_f32_e32 v12, v2, v8
	v_sub_f32_e32 v13, v3, v9
	v_add_f32_e32 v2, v2, v8
	v_add_f32_e32 v3, v3, v9
	v_mul_f32_e32 v14, v42, v12
	v_mul_f32_e32 v15, v42, v13
	v_fma_f32 v16, v36, v12, -v15
	v_fma_f32 v17, v36, v13, v14

; __device__ __forceinline__ float2 cmul(float2 a, float2 b) { return make_float2(a.x * b.x - a.y * b.y, a.x * b.y + a.y * b.x); }
; template <int LR, bool INV>
; __device__ __forceinline__ void fft_stages(float2 (&x)[1 << LR], const int r, const int s) {
;     ...
;     for (int m = 0; m < R; ++m) {
;       if (m & hl) continue;
;       const int k = m & (hl - 1); const int j = k * (8 / hl);
;       const float2 wc = make_float2(c16(j), INV ? s16(j) : -s16(j));
;       const float2 tw = cmul(wb, wc);
;       if (!INV) { const float2 p = x[m], q = x[m + hl]; x[m] = make_float2(p.x + q.x, p.y + q.y); x[m + hl] = cmul(make_float2(p.x - q.x, p.y - q.y), tw); }
;       else { const float2 p = x[m], q = cmul(x[m + hl], tw); x[m] = make_float2(p.x + q.x, p.y + q.y); x[m + hl] = make_float2(p.x - q.x, p.y - q.y); }
;     }
	v_sub_f32_e32 v12, v6, v4
	v_sub_f32_e32 v13, v7, v5
	v_add_f32_e32 v4, v6, v4
	v_add_f32_e32 v5, v7, v5
	v_mul_f32_e32 v14, v40, v12
	v_mul_f32_e32 v15, v40, v13
	v_fma_f32 v22, v38, v12, -v15
	v_fma_f32 v23, v38, v13, v14

; __device__ __forceinline__ float2 cmul(float2 a, float2 b) { return make_float2(a.x * b.x - a.y * b.y, a.x * b.y + a.y * b.x); }
; template <int LR, bool INV>
; __device__ __forceinline__ void fft_stages(float2 (&x)[1 << LR], const int r, const int s) {
;     ...
;     for (int m = 0; m < R; ++m) {
;       if (m & hl) continue;
;       const int k = m & (hl - 1); const int j = k * (8 / hl);
;       const float2 wc = make_float2(c16(j), INV ? s16(j) : -s16(j));
;       const float2 tw = cmul(wb, wc);
;       if (!INV) { const float2 p = x[m], q = x[m + hl]; x[m] = make_float2(p.x + q.x, p.y + q.y); x[m + hl] = cmul(make_float2(p.x - q.x, p.y - q.y), tw); }
;       else { const float2 p = x[m], q = cmul(x[m + hl], tw); x[m] = make_float2(p.x + q.x, p.y + q.y); x[m + hl] = make_float2(p.x - q.x, p.y - q.y); }
;     }
	v_sub_f32_e32 v12, v16, v22
	v_sub_f32_e32 v13, v17, v23
	v_sub_f32_e32 v6, v2, v4
	v_sub_f32_e32 v7, v3, v5
	v_mul_f32_e32 v14, v32, v12
	v_mul_f32_e32 v15, v32, v13
	v_fma_f32 v24, v28, v12, -v15
	v_fma_f32 v25, v28, v13, v14
	v_mul_f32_e32 v8, v32, v6
	v_mul_f32_e32 v9, v32, v7

; __device__ __forceinline__ float2 cmul(float2 a, float2 b) { return make_float2(a.x * b.x - a.y * b.y, a.x * b.y + a.y * b.x); }
; template <int LR, bool INV>
; __device__ __forceinline__ void fft_stages(float2 (&x)[1 << LR], const int r, const int s) {
;     ...
;     for (int m = 0; m < R; ++m) {
;       if (m & hl) continue;
;       const int k = m & (hl - 1); const int j = k * (8 / hl);
;       const float2 wc = make_float2(c16(j), INV ? s16(j) : -s16(j));
;       const float2 tw = cmul(wb, wc);
;       if (!INV) { const float2 p = x[m], q = x[m + hl]; x[m] = make_float2(p.x + q.x, p.y + q.y); x[m + hl] = cmul(make_float2(p.x - q.x, p.y - q.y), tw); }
;       else { const float2 p = x[m], q = cmul(x[m + hl], tw); x[m] = make_float2(p.x + q.x, p.y + q.y); x[m + hl] = make_float2(p.x - q.x, p.y - q.y); }
;     }
	v_fma_f32 v12, v28, v6, -v9
	v_fma_f32 v13, v28, v7, v8
	v_add_f32_e32 v2, v2, v4
	v_add_f32_e32 v3, v3, v5

;     static __device__ __forceinline__ float sl(float g, float up) { return g * __builtin_amdgcn_rcpf(1.0f + __builtin_amdgcn_exp2f(-1.4426950408889634f * g)) * up; }
; __device__ __forceinline__ float bfl(unsigned w) { return __uint_as_float(w << 16); }
; __device__ __forceinline__ float2 cmul(float2 a, float2 b) { return make_float2(a.x * b.x - a.y * b.y, a.x * b.y + a.y * b.x); }
; #define tid ltid()
; template <int LR, bool INV>
; __device__ __forceinline__ void fft_stages(float2 (&x)[1 << LR], const int r, const int s) {
;     ...
;     for (int m = 0; m < R; ++m) {
;       if (m & hl) continue;
;       const int k = m & (hl - 1); const int j = k * (8 / hl);
;       const float2 wc = make_float2(c16(j), INV ? s16(j) : -s16(j));
;       const float2 tw = cmul(wb, wc);
;       if (!INV) { const float2 p = x[m], q = x[m + hl]; x[m] = make_float2(p.x + q.x, p.y + q.y); x[m + hl] = cmul(make_float2(p.x - q.x, p.y - q.y), tw); }
;       else { const float2 p = x[m], q = cmul(x[m + hl], tw); x[m] = make_float2(p.x + q.x, p.y + q.y); x[m + hl] = make_float2(p.x - q.x, p.y - q.y); }
;     }
;   }
; }
; template <int LR, bool INV>
; __device__ __forceinline__ void fft_pass(float2* X, const int N, const int sl, const int tid) {
;   constexpr int R = 1 << LR;
;   const int s = 1 << sl;
;   for (int g = tid; g < (N >> LR); g += NTHR) {
;     const int r = g & (s - 1);
;     const int i0 = ((g >> sl) << (sl + LR)) + r;
;     float2 x[R];
; #pragma unroll
;     for (int m = 0; m < R; ++m) x[m] = X[PIDX(i0 + (m << sl))];
;     fft_stages<LR, INV>(x, r, s);
; #pragma unroll
;     for (int m = 0; m < R; ++m) X[PIDX(i0 + (m << sl))] = x[m];
;   }
;   __syncthreads();
; }
; template <int LR>
; __device__ __forceinline__ void fft_first(float2* X, const bf16* __restrict__ u0, const bf16* __restrict__ u1, const int tid) {
;   constexpr int R = 1 << LR;
;   float2 x[R];
; #pragma unroll
;   for (int m = 0; m < R / 2; ++m) x[m] = make_float2(bfl(u0[tid + 512 * m]), bfl(u1[tid + 512 * m]));
; #pragma unroll
;   for (int m = R / 2; m < R; ++m) x[m] = make_float2(0.f, 0.f);
;   fft_stages<LR, false>(x, tid, 512);
; #pragma unroll
;   for (int m = 0; m < R; ++m) X[PIDX(tid + 512 * m)] = x[m];
;   __syncthreads();
; }
	ds_write_b64 v33, v[2:3] offset:32768
	ds_write_b64 v37, v[12:13] offset:36864
	v_add_f32_e32 v2, v16, v22
	v_add_f32_e32 v3, v17, v23
	ds_write_b64 v39, v[2:3] offset:40960
	ds_write_b64 v41, v[24:25] offset:45056
	v_add_f32_e32 v2, v10, v20
	v_add_f32_e32 v3, v11, v21
	v_add_f32_e32 v4, v18, v26
	v_add_f32_e32 v5, v19, v27
	v_sub_f32_e32 v6, v2, v4
	v_sub_f32_e32 v7, v3, v5
	v_add_f32_e32 v2, v2, v4
	v_add_f32_e32 v3, v3, v5
	v_mul_f32_e32 v8, v32, v6
	v_mul_f32_e32 v9, v32, v7
	v_fma_f32 v10, v28, v6, -v9
	v_fma_f32 v7, v28, v7, v8
	v_mov_b32_e32 v11, v7
	ds_write_b64 v43, v[2:3] offset:49152
	ds_write_b64 v47, v[10:11] offset:53248
	v_add_f32_e32 v2, v30, v34
	v_add_f32_e32 v3, v31, v35
	ds_write_b64 v49, v[2:3] offset:57344
	ds_write_b64 v29, v[44:45] offset:61440
	s_waitcnt lgkmcnt(0)
	s_barrier

;     static __device__ __forceinline__ float sl(float g, float up) { return g * __builtin_amdgcn_rcpf(1.0f + __builtin_amdgcn_exp2f(-1.4426950408889634f * g)) * up; }
; #define tid ltid()
; template <int LR, bool INV>
; __device__ __forceinline__ void fft_pass(float2* X, const int N, const int sl, const int tid) {
;     ...
;   for (int g = tid; g < (N >> LR); g += NTHR) {
;     const int r = g & (s - 1);
;     const int i0 = ((g >> sl) << (sl + LR)) + r;
;     float2 x[R];
; #pragma unroll
;     for (int m = 0; m < R; ++m) x[m] = X[PIDX(i0 + (m << sl))];
.LBB0_675:
	v_and_or_b32 v33, v32, s53, v31
	v_ashrrev_i32_e32 v34, 4, v33
	v_lshlrev_b32_e32 v34, 3, v34
	v_lshlrev_b32_e32 v35, 3, v33
	v_add3_u32 v52, 0, v34, v35


;     static __device__ __forceinline__ float sl(float g, float up) { return g * __builtin_amdgcn_rcpf(1.0f + __builtin_amdgcn_exp2f(-1.4426950408889634f * g)) * up; }
; template <int LR, bool INV>
; __device__ __forceinline__ void fft_pass(float2* X, const int N, const int sl, const int tid) {
;     ...
;     const int i0 = ((g >> sl) << (sl + LR)) + r;
;     float2 x[R];
; #pragma unroll
;     for (int m = 0; m < R; ++m) x[m] = X[PIDX(i0 + (m << sl))];
	v_or_b32_e32 v33, 0x1c0, v33

;     static __device__ __forceinline__ float sl(float g, float up) { return g * __builtin_amdgcn_rcpf(1.0f + __builtin_amdgcn_exp2f(-1.4426950408889634f * g)) * up; }
; template <int LR, bool INV>
; __device__ __forceinline__ void fft_pass(float2* X, const int N, const int sl, const int tid) {
;     ...
;     for (int m = 0; m < R; ++m) x[m] = X[PIDX(i0 + (m << sl))];
	v_ashrrev_i32_e32 v33, 4, v33

;     static __device__ __forceinline__ float sl(float g, float up) { return g * __builtin_amdgcn_rcpf(1.0f + __builtin_amdgcn_exp2f(-1.4426950408889634f * g)) * up; }
; template <int LR, bool INV>
; __device__ __forceinline__ void fft_pass(float2* X, const int N, const int sl, const int tid) {
;     ...
;     for (int m = 0; m < R; ++m) x[m] = X[PIDX(i0 + (m << sl))];
	v_lshlrev_b32_e32 v33, 3, v33

;     static __device__ __forceinline__ float sl(float g, float up) { return g * __builtin_amdgcn_rcpf(1.0f + __builtin_amdgcn_exp2f(-1.4426950408889634f * g)) * up; }
; __device__ __forceinline__ float2 cmul(float2 a, float2 b) { return make_float2(a.x * b.x - a.y * b.y, a.x * b.y + a.y * b.x); }
; #define tid ltid()
; template <int LR, bool INV>
; __device__ __forceinline__ void fft_stages(float2 (&x)[1 << LR], const int r, const int s) {
;     ...
;   for (int st = 0; st < LR; ++st) {
;     const int hl = INV ? (1 << st) : (R >> (st + 1));
;     const float fb = (float)r * (0.5f / (float)(hl * s));
;     const float2 wb = make_float2(__builtin_amdgcn_cosf(fb), INV ? __builtin_amdgcn_sinf(fb) : -__builtin_amdgcn_sinf(fb));
; #pragma unroll
;     for (int m = 0; m < R; ++m) {
;       if (m & hl) continue;
;       const int k = m & (hl - 1); const int j = k * (8 / hl);
;       const float2 wc = make_float2(c16(j), INV ? s16(j) : -s16(j));
;       const float2 tw = cmul(wb, wc);
;       if (!INV) { const float2 p = x[m], q = x[m + hl]; x[m] = make_float2(p.x + q.x, p.y + q.y); x[m + hl] = cmul(make_float2(p.x - q.x, p.y - q.y), tw); }
;       else { const float2 p = x[m], q = cmul(x[m + hl], tw); x[m] = make_float2(p.x + q.x, p.y + q.y); x[m + hl] = make_float2(p.x - q.x, p.y - q.y); }
;     }
; template <int LR, bool INV>
; __device__ __forceinline__ void fft_pass(float2* X, const int N, const int sl, const int tid) {
;     ...
;   for (int g = tid; g < (N >> LR); g += NTHR) {
;     const int r = g & (s - 1);
;     const int i0 = ((g >> sl) << (sl + LR)) + r;
;     float2 x[R];
; #pragma unroll
;     for (int m = 0; m < R; ++m) x[m] = X[PIDX(i0 + (m << sl))];
;     fft_stages<LR, INV>(x, r, s);
; #pragma unroll
;     for (int m = 0; m < R; ++m) X[PIDX(i0 + (m << sl))] = x[m];
	v_add3_u32 v33, 0, v33, v35
	ds_read_b64 v[34:35], v52
	ds_read_b64 v[36:37], v52 offset:544
	ds_read_b64 v[38:39], v52 offset:1088
	ds_read_b64 v[40:41], v52 offset:1632
	ds_read_b64 v[42:43], v52 offset:2176
	ds_read_b64 v[44:45], v52 offset:2720
	ds_read_b64 v[46:47], v52 offset:3264
	ds_read_b64 v[48:49], v52 offset:3808
	v_add_u32_e32 v30, 0x200, v30
	s_waitcnt lgkmcnt(3)
	v_add_f32_e32 v50, v34, v42
	v_add_f32_e32 v51, v35, v43
	v_sub_f32_e32 v34, v34, v42
	v_sub_f32_e32 v35, v35, v43
	s_waitcnt lgkmcnt(2)
	v_add_f32_e32 v42, v36, v44
	v_add_f32_e32 v43, v37, v45
	v_sub_f32_e32 v36, v36, v44
	v_sub_f32_e32 v37, v37, v45
	s_waitcnt lgkmcnt(1)
	v_add_f32_e32 v44, v38, v46
	v_add_f32_e32 v45, v39, v47
	v_sub_f32_e32 v38, v38, v46
	v_sub_f32_e32 v39, v39, v47
	s_waitcnt lgkmcnt(0)
	v_add_f32_e32 v46, v40, v48
	v_add_f32_e32 v47, v41, v49
	v_sub_f32_e32 v40, v40, v48
	v_sub_f32_e32 v41, v41, v49
	v_add_f32_e32 v48, v50, v44
	v_add_f32_e32 v49, v51, v45
	v_sub_f32_e32 v44, v50, v44
	v_sub_f32_e32 v45, v51, v45
	v_add_f32_e32 v50, v42, v46
	v_add_f32_e32 v51, v43, v47
	v_sub_f32_e32 v42, v42, v46
	v_sub_f32_e32 v43, v43, v47
	v_add_f32_e32 v46, v48, v50
	v_add_f32_e32 v47, v49, v51
	v_sub_f32_e32 v48, v48, v50
	v_sub_f32_e32 v49, v49, v51
	ds_write_b64 v52, v[46:47]
	v_mul_f32_e32 v46, v16, v49
	v_mul_f32_e32 v47, v17, v49
	v_cmp_le_i32_e32 vcc, s21, v30
	v_fma_f32 v50, v14, v48, -v46
	v_fma_f32 v51, v15, v48, v47
	v_add_u32_e32 v32, 0x1000, v32

; __device__ __forceinline__ float2 cmul(float2 a, float2 b) { return make_float2(a.x * b.x - a.y * b.y, a.x * b.y + a.y * b.x); }
; template <int LR, bool INV>
; __device__ __forceinline__ void fft_stages(float2 (&x)[1 << LR], const int r, const int s) {
;     ...
;     for (int m = 0; m < R; ++m) {
;       if (m & hl) continue;
;       const int k = m & (hl - 1); const int j = k * (8 / hl);
;       const float2 wc = make_float2(c16(j), INV ? s16(j) : -s16(j));
;       const float2 tw = cmul(wb, wc);
;       if (!INV) { const float2 p = x[m], q = x[m + hl]; x[m] = make_float2(p.x + q.x, p.y + q.y); x[m + hl] = cmul(make_float2(p.x - q.x, p.y - q.y), tw); }
;       else { const float2 p = x[m], q = cmul(x[m + hl], tw); x[m] = make_float2(p.x + q.x, p.y + q.y); x[m + hl] = make_float2(p.x - q.x, p.y - q.y); }
;     }
	v_mul_f32_e32 v46, v18, v45
	v_mul_f32_e32 v47, v19, v45
	ds_write_b64 v52, v[50:51] offset:544
	v_fma_f32 v48, v10, v44, -v46
	v_fma_f32 v49, v11, v44, v47
	s_or_b64 s[14:15], vcc, s[14:15]

; __device__ __forceinline__ float2 cmul(float2 a, float2 b) { return make_float2(a.x * b.x - a.y * b.y, a.x * b.y + a.y * b.x); }
; template <int LR, bool INV>
; __device__ __forceinline__ void fft_stages(float2 (&x)[1 << LR], const int r, const int s) {
;     ...
;     for (int m = 0; m < R; ++m) {
;       if (m & hl) continue;
;       const int k = m & (hl - 1); const int j = k * (8 / hl);
;       const float2 wc = make_float2(c16(j), INV ? s16(j) : -s16(j));
;       const float2 tw = cmul(wb, wc);
;       if (!INV) { const float2 p = x[m], q = x[m + hl]; x[m] = make_float2(p.x + q.x, p.y + q.y); x[m + hl] = cmul(make_float2(p.x - q.x, p.y - q.y), tw); }
;       else { const float2 p = x[m], q = cmul(x[m + hl], tw); x[m] = make_float2(p.x + q.x, p.y + q.y); x[m + hl] = make_float2(p.x - q.x, p.y - q.y); }
;     }
	v_mul_f32_e32 v44, v20, v43
	v_mul_f32_e32 v45, v21, v43
	v_fma_f32 v46, v12, v42, -v44
	v_fma_f32 v47, v13, v42, v45

;     static __device__ __forceinline__ float sl(float g, float up) { return g * __builtin_amdgcn_rcpf(1.0f + __builtin_amdgcn_exp2f(-1.4426950408889634f * g)) * up; }
; __device__ __forceinline__ float2 cmul(float2 a, float2 b) { return make_float2(a.x * b.x - a.y * b.y, a.x * b.y + a.y * b.x); }
; template <int LR, bool INV>
; __device__ __forceinline__ void fft_stages(float2 (&x)[1 << LR], const int r, const int s) {
;     ...
;     for (int m = 0; m < R; ++m) {
;       if (m & hl) continue;
;       const int k = m & (hl - 1); const int j = k * (8 / hl);
;       const float2 wc = make_float2(c16(j), INV ? s16(j) : -s16(j));
;       const float2 tw = cmul(wb, wc);
;       if (!INV) { const float2 p = x[m], q = x[m + hl]; x[m] = make_float2(p.x + q.x, p.y + q.y); x[m + hl] = cmul(make_float2(p.x - q.x, p.y - q.y), tw); }
;       else { const float2 p = x[m], q = cmul(x[m + hl], tw); x[m] = make_float2(p.x + q.x, p.y + q.y); x[m + hl] = make_float2(p.x - q.x, p.y - q.y); }
;     }
; template <int LR, bool INV>
; __device__ __forceinline__ void fft_pass(float2* X, const int N, const int sl, const int tid) {
;     ...
;     for (int m = 0; m < R; ++m) X[PIDX(i0 + (m << sl))] = x[m];
	v_add_f32_e32 v42, v48, v46
	v_add_f32_e32 v43, v49, v47
	v_sub_f32_e32 v44, v48, v46
	v_sub_f32_e32 v45, v49, v47
	ds_write_b64 v52, v[42:43] offset:1088
	v_mul_f32_e32 v42, v16, v45
	v_mul_f32_e32 v43, v17, v45
	v_fma_f32 v46, v14, v44, -v42
	v_fma_f32 v47, v15, v44, v43

;     static __device__ __forceinline__ float sl(float g, float up) { return g * __builtin_amdgcn_rcpf(1.0f + __builtin_amdgcn_exp2f(-1.4426950408889634f * g)) * up; }
; __device__ __forceinline__ float2 cmul(float2 a, float2 b) { return make_float2(a.x * b.x - a.y * b.y, a.x * b.y + a.y * b.x); }
; template <int LR, bool INV>
; __device__ __forceinline__ void fft_stages(float2 (&x)[1 << LR], const int r, const int s) {
;     ...
;     for (int m = 0; m < R; ++m) {
;       if (m & hl) continue;
;       const int k = m & (hl - 1); const int j = k * (8 / hl);
;       const float2 wc = make_float2(c16(j), INV ? s16(j) : -s16(j));
;       const float2 tw = cmul(wb, wc);
;       if (!INV) { const float2 p = x[m], q = x[m + hl]; x[m] = make_float2(p.x + q.x, p.y + q.y); x[m + hl] = cmul(make_float2(p.x - q.x, p.y - q.y), tw); }
;       else { const float2 p = x[m], q = cmul(x[m + hl], tw); x[m] = make_float2(p.x + q.x, p.y + q.y); x[m + hl] = make_float2(p.x - q.x, p.y - q.y); }
;     }
; template <int LR, bool INV>
; __device__ __forceinline__ void fft_pass(float2* X, const int N, const int sl, const int tid) {
;     ...
;     for (int m = 0; m < R; ++m) X[PIDX(i0 + (m << sl))] = x[m];
	v_mul_f32_e32 v42, v22, v35
	v_mul_f32_e32 v43, v23, v35
	ds_write_b64 v52, v[46:47] offset:1632
	v_fma_f32 v44, v2, v34, -v42
	v_fma_f32 v45, v3, v34, v43

; __device__ __forceinline__ float2 cmul(float2 a, float2 b) { return make_float2(a.x * b.x - a.y * b.y, a.x * b.y + a.y * b.x); }
; template <int LR, bool INV>
; __device__ __forceinline__ void fft_stages(float2 (&x)[1 << LR], const int r, const int s) {
;     ...
;     for (int m = 0; m < R; ++m) {
;       if (m & hl) continue;
;       const int k = m & (hl - 1); const int j = k * (8 / hl);
;       const float2 wc = make_float2(c16(j), INV ? s16(j) : -s16(j));
;       const float2 tw = cmul(wb, wc);
;       if (!INV) { const float2 p = x[m], q = x[m + hl]; x[m] = make_float2(p.x + q.x, p.y + q.y); x[m + hl] = cmul(make_float2(p.x - q.x, p.y - q.y), tw); }
;       else { const float2 p = x[m], q = cmul(x[m + hl], tw); x[m] = make_float2(p.x + q.x, p.y + q.y); x[m + hl] = make_float2(p.x - q.x, p.y - q.y); }
;     }
	v_mul_f32_e32 v34, v24, v37
	v_mul_f32_e32 v35, v25, v37
	v_fma_f32 v42, v4, v36, -v34
	v_fma_f32 v43, v5, v36, v35

; __device__ __forceinline__ float2 cmul(float2 a, float2 b) { return make_float2(a.x * b.x - a.y * b.y, a.x * b.y + a.y * b.x); }
; template <int LR, bool INV>
; __device__ __forceinline__ void fft_stages(float2 (&x)[1 << LR], const int r, const int s) {
;     ...
;     for (int m = 0; m < R; ++m) {
;       if (m & hl) continue;
;       const int k = m & (hl - 1); const int j = k * (8 / hl);
;       const float2 wc = make_float2(c16(j), INV ? s16(j) : -s16(j));
;       const float2 tw = cmul(wb, wc);
;       if (!INV) { const float2 p = x[m], q = x[m + hl]; x[m] = make_float2(p.x + q.x, p.y + q.y); x[m + hl] = cmul(make_float2(p.x - q.x, p.y - q.y), tw); }
;       else { const float2 p = x[m], q = cmul(x[m + hl], tw); x[m] = make_float2(p.x + q.x, p.y + q.y); x[m + hl] = make_float2(p.x - q.x, p.y - q.y); }
;     }
	v_mul_f32_e32 v34, v26, v39
	v_mul_f32_e32 v35, v27, v39
	v_fma_f32 v36, v6, v38, -v34
	v_fma_f32 v37, v7, v38, v35

; __device__ __forceinline__ float2 cmul(float2 a, float2 b) { return make_float2(a.x * b.x - a.y * b.y, a.x * b.y + a.y * b.x); }
; template <int LR, bool INV>
; __device__ __forceinline__ void fft_stages(float2 (&x)[1 << LR], const int r, const int s) {
;     ...
;     for (int m = 0; m < R; ++m) {
;       if (m & hl) continue;
;       const int k = m & (hl - 1); const int j = k * (8 / hl);
;       const float2 wc = make_float2(c16(j), INV ? s16(j) : -s16(j));
;       const float2 tw = cmul(wb, wc);
;       if (!INV) { const float2 p = x[m], q = x[m + hl]; x[m] = make_float2(p.x + q.x, p.y + q.y); x[m + hl] = cmul(make_float2(p.x - q.x, p.y - q.y), tw); }
;       else { const float2 p = x[m], q = cmul(x[m + hl], tw); x[m] = make_float2(p.x + q.x, p.y + q.y); x[m + hl] = make_float2(p.x - q.x, p.y - q.y); }
;     }
	v_mul_f32_e32 v34, v28, v41
	v_mul_f32_e32 v35, v29, v41
	v_fma_f32 v38, v8, v40, -v34
	v_fma_f32 v39, v9, v40, v35

;     static __device__ __forceinline__ float sl(float g, float up) { return g * __builtin_amdgcn_rcpf(1.0f + __builtin_amdgcn_exp2f(-1.4426950408889634f * g)) * up; }
; __device__ __forceinline__ float2 cmul(float2 a, float2 b) { return make_float2(a.x * b.x - a.y * b.y, a.x * b.y + a.y * b.x); }
; template <int LR, bool INV>
; __device__ __forceinline__ void fft_stages(float2 (&x)[1 << LR], const int r, const int s) {
;     ...
;     for (int m = 0; m < R; ++m) {
;       if (m & hl) continue;
;       const int k = m & (hl - 1); const int j = k * (8 / hl);
;       const float2 wc = make_float2(c16(j), INV ? s16(j) : -s16(j));
;       const float2 tw = cmul(wb, wc);
;       if (!INV) { const float2 p = x[m], q = x[m + hl]; x[m] = make_float2(p.x + q.x, p.y + q.y); x[m + hl] = cmul(make_float2(p.x - q.x, p.y - q.y), tw); }
;       else { const float2 p = x[m], q = cmul(x[m + hl], tw); x[m] = make_float2(p.x + q.x, p.y + q.y); x[m + hl] = make_float2(p.x - q.x, p.y - q.y); }
;     }
; template <int LR, bool INV>
; __device__ __forceinline__ void fft_pass(float2* X, const int N, const int sl, const int tid) {
;     ...
;     for (int m = 0; m < R; ++m) X[PIDX(i0 + (m << sl))] = x[m];
	v_add_f32_e32 v34, v44, v36
	v_add_f32_e32 v35, v45, v37
	v_add_f32_e32 v40, v42, v38
	v_add_f32_e32 v41, v43, v39
	v_sub_f32_e32 v38, v42, v38
	v_sub_f32_e32 v39, v43, v39
	v_add_f32_e32 v42, v34, v40
	v_add_f32_e32 v43, v35, v41
	v_sub_f32_e32 v34, v34, v40
	v_sub_f32_e32 v35, v35, v41
	v_sub_f32_e32 v36, v44, v36
	v_sub_f32_e32 v37, v45, v37
	v_mul_f32_e32 v40, v16, v35
	v_mul_f32_e32 v41, v17, v35
	ds_write_b64 v52, v[42:43] offset:2176
	v_fma_f32 v42, v14, v34, -v40
	v_fma_f32 v43, v15, v34, v41

;     static __device__ __forceinline__ float sl(float g, float up) { return g * __builtin_amdgcn_rcpf(1.0f + __builtin_amdgcn_exp2f(-1.4426950408889634f * g)) * up; }
; __device__ __forceinline__ float2 cmul(float2 a, float2 b) { return make_float2(a.x * b.x - a.y * b.y, a.x * b.y + a.y * b.x); }
; template <int LR, bool INV>
; __device__ __forceinline__ void fft_stages(float2 (&x)[1 << LR], const int r, const int s) {
;     ...
;     for (int m = 0; m < R; ++m) {
;       if (m & hl) continue;
;       const int k = m & (hl - 1); const int j = k * (8 / hl);
;       const float2 wc = make_float2(c16(j), INV ? s16(j) : -s16(j));
;       const float2 tw = cmul(wb, wc);
;       if (!INV) { const float2 p = x[m], q = x[m + hl]; x[m] = make_float2(p.x + q.x, p.y + q.y); x[m + hl] = cmul(make_float2(p.x - q.x, p.y - q.y), tw); }
;       else { const float2 p = x[m], q = cmul(x[m + hl], tw); x[m] = make_float2(p.x + q.x, p.y + q.y); x[m + hl] = make_float2(p.x - q.x, p.y - q.y); }
;     }
; template <int LR, bool INV>
; __device__ __forceinline__ void fft_pass(float2* X, const int N, const int sl, const int tid) {
;     ...
;     for (int m = 0; m < R; ++m) X[PIDX(i0 + (m << sl))] = x[m];
	v_mul_f32_e32 v34, v18, v37
	v_mul_f32_e32 v35, v19, v37
	ds_write_b64 v52, v[42:43] offset:2720
	v_fma_f32 v40, v10, v36, -v34
	v_fma_f32 v41, v11, v36, v35

; __device__ __forceinline__ float2 cmul(float2 a, float2 b) { return make_float2(a.x * b.x - a.y * b.y, a.x * b.y + a.y * b.x); }
; template <int LR, bool INV>
; __device__ __forceinline__ void fft_stages(float2 (&x)[1 << LR], const int r, const int s) {
;     ...
;     for (int m = 0; m < R; ++m) {
;       if (m & hl) continue;
;       const int k = m & (hl - 1); const int j = k * (8 / hl);
;       const float2 wc = make_float2(c16(j), INV ? s16(j) : -s16(j));
;       const float2 tw = cmul(wb, wc);
;       if (!INV) { const float2 p = x[m], q = x[m + hl]; x[m] = make_float2(p.x + q.x, p.y + q.y); x[m + hl] = cmul(make_float2(p.x - q.x, p.y - q.y), tw); }
;       else { const float2 p = x[m], q = cmul(x[m + hl], tw); x[m] = make_float2(p.x + q.x, p.y + q.y); x[m + hl] = make_float2(p.x - q.x, p.y - q.y); }
;     }
	v_mul_f32_e32 v34, v20, v39
	v_mul_f32_e32 v35, v21, v39
	v_fma_f32 v36, v12, v38, -v34
	v_fma_f32 v37, v13, v38, v35

;     static __device__ __forceinline__ float sl(float g, float up) { return g * __builtin_amdgcn_rcpf(1.0f + __builtin_amdgcn_exp2f(-1.4426950408889634f * g)) * up; }
; __device__ __forceinline__ float2 cmul(float2 a, float2 b) { return make_float2(a.x * b.x - a.y * b.y, a.x * b.y + a.y * b.x); }
; #define tid ltid()
; template <int LR, bool INV>
; __device__ __forceinline__ void fft_stages(float2 (&x)[1 << LR], const int r, const int s) {
;     ...
;     for (int m = 0; m < R; ++m) {
;       if (m & hl) continue;
;       const int k = m & (hl - 1); const int j = k * (8 / hl);
;       const float2 wc = make_float2(c16(j), INV ? s16(j) : -s16(j));
;       const float2 tw = cmul(wb, wc);
;       if (!INV) { const float2 p = x[m], q = x[m + hl]; x[m] = make_float2(p.x + q.x, p.y + q.y); x[m + hl] = cmul(make_float2(p.x - q.x, p.y - q.y), tw); }
;       else { const float2 p = x[m], q = cmul(x[m + hl], tw); x[m] = make_float2(p.x + q.x, p.y + q.y); x[m + hl] = make_float2(p.x - q.x, p.y - q.y); }
;     }
;   }
; }
; template <int LR, bool INV>
; __device__ __forceinline__ void fft_pass(float2* X, const int N, const int sl, const int tid) {
;   constexpr int R = 1 << LR;
;   const int s = 1 << sl;
;   for (int g = tid; g < (N >> LR); g += NTHR) {
;     const int r = g & (s - 1);
;     const int i0 = ((g >> sl) << (sl + LR)) + r;
;     float2 x[R];
; #pragma unroll
;     for (int m = 0; m < R; ++m) x[m] = X[PIDX(i0 + (m << sl))];
;     fft_stages<LR, INV>(x, r, s);
; #pragma unroll
;     for (int m = 0; m < R; ++m) X[PIDX(i0 + (m << sl))] = x[m];
	v_add_f32_e32 v34, v40, v36
	v_add_f32_e32 v35, v41, v37
	v_sub_f32_e32 v36, v40, v36
	v_sub_f32_e32 v37, v41, v37
	ds_write_b64 v52, v[34:35] offset:3264
	v_mul_f32_e32 v34, v16, v37
	v_mul_f32_e32 v35, v17, v37
	v_fma_f32 v38, v14, v36, -v34
	v_fma_f32 v34, v14, v36, v34
	v_fma_f32 v35, v15, v36, v35
	v_mov_b32_e32 v39, v35
	ds_write_b64 v52, v[38:39] offset:3808
	s_andn2_b64 exec, exec, s[14:15]
	s_cbranch_execnz .LBB0_675

;     static __device__ __forceinline__ float sl(float g, float up) { return g * __builtin_amdgcn_rcpf(1.0f + __builtin_amdgcn_exp2f(-1.4426950408889634f * g)) * up; }
; #define tid ltid()
; template <int LR, bool INV>
; __device__ __forceinline__ void fft_pass(float2* X, const int N, const int sl, const int tid) {
;     ...
;   for (int g = tid; g < (N >> LR); g += NTHR) {
;     const int r = g & (s - 1);
;     const int i0 = ((g >> sl) << (sl + LR)) + r;
;     float2 x[R];
; #pragma unroll
;     for (int m = 0; m < R; ++m) x[m] = X[PIDX(i0 + (m << sl))];
.LBB0_678:
	v_and_b32_e32 v33, 0xffffffc0, v32
	v_or_b32_e32 v34, v33, v31
	v_ashrrev_i32_e32 v35, 1, v33
	v_lshlrev_b32_e32 v34, 3, v34
	v_add3_u32 v54, 0, v35, v34
	v_or_b32_e32 v35, 16, v33
	v_ashrrev_i32_e32 v35, 4, v35
	v_lshlrev_b32_e32 v35, 3, v35
	v_add3_u32 v55, 0, v35, v34

;     static __device__ __forceinline__ float sl(float g, float up) { return g * __builtin_amdgcn_rcpf(1.0f + __builtin_amdgcn_exp2f(-1.4426950408889634f * g)) * up; }
; #define tid ltid()
; template <int LR, bool INV>
; __device__ __forceinline__ void fft_pass(float2* X, const int N, const int sl, const int tid) {
;     ...
;   for (int g = tid; g < (N >> LR); g += NTHR) {
;     const int r = g & (s - 1);
;     const int i0 = ((g >> sl) << (sl + LR)) + r;
;     float2 x[R];
; #pragma unroll
;     for (int m = 0; m < R; ++m) x[m] = X[PIDX(i0 + (m << sl))];
	v_or_b32_e32 v33, 48, v33

;     static __device__ __forceinline__ float sl(float g, float up) { return g * __builtin_amdgcn_rcpf(1.0f + __builtin_amdgcn_exp2f(-1.4426950408889634f * g)) * up; }
; #define tid ltid()
; template <int LR, bool INV>
; __device__ __forceinline__ void fft_pass(float2* X, const int N, const int sl, const int tid) {
;     ...
;   for (int g = tid; g < (N >> LR); g += NTHR) {
;     const int r = g & (s - 1);
;     const int i0 = ((g >> sl) << (sl + LR)) + r;
;     float2 x[R];
; #pragma unroll
;     for (int m = 0; m < R; ++m) x[m] = X[PIDX(i0 + (m << sl))];
	v_ashrrev_i32_e32 v33, 4, v33

;     static __device__ __forceinline__ float sl(float g, float up) { return g * __builtin_amdgcn_rcpf(1.0f + __builtin_amdgcn_exp2f(-1.4426950408889634f * g)) * up; }
; #define tid ltid()
; template <int LR, bool INV>
; __device__ __forceinline__ void fft_pass(float2* X, const int N, const int sl, const int tid) {
;     ...
;   for (int g = tid; g < (N >> LR); g += NTHR) {
;     const int r = g & (s - 1);
;     const int i0 = ((g >> sl) << (sl + LR)) + r;
;     float2 x[R];
; #pragma unroll
;     for (int m = 0; m < R; ++m) x[m] = X[PIDX(i0 + (m << sl))];
	v_lshlrev_b32_e32 v33, 3, v33

;     static __device__ __forceinline__ float sl(float g, float up) { return g * __builtin_amdgcn_rcpf(1.0f + __builtin_amdgcn_exp2f(-1.4426950408889634f * g)) * up; }
; __device__ __forceinline__ float2 cmul(float2 a, float2 b) { return make_float2(a.x * b.x - a.y * b.y, a.x * b.y + a.y * b.x); }
; #define tid ltid()
; template <int LR, bool INV>
; __device__ __forceinline__ void fft_stages(float2 (&x)[1 << LR], const int r, const int s) {
;     ...
;   for (int st = 0; st < LR; ++st) {
;     const int hl = INV ? (1 << st) : (R >> (st + 1));
;     const float fb = (float)r * (0.5f / (float)(hl * s));
;     const float2 wb = make_float2(__builtin_amdgcn_cosf(fb), INV ? __builtin_amdgcn_sinf(fb) : -__builtin_amdgcn_sinf(fb));
; #pragma unroll
;     for (int m = 0; m < R; ++m) {
;       if (m & hl) continue;
;       const int k = m & (hl - 1); const int j = k * (8 / hl);
;       const float2 wc = make_float2(c16(j), INV ? s16(j) : -s16(j));
;       const float2 tw = cmul(wb, wc);
;       if (!INV) { const float2 p = x[m], q = x[m + hl]; x[m] = make_float2(p.x + q.x, p.y + q.y); x[m + hl] = cmul(make_float2(p.x - q.x, p.y - q.y), tw); }
;       else { const float2 p = x[m], q = cmul(x[m + hl], tw); x[m] = make_float2(p.x + q.x, p.y + q.y); x[m + hl] = make_float2(p.x - q.x, p.y - q.y); }
;     }
; template <int LR, bool INV>
; __device__ __forceinline__ void fft_pass(float2* X, const int N, const int sl, const int tid) {
;     ...
;   for (int g = tid; g < (N >> LR); g += NTHR) {
;     const int r = g & (s - 1);
;     const int i0 = ((g >> sl) << (sl + LR)) + r;
;     float2 x[R];
; #pragma unroll
;     for (int m = 0; m < R; ++m) x[m] = X[PIDX(i0 + (m << sl))];
	v_add3_u32 v33, 0, v33, v34
	ds_read2_b64 v[34:37], v54 offset1:8
	ds_read2_b64 v[38:41], v55 offset0:16 offset1:24
	ds_read2_b64 v[42:45], v55 offset0:33 offset1:41
	ds_read2_b64 v[46:49], v55 offset0:50 offset1:58
	v_add_u32_e32 v30, 0x200, v30
	v_cmp_le_i32_e32 vcc, s21, v30
	v_add_u32_e32 v32, 0x1000, v32
	s_waitcnt lgkmcnt(1)
	v_add_f32_e32 v50, v34, v42
	v_add_f32_e32 v51, v35, v43
	v_sub_f32_e32 v34, v34, v42
	v_sub_f32_e32 v35, v35, v43
	v_add_f32_e32 v42, v36, v44
	v_add_f32_e32 v43, v37, v45
	v_sub_f32_e32 v36, v36, v44
	v_sub_f32_e32 v37, v37, v45
	s_waitcnt lgkmcnt(0)
	v_add_f32_e32 v44, v38, v46
	v_add_f32_e32 v45, v39, v47
	v_sub_f32_e32 v38, v38, v46
	v_sub_f32_e32 v39, v39, v47
	v_add_f32_e32 v46, v40, v48
	v_add_f32_e32 v47, v41, v49
	v_sub_f32_e32 v40, v40, v48
	v_sub_f32_e32 v41, v41, v49
	v_add_f32_e32 v48, v50, v44
	v_add_f32_e32 v49, v51, v45
	v_sub_f32_e32 v44, v50, v44
	v_sub_f32_e32 v45, v51, v45
	v_add_f32_e32 v50, v42, v46
	v_add_f32_e32 v51, v43, v47
	v_sub_f32_e32 v42, v42, v46
	v_sub_f32_e32 v43, v43, v47
	v_add_f32_e32 v46, v48, v50
	v_add_f32_e32 v47, v49, v51
	v_sub_f32_e32 v48, v48, v50
	v_sub_f32_e32 v49, v49, v51
	s_or_b64 s[14:15], vcc, s[14:15]
	v_mul_f32_e32 v50, v16, v49
	v_mul_f32_e32 v51, v17, v49
	v_fma_f32 v52, v14, v48, -v50
	v_fma_f32 v53, v15, v48, v51

;     static __device__ __forceinline__ float sl(float g, float up) { return g * __builtin_amdgcn_rcpf(1.0f + __builtin_amdgcn_exp2f(-1.4426950408889634f * g)) * up; }
; __device__ __forceinline__ float2 cmul(float2 a, float2 b) { return make_float2(a.x * b.x - a.y * b.y, a.x * b.y + a.y * b.x); }
; template <int LR, bool INV>
; __device__ __forceinline__ void fft_stages(float2 (&x)[1 << LR], const int r, const int s) {
;   constexpr int R = 1 << LR;
; #pragma unroll
;   for (int st = 0; st < LR; ++st) {
;     const int hl = INV ? (1 << st) : (R >> (st + 1));
;     const float fb = (float)r * (0.5f / (float)(hl * s));
;     const float2 wb = make_float2(__builtin_amdgcn_cosf(fb), INV ? __builtin_amdgcn_sinf(fb) : -__builtin_amdgcn_sinf(fb));
; #pragma unroll
;     for (int m = 0; m < R; ++m) {
;       if (m & hl) continue;
;       const int k = m & (hl - 1); const int j = k * (8 / hl);
;       const float2 wc = make_float2(c16(j), INV ? s16(j) : -s16(j));
;       const float2 tw = cmul(wb, wc);
;       if (!INV) { const float2 p = x[m], q = x[m + hl]; x[m] = make_float2(p.x + q.x, p.y + q.y); x[m + hl] = cmul(make_float2(p.x - q.x, p.y - q.y), tw); }
;       else { const float2 p = x[m], q = cmul(x[m + hl], tw); x[m] = make_float2(p.x + q.x, p.y + q.y); x[m + hl] = make_float2(p.x - q.x, p.y - q.y); }
;     }
; template <int LR, bool INV>
; __device__ __forceinline__ void fft_pass(float2* X, const int N, const int sl, const int tid) {
;     ...
; #pragma unroll
;     for (int m = 0; m < R; ++m) X[PIDX(i0 + (m << sl))] = x[m];
	ds_write2_b64 v54, v[46:47], v[52:53] offset1:8
	v_mul_f32_e32 v46, v18, v45
	v_mul_f32_e32 v47, v19, v45
	v_fma_f32 v48, v10, v44, -v46
	v_fma_f32 v49, v11, v44, v47

; __device__ __forceinline__ float2 cmul(float2 a, float2 b) { return make_float2(a.x * b.x - a.y * b.y, a.x * b.y + a.y * b.x); }
; template <int LR, bool INV>
; __device__ __forceinline__ void fft_stages(float2 (&x)[1 << LR], const int r, const int s) {
;   constexpr int R = 1 << LR;
; #pragma unroll
;   for (int st = 0; st < LR; ++st) {
;     const int hl = INV ? (1 << st) : (R >> (st + 1));
;     const float fb = (float)r * (0.5f / (float)(hl * s));
;     const float2 wb = make_float2(__builtin_amdgcn_cosf(fb), INV ? __builtin_amdgcn_sinf(fb) : -__builtin_amdgcn_sinf(fb));
; #pragma unroll
;     for (int m = 0; m < R; ++m) {
;       if (m & hl) continue;
;       const int k = m & (hl - 1); const int j = k * (8 / hl);
;       const float2 wc = make_float2(c16(j), INV ? s16(j) : -s16(j));
;       const float2 tw = cmul(wb, wc);
;       if (!INV) { const float2 p = x[m], q = x[m + hl]; x[m] = make_float2(p.x + q.x, p.y + q.y); x[m + hl] = cmul(make_float2(p.x - q.x, p.y - q.y), tw); }
;       else { const float2 p = x[m], q = cmul(x[m + hl], tw); x[m] = make_float2(p.x + q.x, p.y + q.y); x[m + hl] = make_float2(p.x - q.x, p.y - q.y); }
;     }
	v_mul_f32_e32 v44, v20, v43
	v_mul_f32_e32 v45, v21, v43
	v_fma_f32 v46, v12, v42, -v44
	v_fma_f32 v47, v13, v42, v45

; __device__ __forceinline__ float2 cmul(float2 a, float2 b) { return make_float2(a.x * b.x - a.y * b.y, a.x * b.y + a.y * b.x); }
; template <int LR, bool INV>
; __device__ __forceinline__ void fft_stages(float2 (&x)[1 << LR], const int r, const int s) {
;   constexpr int R = 1 << LR;
; #pragma unroll
;   for (int st = 0; st < LR; ++st) {
;     const int hl = INV ? (1 << st) : (R >> (st + 1));
;     const float fb = (float)r * (0.5f / (float)(hl * s));
;     const float2 wb = make_float2(__builtin_amdgcn_cosf(fb), INV ? __builtin_amdgcn_sinf(fb) : -__builtin_amdgcn_sinf(fb));
; #pragma unroll
;     for (int m = 0; m < R; ++m) {
;       if (m & hl) continue;
;       const int k = m & (hl - 1); const int j = k * (8 / hl);
;       const float2 wc = make_float2(c16(j), INV ? s16(j) : -s16(j));
;       const float2 tw = cmul(wb, wc);
;       if (!INV) { const float2 p = x[m], q = x[m + hl]; x[m] = make_float2(p.x + q.x, p.y + q.y); x[m + hl] = cmul(make_float2(p.x - q.x, p.y - q.y), tw); }
;       else { const float2 p = x[m], q = cmul(x[m + hl], tw); x[m] = make_float2(p.x + q.x, p.y + q.y); x[m + hl] = make_float2(p.x - q.x, p.y - q.y); }
;     }
	v_sub_f32_e32 v44, v48, v46
	v_sub_f32_e32 v45, v49, v47
	v_add_f32_e32 v42, v48, v46
	v_add_f32_e32 v43, v49, v47
	v_mul_f32_e32 v46, v16, v45
	v_mul_f32_e32 v47, v17, v45
	v_fma_f32 v48, v14, v44, -v46
	v_fma_f32 v49, v15, v44, v47

;     static __device__ __forceinline__ float sl(float g, float up) { return g * __builtin_amdgcn_rcpf(1.0f + __builtin_amdgcn_exp2f(-1.4426950408889634f * g)) * up; }
; __device__ __forceinline__ float2 cmul(float2 a, float2 b) { return make_float2(a.x * b.x - a.y * b.y, a.x * b.y + a.y * b.x); }
; template <int LR, bool INV>
; __device__ __forceinline__ void fft_stages(float2 (&x)[1 << LR], const int r, const int s) {
;   constexpr int R = 1 << LR;
; #pragma unroll
;   for (int st = 0; st < LR; ++st) {
;     const int hl = INV ? (1 << st) : (R >> (st + 1));
;     const float fb = (float)r * (0.5f / (float)(hl * s));
;     const float2 wb = make_float2(__builtin_amdgcn_cosf(fb), INV ? __builtin_amdgcn_sinf(fb) : -__builtin_amdgcn_sinf(fb));
; #pragma unroll
;     for (int m = 0; m < R; ++m) {
;       if (m & hl) continue;
;       const int k = m & (hl - 1); const int j = k * (8 / hl);
;       const float2 wc = make_float2(c16(j), INV ? s16(j) : -s16(j));
;       const float2 tw = cmul(wb, wc);
;       if (!INV) { const float2 p = x[m], q = x[m + hl]; x[m] = make_float2(p.x + q.x, p.y + q.y); x[m + hl] = cmul(make_float2(p.x - q.x, p.y - q.y), tw); }
;       else { const float2 p = x[m], q = cmul(x[m + hl], tw); x[m] = make_float2(p.x + q.x, p.y + q.y); x[m + hl] = make_float2(p.x - q.x, p.y - q.y); }
;     }
; template <int LR, bool INV>
; __device__ __forceinline__ void fft_pass(float2* X, const int N, const int sl, const int tid) {
;     ...
; #pragma unroll
;     for (int m = 0; m < R; ++m) X[PIDX(i0 + (m << sl))] = x[m];
	ds_write2_b64 v55, v[42:43], v[48:49] offset0:16 offset1:24
	v_mul_f32_e32 v42, v22, v35
	v_mul_f32_e32 v43, v23, v35
	v_fma_f32 v44, v2, v34, -v42
	v_fma_f32 v45, v3, v34, v43

; __device__ __forceinline__ float2 cmul(float2 a, float2 b) { return make_float2(a.x * b.x - a.y * b.y, a.x * b.y + a.y * b.x); }
; template <int LR, bool INV>
; __device__ __forceinline__ void fft_stages(float2 (&x)[1 << LR], const int r, const int s) {
;   constexpr int R = 1 << LR;
; #pragma unroll
;   for (int st = 0; st < LR; ++st) {
;     const int hl = INV ? (1 << st) : (R >> (st + 1));
;     const float fb = (float)r * (0.5f / (float)(hl * s));
;     const float2 wb = make_float2(__builtin_amdgcn_cosf(fb), INV ? __builtin_amdgcn_sinf(fb) : -__builtin_amdgcn_sinf(fb));
; #pragma unroll
;     for (int m = 0; m < R; ++m) {
;       if (m & hl) continue;
;       const int k = m & (hl - 1); const int j = k * (8 / hl);
;       const float2 wc = make_float2(c16(j), INV ? s16(j) : -s16(j));
;       const float2 tw = cmul(wb, wc);
;       if (!INV) { const float2 p = x[m], q = x[m + hl]; x[m] = make_float2(p.x + q.x, p.y + q.y); x[m + hl] = cmul(make_float2(p.x - q.x, p.y - q.y), tw); }
;       else { const float2 p = x[m], q = cmul(x[m + hl], tw); x[m] = make_float2(p.x + q.x, p.y + q.y); x[m + hl] = make_float2(p.x - q.x, p.y - q.y); }
;     }
	v_mul_f32_e32 v34, v24, v37
	v_mul_f32_e32 v35, v25, v37
	v_fma_f32 v42, v4, v36, -v34
	v_fma_f32 v43, v5, v36, v35

; __device__ __forceinline__ float2 cmul(float2 a, float2 b) { return make_float2(a.x * b.x - a.y * b.y, a.x * b.y + a.y * b.x); }
; template <int LR, bool INV>
; __device__ __forceinline__ void fft_stages(float2 (&x)[1 << LR], const int r, const int s) {
;   constexpr int R = 1 << LR;
; #pragma unroll
;   for (int st = 0; st < LR; ++st) {
;     const int hl = INV ? (1 << st) : (R >> (st + 1));
;     const float fb = (float)r * (0.5f / (float)(hl * s));
;     const float2 wb = make_float2(__builtin_amdgcn_cosf(fb), INV ? __builtin_amdgcn_sinf(fb) : -__builtin_amdgcn_sinf(fb));
; #pragma unroll
;     for (int m = 0; m < R; ++m) {
;       if (m & hl) continue;
;       const int k = m & (hl - 1); const int j = k * (8 / hl);
;       const float2 wc = make_float2(c16(j), INV ? s16(j) : -s16(j));
;       const float2 tw = cmul(wb, wc);
;       if (!INV) { const float2 p = x[m], q = x[m + hl]; x[m] = make_float2(p.x + q.x, p.y + q.y); x[m + hl] = cmul(make_float2(p.x - q.x, p.y - q.y), tw); }
;       else { const float2 p = x[m], q = cmul(x[m + hl], tw); x[m] = make_float2(p.x + q.x, p.y + q.y); x[m + hl] = make_float2(p.x - q.x, p.y - q.y); }
;     }
	v_mul_f32_e32 v34, v26, v39
	v_mul_f32_e32 v35, v27, v39
	v_fma_f32 v36, v6, v38, -v34
	v_fma_f32 v37, v7, v38, v35

; __device__ __forceinline__ float2 cmul(float2 a, float2 b) { return make_float2(a.x * b.x - a.y * b.y, a.x * b.y + a.y * b.x); }
; template <int LR, bool INV>
; __device__ __forceinline__ void fft_stages(float2 (&x)[1 << LR], const int r, const int s) {
;   constexpr int R = 1 << LR;
; #pragma unroll
;   for (int st = 0; st < LR; ++st) {
;     const int hl = INV ? (1 << st) : (R >> (st + 1));
;     const float fb = (float)r * (0.5f / (float)(hl * s));
;     const float2 wb = make_float2(__builtin_amdgcn_cosf(fb), INV ? __builtin_amdgcn_sinf(fb) : -__builtin_amdgcn_sinf(fb));
; #pragma unroll
;     for (int m = 0; m < R; ++m) {
;       if (m & hl) continue;
;       const int k = m & (hl - 1); const int j = k * (8 / hl);
;       const float2 wc = make_float2(c16(j), INV ? s16(j) : -s16(j));
;       const float2 tw = cmul(wb, wc);
;       if (!INV) { const float2 p = x[m], q = x[m + hl]; x[m] = make_float2(p.x + q.x, p.y + q.y); x[m + hl] = cmul(make_float2(p.x - q.x, p.y - q.y), tw); }
;       else { const float2 p = x[m], q = cmul(x[m + hl], tw); x[m] = make_float2(p.x + q.x, p.y + q.y); x[m + hl] = make_float2(p.x - q.x, p.y - q.y); }
;     }
	v_mul_f32_e32 v34, v28, v41
	v_mul_f32_e32 v35, v29, v41
	v_fma_f32 v38, v8, v40, -v34
	v_fma_f32 v39, v9, v40, v35

; __device__ __forceinline__ float2 cmul(float2 a, float2 b) { return make_float2(a.x * b.x - a.y * b.y, a.x * b.y + a.y * b.x); }
; template <int LR, bool INV>
; __device__ __forceinline__ void fft_stages(float2 (&x)[1 << LR], const int r, const int s) {
;   constexpr int R = 1 << LR;
; #pragma unroll
;   for (int st = 0; st < LR; ++st) {
;     const int hl = INV ? (1 << st) : (R >> (st + 1));
;     const float fb = (float)r * (0.5f / (float)(hl * s));
;     const float2 wb = make_float2(__builtin_amdgcn_cosf(fb), INV ? __builtin_amdgcn_sinf(fb) : -__builtin_amdgcn_sinf(fb));
; #pragma unroll
;     for (int m = 0; m < R; ++m) {
;       if (m & hl) continue;
;       const int k = m & (hl - 1); const int j = k * (8 / hl);
;       const float2 wc = make_float2(c16(j), INV ? s16(j) : -s16(j));
;       const float2 tw = cmul(wb, wc);
;       if (!INV) { const float2 p = x[m], q = x[m + hl]; x[m] = make_float2(p.x + q.x, p.y + q.y); x[m + hl] = cmul(make_float2(p.x - q.x, p.y - q.y), tw); }
;       else { const float2 p = x[m], q = cmul(x[m + hl], tw); x[m] = make_float2(p.x + q.x, p.y + q.y); x[m + hl] = make_float2(p.x - q.x, p.y - q.y); }
;     }
	v_add_f32_e32 v34, v44, v36
	v_add_f32_e32 v35, v45, v37
	v_add_f32_e32 v40, v42, v38
	v_add_f32_e32 v41, v43, v39
	v_sub_f32_e32 v38, v42, v38
	v_sub_f32_e32 v39, v43, v39
	v_add_f32_e32 v42, v34, v40
	v_add_f32_e32 v43, v35, v41
	v_sub_f32_e32 v34, v34, v40
	v_sub_f32_e32 v35, v35, v41
	v_sub_f32_e32 v36, v44, v36
	v_sub_f32_e32 v37, v45, v37
	v_mul_f32_e32 v40, v16, v35
	v_mul_f32_e32 v41, v17, v35
	v_fma_f32 v44, v14, v34, -v40
	v_fma_f32 v45, v15, v34, v41

;     static __device__ __forceinline__ float sl(float g, float up) { return g * __builtin_amdgcn_rcpf(1.0f + __builtin_amdgcn_exp2f(-1.4426950408889634f * g)) * up; }
; __device__ __forceinline__ float2 cmul(float2 a, float2 b) { return make_float2(a.x * b.x - a.y * b.y, a.x * b.y + a.y * b.x); }
; template <int LR, bool INV>
; __device__ __forceinline__ void fft_stages(float2 (&x)[1 << LR], const int r, const int s) {
;   constexpr int R = 1 << LR;
; #pragma unroll
;   for (int st = 0; st < LR; ++st) {
;     const int hl = INV ? (1 << st) : (R >> (st + 1));
;     const float fb = (float)r * (0.5f / (float)(hl * s));
;     const float2 wb = make_float2(__builtin_amdgcn_cosf(fb), INV ? __builtin_amdgcn_sinf(fb) : -__builtin_amdgcn_sinf(fb));
; #pragma unroll
;     for (int m = 0; m < R; ++m) {
;       if (m & hl) continue;
;       const int k = m & (hl - 1); const int j = k * (8 / hl);
;       const float2 wc = make_float2(c16(j), INV ? s16(j) : -s16(j));
;       const float2 tw = cmul(wb, wc);
;       if (!INV) { const float2 p = x[m], q = x[m + hl]; x[m] = make_float2(p.x + q.x, p.y + q.y); x[m + hl] = cmul(make_float2(p.x - q.x, p.y - q.y), tw); }
;       else { const float2 p = x[m], q = cmul(x[m + hl], tw); x[m] = make_float2(p.x + q.x, p.y + q.y); x[m + hl] = make_float2(p.x - q.x, p.y - q.y); }
;     }
; template <int LR, bool INV>
; __device__ __forceinline__ void fft_pass(float2* X, const int N, const int sl, const int tid) {
;     ...
; #pragma unroll
;     for (int m = 0; m < R; ++m) X[PIDX(i0 + (m << sl))] = x[m];
	v_mul_f32_e32 v34, v18, v37
	v_mul_f32_e32 v35, v19, v37
	ds_write2_b64 v55, v[42:43], v[44:45] offset0:33 offset1:41
	v_fma_f32 v40, v10, v36, -v34
	v_fma_f32 v41, v11, v36, v35

; __device__ __forceinline__ float2 cmul(float2 a, float2 b) { return make_float2(a.x * b.x - a.y * b.y, a.x * b.y + a.y * b.x); }
; template <int LR, bool INV>
; __device__ __forceinline__ void fft_stages(float2 (&x)[1 << LR], const int r, const int s) {
;   constexpr int R = 1 << LR;
; #pragma unroll
;   for (int st = 0; st < LR; ++st) {
;     const int hl = INV ? (1 << st) : (R >> (st + 1));
;     const float fb = (float)r * (0.5f / (float)(hl * s));
;     const float2 wb = make_float2(__builtin_amdgcn_cosf(fb), INV ? __builtin_amdgcn_sinf(fb) : -__builtin_amdgcn_sinf(fb));
; #pragma unroll
;     for (int m = 0; m < R; ++m) {
;       if (m & hl) continue;
;       const int k = m & (hl - 1); const int j = k * (8 / hl);
;       const float2 wc = make_float2(c16(j), INV ? s16(j) : -s16(j));
;       const float2 tw = cmul(wb, wc);
;       if (!INV) { const float2 p = x[m], q = x[m + hl]; x[m] = make_float2(p.x + q.x, p.y + q.y); x[m + hl] = cmul(make_float2(p.x - q.x, p.y - q.y), tw); }
;       else { const float2 p = x[m], q = cmul(x[m + hl], tw); x[m] = make_float2(p.x + q.x, p.y + q.y); x[m + hl] = make_float2(p.x - q.x, p.y - q.y); }
;     }
	v_mul_f32_e32 v34, v20, v39
	v_mul_f32_e32 v35, v21, v39
	v_fma_f32 v36, v12, v38, -v34
	v_fma_f32 v37, v13, v38, v35

;     static __device__ __forceinline__ float sl(float g, float up) { return g * __builtin_amdgcn_rcpf(1.0f + __builtin_amdgcn_exp2f(-1.4426950408889634f * g)) * up; }
; __device__ __forceinline__ float2 cmul(float2 a, float2 b) { return make_float2(a.x * b.x - a.y * b.y, a.x * b.y + a.y * b.x); }
; template <int LR, bool INV>
; __device__ __forceinline__ void fft_stages(float2 (&x)[1 << LR], const int r, const int s) {
;   constexpr int R = 1 << LR;
; #pragma unroll
;   for (int st = 0; st < LR; ++st) {
;     const int hl = INV ? (1 << st) : (R >> (st + 1));
;     const float fb = (float)r * (0.5f / (float)(hl * s));
;     const float2 wb = make_float2(__builtin_amdgcn_cosf(fb), INV ? __builtin_amdgcn_sinf(fb) : -__builtin_amdgcn_sinf(fb));
; #pragma unroll
;     for (int m = 0; m < R; ++m) {
;       if (m & hl) continue;
;       const int k = m & (hl - 1); const int j = k * (8 / hl);
;       const float2 wc = make_float2(c16(j), INV ? s16(j) : -s16(j));
;       const float2 tw = cmul(wb, wc);
;       if (!INV) { const float2 p = x[m], q = x[m + hl]; x[m] = make_float2(p.x + q.x, p.y + q.y); x[m + hl] = cmul(make_float2(p.x - q.x, p.y - q.y), tw); }
;       else { const float2 p = x[m], q = cmul(x[m + hl], tw); x[m] = make_float2(p.x + q.x, p.y + q.y); x[m + hl] = make_float2(p.x - q.x, p.y - q.y); }
;     }
; template <int LR, bool INV>
; __device__ __forceinline__ void fft_pass(float2* X, const int N, const int sl, const int tid) {
;     ...
; #pragma unroll
;     for (int m = 0; m < R; ++m) X[PIDX(i0 + (m << sl))] = x[m];
;   }
;   __syncthreads();
	v_add_f32_e32 v34, v40, v36
	v_add_f32_e32 v35, v41, v37
	v_sub_f32_e32 v36, v40, v36
	v_sub_f32_e32 v37, v41, v37
	v_mul_f32_e32 v38, v16, v37
	v_mul_f32_e32 v39, v17, v37
	v_fma_f32 v40, v14, v36, -v38
	v_fma_f32 v37, v15, v36, v39
	v_fma_f32 v36, v14, v36, v38
	v_mov_b32_e32 v41, v37
	ds_write2_b64 v55, v[34:35], v[40:41] offset0:50 offset1:58
	s_andn2_b64 exec, exec, s[14:15]
	s_cbranch_execnz .LBB0_678

; __device__ __forceinline__ float2 cmul(float2 a, float2 b) { return make_float2(a.x * b.x - a.y * b.y, a.x * b.y + a.y * b.x); }
; #define tid ltid()
; template <int LR, bool INV>
; __device__ __forceinline__ void fft_stages(float2 (&x)[1 << LR], const int r, const int s) {
;   constexpr int R = 1 << LR;
; #pragma unroll
;   for (int st = 0; st < LR; ++st) {
;     const int hl = INV ? (1 << st) : (R >> (st + 1));
;     const float fb = (float)r * (0.5f / (float)(hl * s));
;     const float2 wb = make_float2(__builtin_amdgcn_cosf(fb), INV ? __builtin_amdgcn_sinf(fb) : -__builtin_amdgcn_sinf(fb));
; #pragma unroll
;     for (int m = 0; m < R; ++m) {
;       if (m & hl) continue;
;       const int k = m & (hl - 1); const int j = k * (8 / hl);
;       const float2 wc = make_float2(c16(j), INV ? s16(j) : -s16(j));
;       const float2 tw = cmul(wb, wc);
;       if (!INV) { const float2 p = x[m], q = x[m + hl]; x[m] = make_float2(p.x + q.x, p.y + q.y); x[m + hl] = cmul(make_float2(p.x - q.x, p.y - q.y), tw); }
;       else { const float2 p = x[m], q = cmul(x[m + hl], tw); x[m] = make_float2(p.x + q.x, p.y + q.y); x[m + hl] = make_float2(p.x - q.x, p.y - q.y); }
;     }
; __device__ __forceinline__ void fft_mid(float2* X, const float2* Hb, const int N, const float invN, const int tid) {
;   for (int g = tid; g < (N >> 3); g += NTHR) {
;     const int i0 = g << 3; const int p0 = PIDX(i0);
;     float2 x[8];
; #pragma unroll
;     for (int m = 0; m < 8; ++m) x[m] = X[p0 + m];
;     fft_stages<3, false>(x, 0, 1);
.LBB0_681:
	v_ashrrev_i32_e32 v4, 4, v3
	v_add_u32_e32 v4, v3, v4
	v_lshl_add_u32 v38, v4, 3, 0
	ds_read2_b64 v[4:7], v38 offset1:1
	ds_read2_b64 v[8:11], v38 offset0:2 offset1:3
	ds_read2_b64 v[12:15], v38 offset0:4 offset1:5
	ds_read2_b64 v[16:19], v38 offset0:6 offset1:7
	v_add_u32_e32 v2, 0x200, v2
	v_cmp_le_i32_e32 vcc, s21, v2
	v_add_u32_e32 v3, 0x1000, v3
	s_waitcnt lgkmcnt(1)
	v_sub_f32_e32 v20, v4, v12
	v_sub_f32_e32 v21, v5, v13
	v_add_f32_e32 v4, v4, v12
	v_add_f32_e32 v5, v5, v13
	v_mul_f32_e32 v22, 0, v20
	v_mul_f32_e32 v23, 0, v21
	s_or_b64 s[14:15], vcc, s[14:15]
	v_sub_f32_e32 v24, v20, v23
	v_sub_f32_e32 v25, v21, v22
	v_add_f32_e32 v20, v20, v23
	v_add_f32_e32 v21, v21, v22
	s_waitcnt lgkmcnt(0)
	v_sub_f32_e32 v22, v8, v16
	v_sub_f32_e32 v23, v9, v17
	v_pk_mov_b32 v[20:21], v[24:25], v[20:21] op_sel:[1,0]
	v_mul_f32_e32 v24, 0, v22
	v_mul_f32_e32 v25, 0, v23
	v_sub_f32_e32 v26, v25, v22
	v_add_f32_e32 v27, v24, v23

; __device__ __forceinline__ float2 cmul(float2 a, float2 b) { return make_float2(a.x * b.x - a.y * b.y, a.x * b.y + a.y * b.x); }
; template <int LR, bool INV>
; __device__ __forceinline__ void fft_stages(float2 (&x)[1 << LR], const int r, const int s) {
;   constexpr int R = 1 << LR;
; #pragma unroll
;   for (int st = 0; st < LR; ++st) {
;     const int hl = INV ? (1 << st) : (R >> (st + 1));
;     const float fb = (float)r * (0.5f / (float)(hl * s));
;     const float2 wb = make_float2(__builtin_amdgcn_cosf(fb), INV ? __builtin_amdgcn_sinf(fb) : -__builtin_amdgcn_sinf(fb));
; #pragma unroll
;     for (int m = 0; m < R; ++m) {
;       if (m & hl) continue;
;       const int k = m & (hl - 1); const int j = k * (8 / hl);
;       const float2 wc = make_float2(c16(j), INV ? s16(j) : -s16(j));
;       const float2 tw = cmul(wb, wc);
;       if (!INV) { const float2 p = x[m], q = x[m + hl]; x[m] = make_float2(p.x + q.x, p.y + q.y); x[m + hl] = cmul(make_float2(p.x - q.x, p.y - q.y), tw); }
;       else { const float2 p = x[m], q = cmul(x[m + hl], tw); x[m] = make_float2(p.x + q.x, p.y + q.y); x[m + hl] = make_float2(p.x - q.x, p.y - q.y); }
;     }
	v_sub_f32_e32 v22, v20, v26
	v_sub_f32_e32 v23, v21, v27
	v_mul_f32_e32 v24, 0, v22
	v_mul_f32_e32 v25, 0, v23
	v_sub_f32_e32 v28, v22, v25
	v_add_f32_e32 v29, v23, v24
	v_add_f32_e32 v24, v10, v18
	v_add_f32_e32 v25, v11, v19

; __device__ __forceinline__ float2 cmul(float2 a, float2 b) { return make_float2(a.x * b.x - a.y * b.y, a.x * b.y + a.y * b.x); }
; template <int LR, bool INV>
; __device__ __forceinline__ void fft_stages(float2 (&x)[1 << LR], const int r, const int s) {
;   constexpr int R = 1 << LR;
; #pragma unroll
;   for (int st = 0; st < LR; ++st) {
;     const int hl = INV ? (1 << st) : (R >> (st + 1));
;     const float fb = (float)r * (0.5f / (float)(hl * s));
;     const float2 wb = make_float2(__builtin_amdgcn_cosf(fb), INV ? __builtin_amdgcn_sinf(fb) : -__builtin_amdgcn_sinf(fb));
; #pragma unroll
;     for (int m = 0; m < R; ++m) {
;       if (m & hl) continue;
;       const int k = m & (hl - 1); const int j = k * (8 / hl);
;       const float2 wc = make_float2(c16(j), INV ? s16(j) : -s16(j));
;       const float2 tw = cmul(wb, wc);
;       if (!INV) { const float2 p = x[m], q = x[m + hl]; x[m] = make_float2(p.x + q.x, p.y + q.y); x[m + hl] = cmul(make_float2(p.x - q.x, p.y - q.y), tw); }
;       else { const float2 p = x[m], q = cmul(x[m + hl], tw); x[m] = make_float2(p.x + q.x, p.y + q.y); x[m + hl] = make_float2(p.x - q.x, p.y - q.y); }
;     }
	v_add_f32_e32 v22, v6, v14
	v_add_f32_e32 v23, v7, v15
	v_sub_f32_e32 v6, v6, v14
	v_sub_f32_e32 v7, v7, v15
	v_sub_f32_e32 v10, v10, v18
	v_sub_f32_e32 v11, v11, v19
	v_mul_f32_e32 v15, 0x3f3504f3, v6
	v_mul_f32_e32 v6, 0x3f3504f3, v7
	v_mul_f32_e32 v34, 0xbf3504f3, v10
	v_mul_f32_e32 v11, 0xbf3504f3, v11
	v_sub_f32_e32 v14, v6, v15
	v_fmac_f32_e32 v15, 0x3f3504f3, v7
	v_add_f32_e32 v6, v8, v16
	v_add_f32_e32 v7, v9, v17
	v_add_f32_e32 v8, v34, v11
	v_fma_f32 v9, v10, s70, -v11
	v_sub_f32_e32 v10, v4, v6
	v_sub_f32_e32 v11, v5, v7
	v_sub_f32_e32 v18, v22, v24
	v_sub_f32_e32 v19, v23, v25
	v_mul_f32_e32 v12, 0, v10
	v_mul_f32_e32 v13, 0, v11
	v_mul_f32_e32 v30, 0, v18
	v_mul_f32_e32 v31, 0, v19
	v_sub_f32_e32 v16, v10, v13
	v_sub_f32_e32 v17, v11, v12
	v_add_f32_e32 v10, v10, v13
	v_add_f32_e32 v11, v11, v12
	v_sub_f32_e32 v12, v14, v8
	v_sub_f32_e32 v13, v15, v9
	v_pk_mov_b32 v[10:11], v[16:17], v[10:11] op_sel:[1,0]
	v_fma_f32 v16, v12, 0, -v13
	v_fma_f32 v17, v13, 0, v12
	v_sub_f32_e32 v32, v31, v18
	v_add_f32_e32 v33, v30, v19

; __device__ __forceinline__ float2 cmul(float2 a, float2 b) { return make_float2(a.x * b.x - a.y * b.y, a.x * b.y + a.y * b.x); }
; template <int LR, bool INV>
; __device__ __forceinline__ void fft_stages(float2 (&x)[1 << LR], const int r, const int s) {
;   constexpr int R = 1 << LR;
; #pragma unroll
;   for (int st = 0; st < LR; ++st) {
;     const int hl = INV ? (1 << st) : (R >> (st + 1));
;     const float fb = (float)r * (0.5f / (float)(hl * s));
;     const float2 wb = make_float2(__builtin_amdgcn_cosf(fb), INV ? __builtin_amdgcn_sinf(fb) : -__builtin_amdgcn_sinf(fb));
; #pragma unroll
;     for (int m = 0; m < R; ++m) {
;       if (m & hl) continue;
;       const int k = m & (hl - 1); const int j = k * (8 / hl);
;       const float2 wc = make_float2(c16(j), INV ? s16(j) : -s16(j));
;       const float2 tw = cmul(wb, wc);
;       if (!INV) { const float2 p = x[m], q = x[m + hl]; x[m] = make_float2(p.x + q.x, p.y + q.y); x[m + hl] = cmul(make_float2(p.x - q.x, p.y - q.y), tw); }
;       else { const float2 p = x[m], q = cmul(x[m + hl], tw); x[m] = make_float2(p.x + q.x, p.y + q.y); x[m + hl] = make_float2(p.x - q.x, p.y - q.y); }
;     }
	v_add_f32_e32 v12, v22, v24
	v_add_f32_e32 v13, v23, v25
	v_add_f32_e32 v4, v4, v6
	v_add_f32_e32 v5, v5, v7

; __device__ __forceinline__ float2 cmul(float2 a, float2 b) { return make_float2(a.x * b.x - a.y * b.y, a.x * b.y + a.y * b.x); }
; template <int LR, bool INV>
; __device__ __forceinline__ void fft_stages(float2 (&x)[1 << LR], const int r, const int s) {
;   constexpr int R = 1 << LR;
; #pragma unroll
;   for (int st = 0; st < LR; ++st) {
;     const int hl = INV ? (1 << st) : (R >> (st + 1));
;     const float fb = (float)r * (0.5f / (float)(hl * s));
;     const float2 wb = make_float2(__builtin_amdgcn_cosf(fb), INV ? __builtin_amdgcn_sinf(fb) : -__builtin_amdgcn_sinf(fb));
; #pragma unroll
;     for (int m = 0; m < R; ++m) {
;       if (m & hl) continue;
;       const int k = m & (hl - 1); const int j = k * (8 / hl);
;       const float2 wc = make_float2(c16(j), INV ? s16(j) : -s16(j));
;       const float2 tw = cmul(wb, wc);
;       if (!INV) { const float2 p = x[m], q = x[m + hl]; x[m] = make_float2(p.x + q.x, p.y + q.y); x[m + hl] = cmul(make_float2(p.x - q.x, p.y - q.y), tw); }
;       else { const float2 p = x[m], q = cmul(x[m + hl], tw); x[m] = make_float2(p.x + q.x, p.y + q.y); x[m + hl] = make_float2(p.x - q.x, p.y - q.y); }
;     }
; __device__ __forceinline__ void fft_mid(float2* X, const float2* Hb, const int N, const float invN, const int tid) {
;     ...
;     for (int m = 0; m < 8; ++m) x[m] = X[p0 + m];
;     fft_stages<3, false>(x, 0, 1);
; #pragma unroll
;     for (int m = 0; m < 8; ++m) { const float2 h = Hb[p0 + m]; const float2 v = x[m]; x[m] = make_float2((v.x * h.x - v.y * h.y) * invN, (v.x * h.y + v.y * h.x) * invN); }
;     fft_stages<3, true>(x, 0, 1);
	v_add_f32_e32 v18, v4, v12
	v_add_f32_e32 v19, v5, v13
	v_sub_f32_e32 v12, v4, v12
	v_sub_f32_e32 v13, v5, v13
	v_add_f32_e32 v4, v20, v26
	v_add_f32_e32 v5, v21, v27
	v_add_f32_e32 v26, v28, v16
	v_add_f32_e32 v27, v29, v17
	v_sub_f32_e32 v16, v28, v16
	v_sub_f32_e32 v17, v29, v17
	v_add_f32_e32 v6, v14, v8
	v_add_f32_e32 v7, v15, v9
	v_fma_f32 v28, 0, v16, v17
	v_fmac_f32_e32 v16, 0x80000000, v17
	v_add_u32_e32 v17, 0x11000, v38
	v_add_f32_e32 v8, v4, v6
	v_add_f32_e32 v9, v5, v7
	v_sub_f32_e32 v14, v4, v6
	v_sub_f32_e32 v15, v5, v7
	ds_read2_b64 v[4:7], v17 offset1:1
	v_fma_f32 v22, 0, v13, v12
	v_fmac_f32_e32 v13, 0x80000000, v12
	v_add_f32_e32 v24, v10, v32
	v_add_f32_e32 v25, v11, v33
	v_sub_f32_e32 v10, v10, v32
	v_sub_f32_e32 v11, v11, v33
	s_waitcnt lgkmcnt(0)
	v_mul_f32_e32 v30, v5, v19
	v_mul_f32_e32 v31, v4, v19
	v_fma_f32 v32, v4, v18, -v30
	v_fma_f32 v33, v5, v18, v31
	v_fma_f32 v12, 0, v10, v11
	v_mov_b32_e32 v4, v13

; __device__ __forceinline__ void fft_mid(float2* X, const float2* Hb, const int N, const float invN, const int tid) {
;     ...
;     for (int m = 0; m < 8; ++m) { const float2 h = Hb[p0 + m]; const float2 v = x[m]; x[m] = make_float2((v.x * h.x - v.y * h.y) * invN, (v.x * h.y + v.y * h.x) * invN); }
	v_mul_f32_e32 v5, v6, v4
	v_mul_f32_e32 v4, v7, v4
	v_fma_f32 v18, v6, v22, -v4
	v_fma_f32 v19, v7, v22, v5
	v_fmac_f32_e32 v10, 0x80000000, v11

; __device__ __forceinline__ void fft_mid(float2* X, const float2* Hb, const int N, const float invN, const int tid) {
;     ...
;     for (int m = 0; m < 8; ++m) { const float2 h = Hb[p0 + m]; const float2 v = x[m]; x[m] = make_float2((v.x * h.x - v.y * h.y) * invN, (v.x * h.y + v.y * h.x) * invN); }
	ds_read2_b64 v[4:7], v17 offset0:2 offset1:3
	v_fma_f32 v20, 0, v14, v15
	v_fmac_f32_e32 v14, 0x80000000, v15
	v_mul_f32_e32 v22, v0, v18
	v_mul_f32_e32 v23, v1, v19
	s_waitcnt lgkmcnt(0)
	v_mul_f32_e32 v30, v24, v5
	v_mul_f32_e32 v31, v24, v4
	v_fma_f32 v34, v25, v4, -v30
	v_fma_f32 v35, v25, v5, v31

; __device__ __forceinline__ void fft_mid(float2* X, const float2* Hb, const int N, const float invN, const int tid) {
;     ...
;     for (int m = 0; m < 8; ++m) { const float2 h = Hb[p0 + m]; const float2 v = x[m]; x[m] = make_float2((v.x * h.x - v.y * h.y) * invN, (v.x * h.y + v.y * h.x) * invN); }
	v_mul_f32_e32 v4, v10, v7
	v_mul_f32_e32 v5, v10, v6
	v_fma_f32 v10, v6, v12, -v4
	v_fma_f32 v11, v7, v12, v5

; __device__ __forceinline__ void fft_mid(float2* X, const float2* Hb, const int N, const float invN, const int tid) {
;     ...
;     for (int m = 0; m < 8; ++m) { const float2 h = Hb[p0 + m]; const float2 v = x[m]; x[m] = make_float2((v.x * h.x - v.y * h.y) * invN, (v.x * h.y + v.y * h.x) * invN); }
	ds_read2_b64 v[4:7], v17 offset0:4 offset1:5
	v_mul_f32_e32 v12, v0, v10
	v_mul_f32_e32 v13, v1, v11
	s_waitcnt lgkmcnt(0)
	v_mul_f32_e32 v24, v8, v5
	v_mul_f32_e32 v25, v8, v4
	v_fma_f32 v30, v9, v4, -v24
	v_fma_f32 v31, v9, v5, -v25
	v_fma_f32 v9, v9, v5, v25
	v_mul_f32_e32 v4, v14, v7
	v_mul_f32_e32 v5, v14, v6
	v_fma_f32 v14, v20, v6, -v4
	v_fma_f32 v15, v20, v7, v5

; __device__ __forceinline__ void fft_mid(float2* X, const float2* Hb, const int N, const float invN, const int tid) {
;     ...
;     for (int m = 0; m < 8; ++m) { const float2 h = Hb[p0 + m]; const float2 v = x[m]; x[m] = make_float2((v.x * h.x - v.y * h.y) * invN, (v.x * h.y + v.y * h.x) * invN); }
	ds_read2_b64 v[4:7], v17 offset0:6 offset1:7
	v_mov_b32_e32 v8, v30
	v_mul_f32_e32 v24, v0, v30
	v_mul_f32_e32 v20, v0, v14
	v_mul_f32_e32 v21, v1, v15
	v_mul_f32_e32 v12, 0, v12
	v_mul_f32_e32 v13, 0, v13
	s_waitcnt lgkmcnt(0)
	v_mul_f32_e32 v30, v26, v5
	v_mul_f32_e32 v31, v26, v4
	v_fma_f32 v36, v27, v4, -v30
	v_fma_f32 v37, v27, v5, v31

; __device__ __forceinline__ void fft_mid(float2* X, const float2* Hb, const int N, const float invN, const int tid) {
;     ...
;     for (int m = 0; m < 8; ++m) { const float2 h = Hb[p0 + m]; const float2 v = x[m]; x[m] = make_float2((v.x * h.x - v.y * h.y) * invN, (v.x * h.y + v.y * h.x) * invN); }
	v_mul_f32_e32 v4, v16, v7
	v_mul_f32_e32 v5, v16, v6
	v_fma_f32 v16, v28, v6, -v4
	v_fma_f32 v17, v28, v7, v5
	v_mul_f32_e32 v6, 0, v22
	v_mul_f32_e32 v7, 0, v23

; __device__ __forceinline__ float2 cmul(float2 a, float2 b) { return make_float2(a.x * b.x - a.y * b.y, a.x * b.y + a.y * b.x); }
; template <int LR, bool INV>
; __device__ __forceinline__ void fft_stages(float2 (&x)[1 << LR], const int r, const int s) {
;   constexpr int R = 1 << LR;
; #pragma unroll
;   for (int st = 0; st < LR; ++st) {
;     const int hl = INV ? (1 << st) : (R >> (st + 1));
;     const float fb = (float)r * (0.5f / (float)(hl * s));
;     const float2 wb = make_float2(__builtin_amdgcn_cosf(fb), INV ? __builtin_amdgcn_sinf(fb) : -__builtin_amdgcn_sinf(fb));
; #pragma unroll
;     for (int m = 0; m < R; ++m) {
;       if (m & hl) continue;
;       const int k = m & (hl - 1); const int j = k * (8 / hl);
;       const float2 wc = make_float2(c16(j), INV ? s16(j) : -s16(j));
;       const float2 tw = cmul(wb, wc);
;       if (!INV) { const float2 p = x[m], q = x[m + hl]; x[m] = make_float2(p.x + q.x, p.y + q.y); x[m + hl] = cmul(make_float2(p.x - q.x, p.y - q.y), tw); }
;       else { const float2 p = x[m], q = cmul(x[m + hl], tw); x[m] = make_float2(p.x + q.x, p.y + q.y); x[m + hl] = make_float2(p.x - q.x, p.y - q.y); }
;     }
; __device__ __forceinline__ void fft_mid(float2* X, const float2* Hb, const int N, const float invN, const int tid) {
;     ...
;     fft_stages<3, true>(x, 0, 1);
	v_fma_f32 v22, v0, v18, -v7
	v_fma_f32 v7, v1, v19, v6
	v_fma_f32 v18, v0, v10, -v13
	v_fma_f32 v11, v1, v11, v12
	v_mul_f32_e32 v12, 0, v20
	v_mul_f32_e32 v13, 0, v21
	v_mul_f32_e32 v4, v0, v16
	v_mul_f32_e32 v5, v1, v17
	v_fma_f32 v20, v0, v14, -v13
	v_pk_fma_f32 v[12:13], v[0:1], v[14:15], v[12:13] op_sel:[0,0,1] op_sel_hi:[1,1,0]
	v_mul_f32_e32 v4, 0, v4
	v_mul_f32_e32 v5, 0, v5
	v_mov_b32_e32 v21, v13
	v_mov_b32_e32 v19, v11
	v_fma_f32 v14, v0, v8, v20
	v_fma_f32 v15, v1, v9, v21
	v_fma_f32 v9, v1, v9, -v13
	v_fma_f32 v12, v0, v16, -v5
	v_fma_f32 v13, v1, v17, v4
	v_fma_f32 v10, v0, v34, v18
	v_fma_f32 v11, v1, v35, v19

; __device__ __forceinline__ float2 cmul(float2 a, float2 b) { return make_float2(a.x * b.x - a.y * b.y, a.x * b.y + a.y * b.x); }
; template <int LR, bool INV>
; __device__ __forceinline__ void fft_stages(float2 (&x)[1 << LR], const int r, const int s) {
;   constexpr int R = 1 << LR;
; #pragma unroll
;   for (int st = 0; st < LR; ++st) {
;     const int hl = INV ? (1 << st) : (R >> (st + 1));
;     const float fb = (float)r * (0.5f / (float)(hl * s));
;     const float2 wb = make_float2(__builtin_amdgcn_cosf(fb), INV ? __builtin_amdgcn_sinf(fb) : -__builtin_amdgcn_sinf(fb));
; #pragma unroll
;     for (int m = 0; m < R; ++m) {
;       if (m & hl) continue;
;       const int k = m & (hl - 1); const int j = k * (8 / hl);
;       const float2 wc = make_float2(c16(j), INV ? s16(j) : -s16(j));
;       const float2 tw = cmul(wb, wc);
;       if (!INV) { const float2 p = x[m], q = x[m + hl]; x[m] = make_float2(p.x + q.x, p.y + q.y); x[m + hl] = cmul(make_float2(p.x - q.x, p.y - q.y), tw); }
;       else { const float2 p = x[m], q = cmul(x[m + hl], tw); x[m] = make_float2(p.x + q.x, p.y + q.y); x[m + hl] = make_float2(p.x - q.x, p.y - q.y); }
;     }
; __device__ __forceinline__ void fft_mid(float2* X, const float2* Hb, const int N, const float invN, const int tid) {
;     ...
;     fft_stages<3, true>(x, 0, 1);
	v_fma_f32 v4, v0, v36, v12
	v_fma_f32 v5, v1, v37, v13
	v_mul_f32_e32 v16, 0, v10
	v_mul_f32_e32 v17, 0, v11
	v_fma_f32 v12, v0, v36, -v12
	v_fma_f32 v13, v1, v37, -v13
	v_sub_f32_e32 v26, v10, v17
	v_add_f32_e32 v11, v11, v16
	v_mul_f32_e32 v16, 0, v4
	v_mul_f32_e32 v17, 0, v5
	v_mul_f32_e32 v25, 0, v12
	v_sub_f32_e32 v28, v4, v17
	v_add_f32_e32 v29, v5, v16
	v_mov_b32_e32 v21, v13

; __device__ __forceinline__ float2 cmul(float2 a, float2 b) { return make_float2(a.x * b.x - a.y * b.y, a.x * b.y + a.y * b.x); }
; template <int LR, bool INV>
; __device__ __forceinline__ void fft_stages(float2 (&x)[1 << LR], const int r, const int s) {
;   constexpr int R = 1 << LR;
; #pragma unroll
;   for (int st = 0; st < LR; ++st) {
;     const int hl = INV ? (1 << st) : (R >> (st + 1));
;     const float fb = (float)r * (0.5f / (float)(hl * s));
;     const float2 wb = make_float2(__builtin_amdgcn_cosf(fb), INV ? __builtin_amdgcn_sinf(fb) : -__builtin_amdgcn_sinf(fb));
; #pragma unroll
;     for (int m = 0; m < R; ++m) {
;       if (m & hl) continue;
;       const int k = m & (hl - 1); const int j = k * (8 / hl);
;       const float2 wc = make_float2(c16(j), INV ? s16(j) : -s16(j));
;       const float2 tw = cmul(wb, wc);
;       if (!INV) { const float2 p = x[m], q = x[m + hl]; x[m] = make_float2(p.x + q.x, p.y + q.y); x[m + hl] = cmul(make_float2(p.x - q.x, p.y - q.y), tw); }
;       else { const float2 p = x[m], q = cmul(x[m + hl], tw); x[m] = make_float2(p.x + q.x, p.y + q.y); x[m + hl] = make_float2(p.x - q.x, p.y - q.y); }
;     }
; __device__ __forceinline__ void fft_mid(float2* X, const float2* Hb, const int N, const float invN, const int tid) {
;     ...
;     fft_stages<3, true>(x, 0, 1);
	v_add_f32_e32 v4, v14, v28
	v_add_f32_e32 v5, v15, v29
	v_fmac_f32_e32 v12, 0, v13
	v_sub_f32_e32 v16, v24, v20
	v_sub_f32_e32 v17, v25, v21
	v_add_f32_e32 v20, v9, v12
	v_sub_f32_e32 v24, v9, v12
	v_mul_f32_e32 v8, 0, v4
	v_mul_f32_e32 v9, 0, v5
	v_fma_f32 v18, v0, v34, -v18
	v_fma_f32 v19, v1, v35, -v19
	v_mov_b32_e32 v23, v7
	v_add_f32_e32 v21, v16, v17
	v_sub_f32_e32 v12, v4, v9
	v_add_f32_e32 v5, v5, v8
	v_mul_f32_e32 v9, 0x3f3504f3, v20
	v_mul_f32_e32 v20, 0x3f3504f3, v24
	v_fma_f32 v24, v18, 0, -v19
	v_fma_f32 v25, v19, 0, v18
	v_fma_f32 v6, v0, v32, v22
	v_fma_f32 v7, v1, v33, v23
	v_mov_b32_e32 v27, v11
	v_mul_f32_e32 v8, 0x3f3504f3, v21
	v_fma_f32 v22, v0, v32, -v22
	v_fma_f32 v23, v1, v33, -v23

; __device__ __forceinline__ void fft_mid(float2* X, const float2* Hb, const int N, const float invN, const int tid) {
;     ...
;     fft_stages<3, true>(x, 0, 1);
; #pragma unroll
;     for (int m = 0; m < 8; ++m) X[p0 + m] = x[m];
	v_add_f32_e32 v10, v6, v26
	v_add_f32_e32 v11, v7, v27
	v_mov_b32_e32 v13, v5
	v_add_f32_e32 v18, v22, v24
	v_add_f32_e32 v19, v23, v25
	v_sub_f32_e32 v8, v8, v9
	v_fmac_f32_e32 v9, 0x3f3504f3, v21
	v_add_f32_e32 v4, v10, v12
	v_add_f32_e32 v5, v11, v13
	v_add_f32_e32 v30, v18, v8
	v_add_f32_e32 v31, v19, v9
	ds_write2_b64 v38, v[4:5], v[30:31] offset1:1
	v_sub_f32_e32 v4, v6, v26
	v_sub_f32_e32 v5, v7, v27
	v_sub_f32_e32 v6, v14, v28
	v_sub_f32_e32 v7, v15, v29
	v_pk_add_f32 v[16:17], v[16:17], v[16:17] op_sel:[0,1] op_sel_hi:[0,1] neg_lo:[0,1] neg_hi:[0,1]
	v_fma_f32 v14, v6, 0, -v7
	v_fma_f32 v15, v7, 0, v6
	v_fma_f32 v16, v16, s70, -v20
	v_fma_f32 v17, v17, s71, -v20

; __device__ __forceinline__ void fft_mid(float2* X, const float2* Hb, const int N, const float invN, const int tid) {
;     ...
;     fft_stages<3, true>(x, 0, 1);
; #pragma unroll
;     for (int m = 0; m < 8; ++m) X[p0 + m] = x[m];
;   }
	v_sub_f32_e32 v20, v22, v24
	v_sub_f32_e32 v21, v23, v25
	v_add_f32_e32 v6, v4, v14
	v_add_f32_e32 v7, v5, v15
	v_add_f32_e32 v22, v20, v16
	v_add_f32_e32 v23, v21, v17
	ds_write2_b64 v38, v[6:7], v[22:23] offset0:2 offset1:3
	v_sub_f32_e32 v6, v10, v12
	v_sub_f32_e32 v7, v11, v13
	v_sub_f32_e32 v8, v18, v8
	v_sub_f32_e32 v9, v19, v9
	ds_write2_b64 v38, v[6:7], v[8:9] offset0:4 offset1:5
	v_sub_f32_e32 v4, v4, v14
	v_sub_f32_e32 v5, v5, v15
	v_sub_f32_e32 v6, v20, v16
	v_sub_f32_e32 v7, v21, v17
	ds_write2_b64 v38, v[4:5], v[6:7] offset0:6 offset1:7
	s_andn2_b64 exec, exec, s[14:15]
	s_cbranch_execnz .LBB0_681

;     static __device__ __forceinline__ float sl(float g, float up) { return g * __builtin_amdgcn_rcpf(1.0f + __builtin_amdgcn_exp2f(-1.4426950408889634f * g)) * up; }
; #define tid ltid()
; template <int LR, bool INV>
; __device__ __forceinline__ void fft_pass(float2* X, const int N, const int sl, const int tid) {
;     ...
;   for (int g = tid; g < (N >> LR); g += NTHR) {
;     const int r = g & (s - 1);
;     const int i0 = ((g >> sl) << (sl + LR)) + r;
;     float2 x[R];
; #pragma unroll
;     for (int m = 0; m < R; ++m) x[m] = X[PIDX(i0 + (m << sl))];
.LBB0_684:
	v_and_b32_e32 v33, 0xffffffc0, v32
	v_or_b32_e32 v34, v33, v31
	v_ashrrev_i32_e32 v35, 1, v33
	v_or_b32_e32 v36, 16, v33

;     static __device__ __forceinline__ float sl(float g, float up) { return g * __builtin_amdgcn_rcpf(1.0f + __builtin_amdgcn_exp2f(-1.4426950408889634f * g)) * up; }
; #define tid ltid()
; template <int LR, bool INV>
; __device__ __forceinline__ void fft_pass(float2* X, const int N, const int sl, const int tid) {
;     ...
;   for (int g = tid; g < (N >> LR); g += NTHR) {
;     const int r = g & (s - 1);
;     const int i0 = ((g >> sl) << (sl + LR)) + r;
;     float2 x[R];
; #pragma unroll
;     for (int m = 0; m < R; ++m) x[m] = X[PIDX(i0 + (m << sl))];
	v_or_b32_e32 v33, 48, v33
	v_lshl_add_u32 v34, v34, 3, 0
	v_ashrrev_i32_e32 v36, 4, v36

;     static __device__ __forceinline__ float sl(float g, float up) { return g * __builtin_amdgcn_rcpf(1.0f + __builtin_amdgcn_exp2f(-1.4426950408889634f * g)) * up; }
; #define tid ltid()
; template <int LR, bool INV>
; __device__ __forceinline__ void fft_pass(float2* X, const int N, const int sl, const int tid) {
;     ...
;   for (int g = tid; g < (N >> LR); g += NTHR) {
;     const int r = g & (s - 1);
;     const int i0 = ((g >> sl) << (sl + LR)) + r;
;     float2 x[R];
; #pragma unroll
;     for (int m = 0; m < R; ++m) x[m] = X[PIDX(i0 + (m << sl))];
	v_ashrrev_i32_e32 v33, 4, v33
	v_add_u32_e32 v60, v34, v35
	v_lshl_add_u32 v61, v36, 3, v34

;     static __device__ __forceinline__ float sl(float g, float up) { return g * __builtin_amdgcn_rcpf(1.0f + __builtin_amdgcn_exp2f(-1.4426950408889634f * g)) * up; }
; __device__ __forceinline__ float2 cmul(float2 a, float2 b) { return make_float2(a.x * b.x - a.y * b.y, a.x * b.y + a.y * b.x); }
; template <int LR, bool INV>
; __device__ __forceinline__ void fft_stages(float2 (&x)[1 << LR], const int r, const int s) {
;     ...
;   for (int st = 0; st < LR; ++st) {
;     const int hl = INV ? (1 << st) : (R >> (st + 1));
;     const float fb = (float)r * (0.5f / (float)(hl * s));
;     const float2 wb = make_float2(__builtin_amdgcn_cosf(fb), INV ? __builtin_amdgcn_sinf(fb) : -__builtin_amdgcn_sinf(fb));
; #pragma unroll
;     for (int m = 0; m < R; ++m) {
;       if (m & hl) continue;
;       const int k = m & (hl - 1); const int j = k * (8 / hl);
;       const float2 wc = make_float2(c16(j), INV ? s16(j) : -s16(j));
;       const float2 tw = cmul(wb, wc);
;       if (!INV) { const float2 p = x[m], q = x[m + hl]; x[m] = make_float2(p.x + q.x, p.y + q.y); x[m + hl] = cmul(make_float2(p.x - q.x, p.y - q.y), tw); }
;       else { const float2 p = x[m], q = cmul(x[m + hl], tw); x[m] = make_float2(p.x + q.x, p.y + q.y); x[m + hl] = make_float2(p.x - q.x, p.y - q.y); }
; template <int LR, bool INV>
; __device__ __forceinline__ void fft_pass(float2* X, const int N, const int sl, const int tid) {
;     ...
;     for (int m = 0; m < R; ++m) x[m] = X[PIDX(i0 + (m << sl))];
	v_lshl_add_u32 v33, v33, 3, v34
	ds_read2_b64 v[34:37], v60 offset1:8
	ds_read2_b64 v[38:41], v61 offset0:16 offset1:24
	ds_read2_b64 v[42:45], v61 offset0:33 offset1:41
	ds_read2_b64 v[46:49], v61 offset0:50 offset1:58
	v_add_u32_e32 v30, 0x200, v30
	s_waitcnt lgkmcnt(3)
	v_mul_f32_e32 v50, v36, v2
	v_mul_f32_e32 v51, v37, v3
	s_waitcnt lgkmcnt(2)
	v_mul_f32_e32 v52, v2, v40
	v_mul_f32_e32 v53, v3, v41
	s_waitcnt lgkmcnt(1)
	v_mul_f32_e32 v54, v2, v44
	v_mul_f32_e32 v55, v3, v45
	s_waitcnt lgkmcnt(0)
	v_mul_f32_e32 v56, v2, v48
	v_mul_f32_e32 v57, v3, v49
	v_fma_f32 v58, v36, v6, -v51
	v_fma_f32 v37, v37, v7, v50
	v_fma_f32 v50, v6, v40, -v53
	v_fma_f32 v51, v7, v41, v52
	v_fma_f32 v52, v6, v44, -v55
	v_fma_f32 v53, v7, v45, v54
	v_fma_f32 v54, v6, v48, -v57
	v_fma_f32 v55, v7, v49, v56


; __device__ __forceinline__ float2 cmul(float2 a, float2 b) { return make_float2(a.x * b.x - a.y * b.y, a.x * b.y + a.y * b.x); }
; template <int LR, bool INV>
; __device__ __forceinline__ void fft_stages(float2 (&x)[1 << LR], const int r, const int s) {
;   constexpr int R = 1 << LR;
; #pragma unroll
;   for (int st = 0; st < LR; ++st) {
;     const int hl = INV ? (1 << st) : (R >> (st + 1));
;     const float fb = (float)r * (0.5f / (float)(hl * s));
;     const float2 wb = make_float2(__builtin_amdgcn_cosf(fb), INV ? __builtin_amdgcn_sinf(fb) : -__builtin_amdgcn_sinf(fb));
; #pragma unroll
;     for (int m = 0; m < R; ++m) {
;       if (m & hl) continue;
;       const int k = m & (hl - 1); const int j = k * (8 / hl);
;       const float2 wc = make_float2(c16(j), INV ? s16(j) : -s16(j));
;       const float2 tw = cmul(wb, wc);
;       if (!INV) { const float2 p = x[m], q = x[m + hl]; x[m] = make_float2(p.x + q.x, p.y + q.y); x[m + hl] = cmul(make_float2(p.x - q.x, p.y - q.y), tw); }
;       else { const float2 p = x[m], q = cmul(x[m + hl], tw); x[m] = make_float2(p.x + q.x, p.y + q.y); x[m + hl] = make_float2(p.x - q.x, p.y - q.y); }
	v_sub_f32_e32 v40, v38, v50
	v_sub_f32_e32 v41, v39, v51
	v_add_f32_e32 v48, v46, v54
	v_add_f32_e32 v49, v47, v55
	v_add_f32_e32 v38, v38, v50
	v_add_f32_e32 v39, v39, v51
	v_sub_f32_e32 v46, v46, v54
	v_sub_f32_e32 v47, v47, v55
	v_mov_b32_e32 v59, v37
	v_add_f32_e32 v44, v42, v52
	v_add_f32_e32 v45, v43, v53
	v_sub_f32_e32 v42, v42, v52
	v_sub_f32_e32 v43, v43, v53
	v_mul_f32_e32 v50, v4, v40
	v_mul_f32_e32 v51, v5, v41
	v_mul_f32_e32 v52, v10, v48
	v_mul_f32_e32 v53, v11, v49
	v_mul_f32_e32 v54, v10, v38
	v_mul_f32_e32 v55, v11, v39
	v_mul_f32_e32 v56, v4, v46
	v_mul_f32_e32 v57, v5, v47
	v_sub_f32_e32 v36, v34, v58
	v_sub_f32_e32 v37, v35, v59
	v_add_f32_e32 v34, v34, v58
	v_add_f32_e32 v35, v35, v59
	v_fma_f32 v58, v12, v40, -v51
	v_fma_f32 v59, v13, v41, v50
	v_fma_f32 v50, v8, v48, -v53
	v_fma_f32 v51, v9, v49, v52
	v_fma_f32 v52, v8, v38, -v55
	v_fma_f32 v53, v9, v39, v54
	v_fma_f32 v54, v12, v46, -v57
	v_fma_f32 v55, v13, v47, v56


; __device__ __forceinline__ float2 cmul(float2 a, float2 b) { return make_float2(a.x * b.x - a.y * b.y, a.x * b.y + a.y * b.x); }
; template <int LR, bool INV>
; __device__ __forceinline__ void fft_stages(float2 (&x)[1 << LR], const int r, const int s) {
;   constexpr int R = 1 << LR;
; #pragma unroll
;   for (int st = 0; st < LR; ++st) {
;     const int hl = INV ? (1 << st) : (R >> (st + 1));
;     const float fb = (float)r * (0.5f / (float)(hl * s));
;     const float2 wb = make_float2(__builtin_amdgcn_cosf(fb), INV ? __builtin_amdgcn_sinf(fb) : -__builtin_amdgcn_sinf(fb));
; #pragma unroll
;     for (int m = 0; m < R; ++m) {
;       if (m & hl) continue;
;       const int k = m & (hl - 1); const int j = k * (8 / hl);
;       const float2 wc = make_float2(c16(j), INV ? s16(j) : -s16(j));
;       const float2 tw = cmul(wb, wc);
;       if (!INV) { const float2 p = x[m], q = x[m + hl]; x[m] = make_float2(p.x + q.x, p.y + q.y); x[m + hl] = cmul(make_float2(p.x - q.x, p.y - q.y), tw); }
;       else { const float2 p = x[m], q = cmul(x[m + hl], tw); x[m] = make_float2(p.x + q.x, p.y + q.y); x[m + hl] = make_float2(p.x - q.x, p.y - q.y); }
	v_sub_f32_e32 v40, v44, v50
	v_sub_f32_e32 v41, v45, v51
	v_add_f32_e32 v44, v44, v50
	v_add_f32_e32 v45, v45, v51
	v_add_f32_e32 v48, v42, v54
	v_add_f32_e32 v49, v43, v55
	v_sub_f32_e32 v46, v34, v52
	v_sub_f32_e32 v47, v35, v53
	v_add_f32_e32 v34, v34, v52
	v_add_f32_e32 v35, v35, v53
	v_sub_f32_e32 v42, v42, v54
	v_sub_f32_e32 v43, v43, v55
	v_mul_f32_e32 v50, v20, v41
	v_mul_f32_e32 v51, v21, v40
	v_mul_f32_e32 v52, v16, v45
	v_mul_f32_e32 v53, v17, v44
	v_mul_f32_e32 v54, v22, v49
	v_mul_f32_e32 v55, v23, v48
	v_sub_f32_e32 v38, v36, v58
	v_sub_f32_e32 v39, v37, v59
	v_add_f32_e32 v36, v36, v58
	v_add_f32_e32 v37, v37, v59
	v_mul_f32_e32 v56, v28, v43
	v_mul_f32_e32 v57, v29, v43
	v_fma_f32 v58, v18, v40, -v50
	v_fma_f32 v41, v19, v41, v51
	v_fma_f32 v50, v14, v44, -v52
	v_fma_f32 v51, v15, v45, v53
	v_fma_f32 v52, v26, v48, -v54
	v_fma_f32 v53, v27, v49, v55
	v_cmp_le_i32_e32 vcc, s21, v30
	v_fma_f32 v54, v24, v42, -v56
	v_fma_f32 v55, v25, v42, v57


; __device__ __forceinline__ float2 cmul(float2 a, float2 b) { return make_float2(a.x * b.x - a.y * b.y, a.x * b.y + a.y * b.x); }
; template <int LR, bool INV>
; __device__ __forceinline__ void fft_stages(float2 (&x)[1 << LR], const int r, const int s) {
;   constexpr int R = 1 << LR;
; #pragma unroll
;   for (int st = 0; st < LR; ++st) {
;     const int hl = INV ? (1 << st) : (R >> (st + 1));
;     const float fb = (float)r * (0.5f / (float)(hl * s));
;     const float2 wb = make_float2(__builtin_amdgcn_cosf(fb), INV ? __builtin_amdgcn_sinf(fb) : -__builtin_amdgcn_sinf(fb));
; #pragma unroll
;     for (int m = 0; m < R; ++m) {
;       if (m & hl) continue;
;       const int k = m & (hl - 1); const int j = k * (8 / hl);
;       const float2 wc = make_float2(c16(j), INV ? s16(j) : -s16(j));
;       const float2 tw = cmul(wb, wc);
;       if (!INV) { const float2 p = x[m], q = x[m + hl]; x[m] = make_float2(p.x + q.x, p.y + q.y); x[m + hl] = cmul(make_float2(p.x - q.x, p.y - q.y), tw); }
;       else { const float2 p = x[m], q = cmul(x[m + hl], tw); x[m] = make_float2(p.x + q.x, p.y + q.y); x[m + hl] = make_float2(p.x - q.x, p.y - q.y); }
	v_add_u32_e32 v32, 0x1000, v32
	s_or_b64 s[14:15], vcc, s[14:15]
	v_mov_b32_e32 v59, v41

;     static __device__ __forceinline__ float sl(float g, float up) { return g * __builtin_amdgcn_rcpf(1.0f + __builtin_amdgcn_exp2f(-1.4426950408889634f * g)) * up; }
; __device__ __forceinline__ float2 cmul(float2 a, float2 b) { return make_float2(a.x * b.x - a.y * b.y, a.x * b.y + a.y * b.x); }
; template <int LR, bool INV>
; __device__ __forceinline__ void fft_stages(float2 (&x)[1 << LR], const int r, const int s) {
;     ...
;       else { const float2 p = x[m], q = cmul(x[m + hl], tw); x[m] = make_float2(p.x + q.x, p.y + q.y); x[m + hl] = make_float2(p.x - q.x, p.y - q.y); }
; template <int LR, bool INV>
; __device__ __forceinline__ void fft_pass(float2* X, const int N, const int sl, const int tid) {
;     ...
; #pragma unroll
;     for (int m = 0; m < R; ++m) X[PIDX(i0 + (m << sl))] = x[m];
	v_add_f32_e32 v42, v34, v50
	v_add_f32_e32 v43, v35, v51
	v_add_f32_e32 v44, v36, v52
	v_add_f32_e32 v45, v37, v53
	v_add_f32_e32 v40, v46, v58
	v_add_f32_e32 v41, v47, v59
	v_add_f32_e32 v48, v38, v54
	v_add_f32_e32 v49, v39, v55
	v_sub_f32_e32 v34, v34, v50
	v_sub_f32_e32 v35, v35, v51
	v_sub_f32_e32 v36, v36, v52
	v_sub_f32_e32 v37, v37, v53
	v_sub_f32_e32 v46, v46, v58
	v_sub_f32_e32 v47, v47, v59
	v_sub_f32_e32 v38, v38, v54
	v_sub_f32_e32 v39, v39, v55
	ds_write2_b64 v60, v[42:43], v[44:45] offset1:8
	ds_write2_b64 v61, v[40:41], v[48:49] offset0:16 offset1:24
	ds_write2_b64 v61, v[34:35], v[36:37] offset0:33 offset1:41
	ds_write2_b64 v61, v[46:47], v[38:39] offset0:50 offset1:58
	s_andn2_b64 exec, exec, s[14:15]
	s_cbranch_execnz .LBB0_684

;     static __device__ __forceinline__ float sl(float g, float up) { return g * __builtin_amdgcn_rcpf(1.0f + __builtin_amdgcn_exp2f(-1.4426950408889634f * g)) * up; }
; #define tid ltid()
; template <int LR, bool INV>
; __device__ __forceinline__ void fft_pass(float2* X, const int N, const int sl, const int tid) {
;     ...
;   for (int g = tid; g < (N >> LR); g += NTHR) {
;     const int r = g & (s - 1);
;     const int i0 = ((g >> sl) << (sl + LR)) + r;
;     float2 x[R];
; #pragma unroll
;     for (int m = 0; m < R; ++m) x[m] = X[PIDX(i0 + (m << sl))];
.LBB0_687:
	v_and_or_b32 v33, v32, s53, v31
	v_ashrrev_i32_e32 v34, 4, v33
	v_lshl_add_u32 v35, v33, 3, 0
	v_or_b32_e32 v36, 64, v33


;     static __device__ __forceinline__ float sl(float g, float up) { return g * __builtin_amdgcn_rcpf(1.0f + __builtin_amdgcn_exp2f(-1.4426950408889634f * g)) * up; }
; #define tid ltid()
; template <int LR, bool INV>
; __device__ __forceinline__ void fft_pass(float2* X, const int N, const int sl, const int tid) {
;     ...
;   for (int g = tid; g < (N >> LR); g += NTHR) {
;     const int r = g & (s - 1);
;     const int i0 = ((g >> sl) << (sl + LR)) + r;
;     float2 x[R];
; #pragma unroll
;     for (int m = 0; m < R; ++m) x[m] = X[PIDX(i0 + (m << sl))];
	v_or_b32_e32 v33, 0x1c0, v33
	v_lshl_add_u32 v60, v34, 3, v35
	v_ashrrev_i32_e32 v34, 4, v36


;     static __device__ __forceinline__ float sl(float g, float up) { return g * __builtin_amdgcn_rcpf(1.0f + __builtin_amdgcn_exp2f(-1.4426950408889634f * g)) * up; }
; #define tid ltid()
; template <int LR, bool INV>
; __device__ __forceinline__ void fft_pass(float2* X, const int N, const int sl, const int tid) {
;     ...
;   for (int g = tid; g < (N >> LR); g += NTHR) {
;     const int r = g & (s - 1);
;     const int i0 = ((g >> sl) << (sl + LR)) + r;
;     float2 x[R];
; #pragma unroll
;     for (int m = 0; m < R; ++m) x[m] = X[PIDX(i0 + (m << sl))];
	v_ashrrev_i32_e32 v33, 4, v33
	v_lshl_add_u32 v61, v34, 3, v35


;     static __device__ __forceinline__ float sl(float g, float up) { return g * __builtin_amdgcn_rcpf(1.0f + __builtin_amdgcn_exp2f(-1.4426950408889634f * g)) * up; }
; __device__ __forceinline__ float2 cmul(float2 a, float2 b) { return make_float2(a.x * b.x - a.y * b.y, a.x * b.y + a.y * b.x); }
; template <int LR, bool INV>
; __device__ __forceinline__ void fft_stages(float2 (&x)[1 << LR], const int r, const int s) {
;     ...
;   for (int st = 0; st < LR; ++st) {
;     const int hl = INV ? (1 << st) : (R >> (st + 1));
;     const float fb = (float)r * (0.5f / (float)(hl * s));
;     const float2 wb = make_float2(__builtin_amdgcn_cosf(fb), INV ? __builtin_amdgcn_sinf(fb) : -__builtin_amdgcn_sinf(fb));
; #pragma unroll
;     for (int m = 0; m < R; ++m) {
;       if (m & hl) continue;
;       const int k = m & (hl - 1); const int j = k * (8 / hl);
;       const float2 wc = make_float2(c16(j), INV ? s16(j) : -s16(j));
;       const float2 tw = cmul(wb, wc);
;       if (!INV) { const float2 p = x[m], q = x[m + hl]; x[m] = make_float2(p.x + q.x, p.y + q.y); x[m + hl] = cmul(make_float2(p.x - q.x, p.y - q.y), tw); }
;       else { const float2 p = x[m], q = cmul(x[m + hl], tw); x[m] = make_float2(p.x + q.x, p.y + q.y); x[m + hl] = make_float2(p.x - q.x, p.y - q.y); }
; template <int LR, bool INV>
; __device__ __forceinline__ void fft_pass(float2* X, const int N, const int sl, const int tid) {
;     ...
;     for (int m = 0; m < R; ++m) x[m] = X[PIDX(i0 + (m << sl))];
	v_lshl_add_u32 v33, v33, 3, v35
	ds_read_b64 v[34:35], v60
	ds_read_b64 v[36:37], v60 offset:544
	ds_read_b64 v[38:39], v60 offset:1088
	ds_read_b64 v[40:41], v60 offset:1632
	ds_read_b64 v[42:43], v60 offset:2176
	ds_read_b64 v[44:45], v60 offset:2720
	ds_read_b64 v[46:47], v60 offset:3808
	ds_read_b64 v[48:49], v60 offset:3264
	s_waitcnt lgkmcnt(6)
	v_mul_f32_e32 v50, v36, v2
	v_mul_f32_e32 v51, v37, v3
	s_waitcnt lgkmcnt(4)
	v_mul_f32_e32 v52, v2, v40
	v_mul_f32_e32 v53, v3, v41
	s_waitcnt lgkmcnt(2)
	v_mul_f32_e32 v54, v2, v44
	v_mul_f32_e32 v55, v3, v45
	s_waitcnt lgkmcnt(1)
	v_mul_f32_e32 v56, v2, v46
	v_mul_f32_e32 v57, v3, v47
	v_fma_f32 v58, v36, v6, -v51
	v_fma_f32 v37, v37, v7, v50
	v_fma_f32 v50, v6, v40, -v53
	v_fma_f32 v51, v7, v41, v52
	v_fma_f32 v52, v6, v44, -v55
	v_fma_f32 v53, v7, v45, v54
	v_fma_f32 v54, v6, v46, -v57
	v_fma_f32 v55, v7, v47, v56


; __device__ __forceinline__ float2 cmul(float2 a, float2 b) { return make_float2(a.x * b.x - a.y * b.y, a.x * b.y + a.y * b.x); }
; template <int LR, bool INV>
; __device__ __forceinline__ void fft_stages(float2 (&x)[1 << LR], const int r, const int s) {
;   constexpr int R = 1 << LR;
; #pragma unroll
;   for (int st = 0; st < LR; ++st) {
;     const int hl = INV ? (1 << st) : (R >> (st + 1));
;     const float fb = (float)r * (0.5f / (float)(hl * s));
;     const float2 wb = make_float2(__builtin_amdgcn_cosf(fb), INV ? __builtin_amdgcn_sinf(fb) : -__builtin_amdgcn_sinf(fb));
; #pragma unroll
;     for (int m = 0; m < R; ++m) {
;       if (m & hl) continue;
;       const int k = m & (hl - 1); const int j = k * (8 / hl);
;       const float2 wc = make_float2(c16(j), INV ? s16(j) : -s16(j));
;       const float2 tw = cmul(wb, wc);
;       if (!INV) { const float2 p = x[m], q = x[m + hl]; x[m] = make_float2(p.x + q.x, p.y + q.y); x[m + hl] = cmul(make_float2(p.x - q.x, p.y - q.y), tw); }
;       else { const float2 p = x[m], q = cmul(x[m + hl], tw); x[m] = make_float2(p.x + q.x, p.y + q.y); x[m + hl] = make_float2(p.x - q.x, p.y - q.y); }
	v_sub_f32_e32 v40, v38, v50
	v_sub_f32_e32 v41, v39, v51
	s_waitcnt lgkmcnt(0)
	v_add_f32_e32 v46, v48, v54
	v_add_f32_e32 v47, v49, v55
	v_mov_b32_e32 v59, v37
	v_add_f32_e32 v44, v42, v52
	v_add_f32_e32 v45, v43, v53
	v_add_f32_e32 v38, v38, v50
	v_add_f32_e32 v39, v39, v51
	v_sub_f32_e32 v42, v42, v52
	v_sub_f32_e32 v43, v43, v53
	v_sub_f32_e32 v48, v48, v54
	v_sub_f32_e32 v49, v49, v55
	v_mul_f32_e32 v50, v4, v40
	v_mul_f32_e32 v51, v5, v41
	v_mul_f32_e32 v52, v10, v46
	v_mul_f32_e32 v53, v11, v47
	v_sub_f32_e32 v36, v34, v58
	v_sub_f32_e32 v37, v35, v59
	v_add_f32_e32 v34, v34, v58
	v_add_f32_e32 v35, v35, v59
	v_mul_f32_e32 v54, v10, v38
	v_mul_f32_e32 v55, v11, v39
	v_mul_f32_e32 v56, v4, v48
	v_mul_f32_e32 v57, v5, v49
	v_fma_f32 v58, v12, v40, -v51
	v_fma_f32 v59, v13, v41, v50
	v_fma_f32 v50, v8, v46, -v53
	v_fma_f32 v51, v9, v47, v52
	v_fma_f32 v52, v8, v38, -v55
	v_fma_f32 v53, v9, v39, v54
	v_fma_f32 v54, v12, v48, -v57
	v_fma_f32 v55, v13, v49, v56


; __device__ __forceinline__ float2 cmul(float2 a, float2 b) { return make_float2(a.x * b.x - a.y * b.y, a.x * b.y + a.y * b.x); }
; template <int LR, bool INV>
; __device__ __forceinline__ void fft_stages(float2 (&x)[1 << LR], const int r, const int s) {
;   constexpr int R = 1 << LR;
; #pragma unroll
;   for (int st = 0; st < LR; ++st) {
;     const int hl = INV ? (1 << st) : (R >> (st + 1));
;     const float fb = (float)r * (0.5f / (float)(hl * s));
;     const float2 wb = make_float2(__builtin_amdgcn_cosf(fb), INV ? __builtin_amdgcn_sinf(fb) : -__builtin_amdgcn_sinf(fb));
; #pragma unroll
;     for (int m = 0; m < R; ++m) {
;       if (m & hl) continue;
;       const int k = m & (hl - 1); const int j = k * (8 / hl);
;       const float2 wc = make_float2(c16(j), INV ? s16(j) : -s16(j));
;       const float2 tw = cmul(wb, wc);
;       if (!INV) { const float2 p = x[m], q = x[m + hl]; x[m] = make_float2(p.x + q.x, p.y + q.y); x[m + hl] = cmul(make_float2(p.x - q.x, p.y - q.y), tw); }
;       else { const float2 p = x[m], q = cmul(x[m + hl], tw); x[m] = make_float2(p.x + q.x, p.y + q.y); x[m + hl] = make_float2(p.x - q.x, p.y - q.y); }
	v_sub_f32_e32 v40, v44, v50
	v_sub_f32_e32 v41, v45, v51
	v_add_f32_e32 v44, v44, v50
	v_add_f32_e32 v45, v45, v51
	v_sub_f32_e32 v46, v34, v52
	v_sub_f32_e32 v47, v35, v53
	v_add_f32_e32 v34, v34, v52
	v_add_f32_e32 v35, v35, v53
	v_add_f32_e32 v48, v42, v54
	v_add_f32_e32 v49, v43, v55
	v_sub_f32_e32 v42, v42, v54
	v_sub_f32_e32 v43, v43, v55
	v_mul_f32_e32 v50, v20, v41
	v_mul_f32_e32 v51, v21, v40
	v_mul_f32_e32 v52, v16, v45
	v_mul_f32_e32 v53, v17, v44
	v_add_u32_e32 v30, 0x200, v30
	v_sub_f32_e32 v38, v36, v58
	v_sub_f32_e32 v39, v37, v59
	v_add_f32_e32 v36, v36, v58
	v_add_f32_e32 v37, v37, v59
	v_mul_f32_e32 v54, v22, v49
	v_mul_f32_e32 v55, v23, v48
	v_mul_f32_e32 v56, v28, v43
	v_mul_f32_e32 v57, v29, v43
	v_fma_f32 v58, v18, v40, -v50
	v_fma_f32 v41, v19, v41, v51
	v_fma_f32 v50, v14, v44, -v52
	v_fma_f32 v51, v15, v45, v53
	v_cmp_le_i32_e32 vcc, s21, v30
	v_fma_f32 v52, v26, v48, -v54
	v_fma_f32 v53, v27, v49, v55
	v_fma_f32 v54, v24, v42, -v56
	v_fma_f32 v55, v25, v42, v57

; __device__ __forceinline__ float2 cmul(float2 a, float2 b) { return make_float2(a.x * b.x - a.y * b.y, a.x * b.y + a.y * b.x); }
; template <int LR, bool INV>
; __device__ __forceinline__ void fft_stages(float2 (&x)[1 << LR], const int r, const int s) {
;   constexpr int R = 1 << LR;
; #pragma unroll
;   for (int st = 0; st < LR; ++st) {
;     const int hl = INV ? (1 << st) : (R >> (st + 1));
;     const float fb = (float)r * (0.5f / (float)(hl * s));
;     const float2 wb = make_float2(__builtin_amdgcn_cosf(fb), INV ? __builtin_amdgcn_sinf(fb) : -__builtin_amdgcn_sinf(fb));
; #pragma unroll
;     for (int m = 0; m < R; ++m) {
;       if (m & hl) continue;
;       const int k = m & (hl - 1); const int j = k * (8 / hl);
;       const float2 wc = make_float2(c16(j), INV ? s16(j) : -s16(j));
;       const float2 tw = cmul(wb, wc);
;       if (!INV) { const float2 p = x[m], q = x[m + hl]; x[m] = make_float2(p.x + q.x, p.y + q.y); x[m + hl] = cmul(make_float2(p.x - q.x, p.y - q.y), tw); }
;       else { const float2 p = x[m], q = cmul(x[m + hl], tw); x[m] = make_float2(p.x + q.x, p.y + q.y); x[m + hl] = make_float2(p.x - q.x, p.y - q.y); }
	v_add_u32_e32 v32, 0x1000, v32
	s_or_b64 s[14:15], vcc, s[14:15]
	v_mov_b32_e32 v59, v41


;     static __device__ __forceinline__ float sl(float g, float up) { return g * __builtin_amdgcn_rcpf(1.0f + __builtin_amdgcn_exp2f(-1.4426950408889634f * g)) * up; }
; __device__ __forceinline__ float2 cmul(float2 a, float2 b) { return make_float2(a.x * b.x - a.y * b.y, a.x * b.y + a.y * b.x); }
; template <int LR, bool INV>
; __device__ __forceinline__ void fft_stages(float2 (&x)[1 << LR], const int r, const int s) {
;     ...
;       else { const float2 p = x[m], q = cmul(x[m + hl], tw); x[m] = make_float2(p.x + q.x, p.y + q.y); x[m + hl] = make_float2(p.x - q.x, p.y - q.y); }
; template <int LR, bool INV>
; __device__ __forceinline__ void fft_pass(float2* X, const int N, const int sl, const int tid) {
;     ...
; #pragma unroll
;     for (int m = 0; m < R; ++m) X[PIDX(i0 + (m << sl))] = x[m];
	v_add_f32_e32 v42, v34, v50
	v_add_f32_e32 v43, v35, v51
	v_add_f32_e32 v40, v46, v58
	v_add_f32_e32 v41, v47, v59
	v_add_f32_e32 v44, v36, v52
	v_add_f32_e32 v45, v37, v53
	v_add_f32_e32 v48, v38, v54
	v_add_f32_e32 v49, v39, v55
	v_sub_f32_e32 v34, v34, v50
	v_sub_f32_e32 v35, v35, v51
	v_sub_f32_e32 v36, v36, v52
	v_sub_f32_e32 v37, v37, v53
	v_sub_f32_e32 v46, v46, v58
	v_sub_f32_e32 v47, v47, v59
	v_sub_f32_e32 v38, v38, v54
	v_sub_f32_e32 v39, v39, v55
	ds_write_b64 v60, v[42:43]
	ds_write_b64 v60, v[44:45] offset:544
	ds_write_b64 v60, v[40:41] offset:1088
	ds_write_b64 v60, v[48:49] offset:1632
	ds_write_b64 v60, v[34:35] offset:2176
	ds_write_b64 v60, v[36:37] offset:2720
	ds_write_b64 v60, v[46:47] offset:3264
	ds_write_b64 v60, v[38:39] offset:3808
	s_andn2_b64 exec, exec, s[14:15]
	s_cbranch_execnz .LBB0_687
